# baseline (speedup 1.0000x reference)
; #define G_STA(bufoff, gbase, ld) G_STAGE(bufoff, gbase, RA0, RA1, ld)
; #define G_STB(bufoff, gbase, ld) G_STAGE(bufoff, gbase, RB0, RB1, ld)
; #define G_LDA(dst, b, h) do { _Pragma("unroll") for (int m = 0; m < 4; ++m) _Pragma("unroll") for (int k = 0; k < 2; ++k) dst[m][k] = *(const LAS bf16x8*)(lds + G_SA(b, h) + aoff + m * 2048 + k * 1024); } while (0)
; #define G_LDB(dst, b, h) do { _Pragma("unroll") for (int n = 0; n < 2; ++n) _Pragma("unroll") for (int k = 0; k < 2; ++k) dst[n][k] = *(const LAS bf16x8*)(lds + G_SB(b, h) + boff + n * 2048 + k * 1024); } while (0)
; #define G_WAIT_V(n) asm volatile("s_waitcnt vmcnt(" #n ")" ::: "memory")
; #define G_BAR __builtin_amdgcn_s_barrier()
; template <bool PERM, class SchedT, class Epi>
; __device__ __forceinline__ void gemm_phase(LAS unsigned char* lds, const SchedT& S, const Epi& E) {
;     ...
;         for (int t = 0; t < nt; t += 2) {
;             const bool last = (t == nt - 2);
;             const char* a1 = cA + (size_t)(t + 1) * kstep;
;             const char* a2 = last ? nA : cA + (size_t)(t + 2) * kstep; const char* b2 = last ? nB : cB + (size_t)(t + 2) * kstep;
;             const char* a3 = a2 + kstep; const char* b3 = b2 + kstep;
;             const int wlda = last ? nlda : lda, wK = last ? nK : K;
;             G_LDB(B0, 0, 0); G_SCHED; G_LDA(At, 0, 0); G_STA(G_SA(1, 1), a1 + HSTEP(lda), lda);
;             G_WAIT_L(8); G_BAR; G_WAIT_L(0); G_MMA(0, 0, At, B0); G_BAR; G_SCHED;
;             G_LDB(B1, 0, 1); G_STB(G_SB(0, 0), b2, wK);
;             G_BAR; G_WAIT_L(0); G_MMA(0, 1, At, B1); G_BAR;
;             G_LDA(At, 0, 1); G_STA(G_SA(0, 0), a2, wlda);
;             G_BAR; G_WAIT_L(0); G_MMA(1, 0, At, B0); G_BAR; G_SCHED;
;             G_STB(G_SB(0, 1), b2 + HSTEP(wK), wK);
;             G_WAIT_V(6); G_BAR; G_MMA(1, 1, At, B1); G_BAR;
;             G_LDB(B0, 1, 0); G_SCHED; G_LDA(At, 1, 0); G_STA(G_SA(0, 1), a2 + HSTEP(wlda), wlda);
;             G_WAIT_L(8); G_BAR; G_WAIT_L(0); G_MMA(0, 0, At, B0); G_BAR; G_SCHED;
;             G_LDB(B1, 1, 1); G_STB(G_SB(1, 0), b3, wK);
;             G_BAR; G_WAIT_L(0); G_MMA(0, 1, At, B1); G_BAR;
;             G_LDA(At, 1, 1); G_STA(G_SA(1, 0), a3, wlda);
;             G_BAR; G_WAIT_L(0); G_MMA(1, 0, At, B0); G_BAR; G_SCHED;
;             G_STB(G_SB(1, 1), b3 + HSTEP(wK), wK);
;             G_WAIT_V(6); G_BAR; G_MMA(1, 1, At, B1); G_BAR;
.LBB0_44:
	s_cmp_eq_u32 s45, s47
	s_cselect_b64 s[28:29], -1, 0
	s_add_i32 s47, s47, 2
	s_add_u32 s26, s22, 0x80
	s_addc_u32 s27, s23, 0
	s_and_b64 s[24:25], s[28:29], exec
	s_cselect_b32 s25, s13, s27
	s_cselect_b32 s24, s12, s26
	s_cselect_b32 s26, s40, s20
	s_add_i32 s27, 0, 0x10000
	v_add_u32_e32 v152, s27, v194
	ds_read_b128 v[134:137], v152
	ds_read_b128 v[144:147], v152 offset:1024
	ds_read_b128 v[148:151], v152 offset:2048
	ds_read_b128 v[152:155], v152 offset:3072
	s_and_b64 s[28:29], s[28:29], exec
	s_cselect_b32 s29, s19, s46
	s_cselect_b32 s28, s18, s21
	s_cselect_b32 s72, s11, s44
	v_lshl_add_u64 v[156:157], s[22:23], 0, v[130:131]
	s_add_i32 m0, s30, 0xc000
	ds_read_b128 v[160:163], v196
	ds_read_b128 v[164:167], v196 offset:1024
	ds_read_b128 v[168:171], v196 offset:2048
	ds_read_b128 v[172:175], v196 offset:3072
	ds_read_b128 v[176:179], v196 offset:4096
	ds_read_b128 v[198:201], v196 offset:5120
	ds_read_b128 v[202:205], v196 offset:6144
	ds_read_b128 v[206:209], v196 offset:7168
	global_load_lds_dwordx4 v[156:157], off
	v_lshl_add_u64 v[156:157], s[22:23], 0, v[132:133]
	s_add_i32 m0, s30, 0xe000
	s_nop 0
	global_load_lds_dwordx4 v[156:157], off
	s_waitcnt lgkmcnt(8)
	s_barrier
	s_waitcnt lgkmcnt(0)
	s_setprio 1
	s_waitcnt lgkmcnt(0)
	v_mfma_f32_16x16x32_bf16 v[126:129], v[134:137], v[160:163], v[126:129]
	v_mfma_f32_16x16x32_bf16 v[122:125], v[148:151], v[160:163], v[122:125]
	v_mfma_f32_16x16x32_bf16 v[118:121], v[134:137], v[168:171], v[118:121]
	v_mfma_f32_16x16x32_bf16 v[114:117], v[148:151], v[168:171], v[114:117]
	v_mfma_f32_16x16x32_bf16 v[102:105], v[134:137], v[176:179], v[102:105]
	v_mfma_f32_16x16x32_bf16 v[98:101], v[148:151], v[176:179], v[98:101]
	v_mfma_f32_16x16x32_bf16 v[86:89], v[134:137], v[202:205], v[86:89]
	v_mfma_f32_16x16x32_bf16 v[82:85], v[148:151], v[202:205], v[82:85]
	v_mfma_f32_16x16x32_bf16 v[126:129], v[144:147], v[164:167], v[126:129]
	v_mfma_f32_16x16x32_bf16 v[122:125], v[152:155], v[164:167], v[122:125]
	v_mfma_f32_16x16x32_bf16 v[118:121], v[144:147], v[172:175], v[118:121]
	v_mfma_f32_16x16x32_bf16 v[114:117], v[152:155], v[172:175], v[114:117]
	v_mfma_f32_16x16x32_bf16 v[102:105], v[144:147], v[198:201], v[102:105]
	v_mfma_f32_16x16x32_bf16 v[98:101], v[152:155], v[198:201], v[98:101]
	v_mfma_f32_16x16x32_bf16 v[86:89], v[144:147], v[206:209], v[86:89]
	v_mfma_f32_16x16x32_bf16 v[82:85], v[152:155], v[206:209], v[82:85]
	s_setprio 0
	s_barrier
	s_add_i32 s50, 0, 0x14000
	v_add_u32_e32 v156, s50, v194
	s_add_i32 s27, s27, s5
	ds_read_b128 v[210:213], v156
	ds_read_b128 v[214:217], v156 offset:1024
	ds_read_b128 v[218:221], v156 offset:2048
	ds_read_b128 v[222:225], v156 offset:3072
	v_mad_u64_u32 v[156:157], s[48:49], v143, s72, v[138:139]
	s_mov_b32 m0, s27
	v_mad_u64_u32 v[230:231], s[48:49], v192, s72, v[140:141]
	global_load_lds_dwordx4 v156, s[28:29]
	s_add_i32 m0, s27, 0x2000
	v_mov_b32_e32 v157, v1
	global_load_lds_dwordx4 v230, s[28:29]
	s_barrier
	s_waitcnt lgkmcnt(0)
	v_mov_b32_e32 v231, v1
	v_lshl_add_u64 v[232:233], s[28:29], 0, v[156:157]
	v_lshl_add_u64 v[234:235], s[28:29], 0, v[230:231]
	s_setprio 1
	s_waitcnt lgkmcnt(0)
	v_mfma_f32_16x16x32_bf16 v[110:113], v[210:213], v[160:163], v[110:113]
	v_mfma_f32_16x16x32_bf16 v[106:109], v[218:221], v[160:163], v[106:109]
	v_mfma_f32_16x16x32_bf16 v[94:97], v[210:213], v[168:171], v[94:97]
	v_mfma_f32_16x16x32_bf16 v[90:93], v[218:221], v[168:171], v[90:93]
	v_mfma_f32_16x16x32_bf16 v[78:81], v[210:213], v[176:179], v[78:81]
	v_mfma_f32_16x16x32_bf16 v[74:77], v[218:221], v[176:179], v[74:77]
	v_mfma_f32_16x16x32_bf16 v[70:73], v[210:213], v[202:205], v[70:73]
	v_mfma_f32_16x16x32_bf16 v[66:69], v[218:221], v[202:205], v[66:69]
	v_mfma_f32_16x16x32_bf16 v[110:113], v[214:217], v[164:167], v[110:113]
	v_mfma_f32_16x16x32_bf16 v[106:109], v[222:225], v[164:167], v[106:109]
	v_mfma_f32_16x16x32_bf16 v[94:97], v[214:217], v[172:175], v[94:97]
	v_mfma_f32_16x16x32_bf16 v[90:93], v[222:225], v[172:175], v[90:93]
	v_mfma_f32_16x16x32_bf16 v[78:81], v[214:217], v[198:201], v[78:81]
	v_mfma_f32_16x16x32_bf16 v[74:77], v[222:225], v[198:201], v[74:77]
	v_mfma_f32_16x16x32_bf16 v[70:73], v[214:217], v[206:209], v[70:73]
	v_mfma_f32_16x16x32_bf16 v[66:69], v[222:225], v[206:209], v[66:69]
	s_setprio 0
	s_mov_b32 m0, s30
	v_mad_u64_u32 v[236:237], s[48:49], s26, v139, v[138:139]
	s_barrier
	ds_read_b128 v[160:163], v196 offset:16384
	ds_read_b128 v[164:167], v196 offset:17408
	ds_read_b128 v[168:171], v196 offset:18432
	ds_read_b128 v[172:175], v196 offset:19456
	ds_read_b128 v[176:179], v196 offset:20480
	ds_read_b128 v[198:201], v196 offset:21504
	ds_read_b128 v[202:205], v196 offset:22528
	ds_read_b128 v[206:209], v196 offset:23552
	global_load_lds_dwordx4 v236, s[24:25]
	v_mad_u64_u32 v[238:239], s[48:49], s26, v141, v[140:141]
	s_mov_b32 m0, s31
	v_mov_b32_e32 v237, v1
	global_load_lds_dwordx4 v238, s[24:25]
	s_barrier
	s_waitcnt lgkmcnt(0)
	v_mov_b32_e32 v239, v1
	v_lshl_add_u64 v[240:241], s[24:25], 0, v[236:237]
	v_lshl_add_u64 v[242:243], s[24:25], 0, v[238:239]
	s_setprio 1
	s_waitcnt lgkmcnt(0)
	v_mfma_f32_16x16x32_bf16 v[62:65], v[134:137], v[160:163], v[62:65]
	v_mfma_f32_16x16x32_bf16 v[58:61], v[148:151], v[160:163], v[58:61]
	v_mfma_f32_16x16x32_bf16 v[54:57], v[134:137], v[168:171], v[54:57]
	v_mfma_f32_16x16x32_bf16 v[50:53], v[148:151], v[168:171], v[50:53]
	v_mfma_f32_16x16x32_bf16 v[38:41], v[134:137], v[176:179], v[38:41]
	v_mfma_f32_16x16x32_bf16 v[34:37], v[148:151], v[176:179], v[34:37]
	v_mfma_f32_16x16x32_bf16 v[22:25], v[134:137], v[202:205], v[22:25]
	v_mfma_f32_16x16x32_bf16 v[18:21], v[148:151], v[202:205], v[18:21]
	v_mfma_f32_16x16x32_bf16 v[62:65], v[144:147], v[164:167], v[62:65]
	v_mfma_f32_16x16x32_bf16 v[58:61], v[152:155], v[164:167], v[58:61]
	v_mfma_f32_16x16x32_bf16 v[54:57], v[144:147], v[172:175], v[54:57]
	v_mfma_f32_16x16x32_bf16 v[50:53], v[152:155], v[172:175], v[50:53]
	v_mfma_f32_16x16x32_bf16 v[38:41], v[144:147], v[198:201], v[38:41]
	v_mfma_f32_16x16x32_bf16 v[34:37], v[152:155], v[198:201], v[34:37]
	v_mfma_f32_16x16x32_bf16 v[22:25], v[144:147], v[206:209], v[22:25]
	v_mfma_f32_16x16x32_bf16 v[18:21], v[152:155], v[206:209], v[18:21]
	s_setprio 0
	s_barrier
; #define G_STA(bufoff, gbase, ld) G_STAGE(bufoff, gbase, RA0, RA1, ld)
; #define G_STB(bufoff, gbase, ld) G_STAGE(bufoff, gbase, RB0, RB1, ld)
; #define G_LDA(dst, b, h) do { _Pragma("unroll") for (int m = 0; m < 4; ++m) _Pragma("unroll") for (int k = 0; k < 2; ++k) dst[m][k] = *(const LAS bf16x8*)(lds + G_SA(b, h) + aoff + m * 2048 + k * 1024); } while (0)
; #define G_LDB(dst, b, h) do { _Pragma("unroll") for (int n = 0; n < 2; ++n) _Pragma("unroll") for (int k = 0; k < 2; ++k) dst[n][k] = *(const LAS bf16x8*)(lds + G_SB(b, h) + boff + n * 2048 + k * 1024); } while (0)
; #define G_WAIT_V(n) asm volatile("s_waitcnt vmcnt(" #n ")" ::: "memory")
; #define G_BAR __builtin_amdgcn_s_barrier()
; template <bool PERM, class SchedT, class Epi>
; __device__ __forceinline__ void gemm_phase(LAS unsigned char* lds, const SchedT& S, const Epi& E) {
;     ...
;         for (int t = 0; t < nt; t += 2) {
;             const bool last = (t == nt - 2);
;             const char* a1 = cA + (size_t)(t + 1) * kstep;
;             const char* a2 = last ? nA : cA + (size_t)(t + 2) * kstep; const char* b2 = last ? nB : cB + (size_t)(t + 2) * kstep;
;             const char* a3 = a2 + kstep; const char* b3 = b2 + kstep;
;             const int wlda = last ? nlda : lda, wK = last ? nK : K;
;             G_LDB(B0, 0, 0); G_SCHED; G_LDA(At, 0, 0); G_STA(G_SA(1, 1), a1 + HSTEP(lda), lda);
;             G_WAIT_L(8); G_BAR; G_WAIT_L(0); G_MMA(0, 0, At, B0); G_BAR; G_SCHED;
;             G_LDB(B1, 0, 1); G_STB(G_SB(0, 0), b2, wK);
;             G_BAR; G_WAIT_L(0); G_MMA(0, 1, At, B1); G_BAR;
;             G_LDA(At, 0, 1); G_STA(G_SA(0, 0), a2, wlda);
;             G_BAR; G_WAIT_L(0); G_MMA(1, 0, At, B0); G_BAR; G_SCHED;
;             G_STB(G_SB(0, 1), b2 + HSTEP(wK), wK);
;             G_WAIT_V(6); G_BAR; G_MMA(1, 1, At, B1); G_BAR;
;             G_LDB(B0, 1, 0); G_SCHED; G_LDA(At, 1, 0); G_STA(G_SA(0, 1), a2 + HSTEP(wlda), wlda);
;             G_WAIT_L(8); G_BAR; G_WAIT_L(0); G_MMA(0, 0, At, B0); G_BAR; G_SCHED;
;             G_LDB(B1, 1, 1); G_STB(G_SB(1, 0), b3, wK);
;             G_BAR; G_WAIT_L(0); G_MMA(0, 1, At, B1); G_BAR;
;             G_LDA(At, 1, 1); G_STA(G_SA(1, 0), a3, wlda);
;             G_BAR; G_WAIT_L(0); G_MMA(1, 0, At, B0); G_BAR; G_SCHED;
;             G_STB(G_SB(1, 1), b3 + HSTEP(wK), wK);
;             G_WAIT_V(6); G_BAR; G_MMA(1, 1, At, B1); G_BAR;
	s_lshl_b64 s[48:49], s[72:73], 8
	s_add_u32 s28, s28, s48
	s_addc_u32 s29, s29, s49
	s_add_i32 s27, s50, s5
	s_mov_b32 m0, s27
	s_nop 0
	global_load_lds_dwordx4 v156, s[28:29]
	s_add_i32 m0, s27, 0x2000
	v_lshl_add_u64 v[156:157], s[28:29], 0, v[156:157]
	global_load_lds_dwordx4 v230, s[28:29]
	s_waitcnt vmcnt(6)
	v_lshl_add_u64 v[230:231], s[28:29], 0, v[230:231]
	s_barrier
	s_setprio 1
	v_mfma_f32_16x16x32_bf16 v[46:49], v[210:213], v[160:163], v[46:49]
	v_mfma_f32_16x16x32_bf16 v[42:45], v[218:221], v[160:163], v[42:45]
	v_mfma_f32_16x16x32_bf16 v[30:33], v[210:213], v[168:171], v[30:33]
	v_mfma_f32_16x16x32_bf16 v[26:29], v[218:221], v[168:171], v[26:29]
	v_mfma_f32_16x16x32_bf16 v[14:17], v[210:213], v[176:179], v[14:17]
	v_mfma_f32_16x16x32_bf16 v[10:13], v[218:221], v[176:179], v[10:13]
	v_mfma_f32_16x16x32_bf16 v[6:9], v[210:213], v[202:205], v[6:9]
	v_mfma_f32_16x16x32_bf16 v[2:5], v[218:221], v[202:205], v[2:5]
	v_mfma_f32_16x16x32_bf16 v[46:49], v[214:217], v[164:167], v[46:49]
	v_mfma_f32_16x16x32_bf16 v[42:45], v[222:225], v[164:167], v[42:45]
	v_mfma_f32_16x16x32_bf16 v[30:33], v[214:217], v[172:175], v[30:33]
	v_mfma_f32_16x16x32_bf16 v[26:29], v[222:225], v[172:175], v[26:29]
	v_mfma_f32_16x16x32_bf16 v[14:17], v[214:217], v[198:201], v[14:17]
	v_mfma_f32_16x16x32_bf16 v[10:13], v[222:225], v[198:201], v[10:13]
	v_mfma_f32_16x16x32_bf16 v[6:9], v[214:217], v[206:209], v[6:9]
	v_mfma_f32_16x16x32_bf16 v[2:5], v[222:225], v[206:209], v[2:5]
	s_setprio 0
	s_add_i32 s28, 0, 0x18000
	v_add_u32_e32 v152, s28, v194
	s_barrier
	ds_read_b128 v[134:137], v152
	ds_read_b128 v[144:147], v152 offset:1024
	ds_read_b128 v[148:151], v152 offset:2048
	ds_read_b128 v[152:155], v152 offset:3072
	s_mov_b32 s27, s73
	s_lshl_b64 s[26:27], s[26:27], 8
	s_add_u32 s24, s24, s26
	s_addc_u32 s25, s25, s27
	s_mov_b32 m0, s34
	ds_read_b128 v[160:163], v196 offset:32768
	ds_read_b128 v[164:167], v196 offset:33792
	ds_read_b128 v[168:171], v196 offset:34816
	ds_read_b128 v[172:175], v196 offset:35840
	ds_read_b128 v[176:179], v196 offset:36864
	ds_read_b128 v[198:201], v196 offset:37888
	ds_read_b128 v[202:205], v196 offset:38912
	ds_read_b128 v[206:209], v196 offset:39936
	global_load_lds_dwordx4 v236, s[24:25]
	s_mov_b32 m0, s35
	s_nop 0
	global_load_lds_dwordx4 v238, s[24:25]
	s_waitcnt lgkmcnt(8)
	s_barrier
	s_waitcnt lgkmcnt(0)
	s_setprio 1
	s_waitcnt lgkmcnt(0)
	v_mfma_f32_16x16x32_bf16 v[126:129], v[134:137], v[160:163], v[126:129]
	v_mfma_f32_16x16x32_bf16 v[122:125], v[148:151], v[160:163], v[122:125]
	v_mfma_f32_16x16x32_bf16 v[118:121], v[134:137], v[168:171], v[118:121]
	v_mfma_f32_16x16x32_bf16 v[114:117], v[148:151], v[168:171], v[114:117]
	v_mfma_f32_16x16x32_bf16 v[102:105], v[134:137], v[176:179], v[102:105]
	v_mfma_f32_16x16x32_bf16 v[98:101], v[148:151], v[176:179], v[98:101]
	v_mfma_f32_16x16x32_bf16 v[86:89], v[134:137], v[202:205], v[86:89]
	v_mfma_f32_16x16x32_bf16 v[82:85], v[148:151], v[202:205], v[82:85]
	v_mfma_f32_16x16x32_bf16 v[126:129], v[144:147], v[164:167], v[126:129]
	v_mfma_f32_16x16x32_bf16 v[122:125], v[152:155], v[164:167], v[122:125]
	v_mfma_f32_16x16x32_bf16 v[118:121], v[144:147], v[172:175], v[118:121]
	v_mfma_f32_16x16x32_bf16 v[114:117], v[152:155], v[172:175], v[114:117]
	v_mfma_f32_16x16x32_bf16 v[102:105], v[144:147], v[198:201], v[102:105]
	v_mfma_f32_16x16x32_bf16 v[98:101], v[152:155], v[198:201], v[98:101]
	v_mfma_f32_16x16x32_bf16 v[86:89], v[144:147], v[206:209], v[86:89]
	v_mfma_f32_16x16x32_bf16 v[82:85], v[152:155], v[206:209], v[82:85]
	s_setprio 0
	s_barrier
	s_add_i32 s24, 0, 0x1c000
	s_add_i32 s25, s28, s5
	v_add_u32_e32 v197, s24, v194
	v_lshl_add_u64 v[232:233], v[232:233], 0, s[78:79]
	s_mov_b32 m0, s25
	ds_read_b128 v[210:213], v197
	ds_read_b128 v[214:217], v197 offset:1024
	ds_read_b128 v[218:221], v197 offset:2048
	ds_read_b128 v[222:225], v197 offset:3072
	global_load_lds_dwordx4 v[232:233], off
	v_lshl_add_u64 v[232:233], v[234:235], 0, s[78:79]
	s_add_i32 m0, s25, 0x2000
	s_nop 0
	global_load_lds_dwordx4 v[232:233], off
	s_barrier
	s_waitcnt lgkmcnt(0)
	s_setprio 1
	s_waitcnt lgkmcnt(0)
	v_mfma_f32_16x16x32_bf16 v[110:113], v[210:213], v[160:163], v[110:113]
	v_mfma_f32_16x16x32_bf16 v[106:109], v[218:221], v[160:163], v[106:109]
	v_mfma_f32_16x16x32_bf16 v[94:97], v[210:213], v[168:171], v[94:97]
	v_mfma_f32_16x16x32_bf16 v[90:93], v[218:221], v[168:171], v[90:93]
	v_mfma_f32_16x16x32_bf16 v[78:81], v[210:213], v[176:179], v[78:81]
	v_mfma_f32_16x16x32_bf16 v[74:77], v[218:221], v[176:179], v[74:77]
	v_mfma_f32_16x16x32_bf16 v[70:73], v[210:213], v[202:205], v[70:73]
	v_mfma_f32_16x16x32_bf16 v[66:69], v[218:221], v[202:205], v[66:69]
	v_mfma_f32_16x16x32_bf16 v[110:113], v[214:217], v[164:167], v[110:113]
	v_mfma_f32_16x16x32_bf16 v[106:109], v[222:225], v[164:167], v[106:109]
	v_mfma_f32_16x16x32_bf16 v[94:97], v[214:217], v[172:175], v[94:97]
	v_mfma_f32_16x16x32_bf16 v[90:93], v[222:225], v[172:175], v[90:93]
	v_mfma_f32_16x16x32_bf16 v[78:81], v[214:217], v[198:201], v[78:81]
	v_mfma_f32_16x16x32_bf16 v[74:77], v[222:225], v[198:201], v[74:77]
	v_mfma_f32_16x16x32_bf16 v[70:73], v[214:217], v[206:209], v[70:73]
	v_mfma_f32_16x16x32_bf16 v[66:69], v[222:225], v[206:209], v[66:69]
	s_setprio 0
	s_mov_b32 m0, s36
	v_lshl_add_u64 v[232:233], v[240:241], 0, s[78:79]
	s_barrier
	ds_read_b128 v[160:163], v196 offset:49152
	ds_read_b128 v[164:167], v196 offset:50176
	ds_read_b128 v[168:171], v196 offset:51200
	ds_read_b128 v[172:175], v196 offset:52224
	ds_read_b128 v[176:179], v196 offset:53248
	ds_read_b128 v[198:201], v196 offset:54272
	ds_read_b128 v[202:205], v196 offset:55296
	ds_read_b128 v[206:209], v196 offset:56320
	global_load_lds_dwordx4 v[232:233], off
	v_lshl_add_u64 v[232:233], v[242:243], 0, s[78:79]
	s_mov_b32 m0, s37
	s_nop 0
	global_load_lds_dwordx4 v[232:233], off
	s_barrier
; #define G_STB(bufoff, gbase, ld) G_STAGE(bufoff, gbase, RB0, RB1, ld)
; #define G_MMA(ai, bj, At, Bt) do { __builtin_amdgcn_s_setprio(1); _Pragma("unroll") for (int m = 0; m < 4; ++m) _Pragma("unroll") for (int n = 0; n < 2; ++n) _Pragma("unroll") for (int k = 0; k < 2; ++k) \
;         acc[ai][bj][m][n] = __builtin_amdgcn_mfma_f32_16x16x32_bf16(Bt[n][k], At[m][k], acc[ai][bj][m][n], 0, 0, 0); __builtin_amdgcn_s_setprio(0); } while (0)
; #define G_WAIT_V(n) asm volatile("s_waitcnt vmcnt(" #n ")" ::: "memory")
; #define G_WAIT_L(n) asm volatile("s_waitcnt lgkmcnt(" #n ")" ::: "memory")
; #define G_BAR __builtin_amdgcn_s_barrier()
; #define G_SCHED __builtin_amdgcn_sched_barrier(0)
; template <bool PERM, class SchedT, class Epi>
; __device__ __forceinline__ void gemm_phase(LAS unsigned char* lds, const SchedT& S, const Epi& E) {
;     ...
;             G_BAR; G_WAIT_L(0); G_MMA(1, 0, At, B0); G_BAR; G_SCHED;
;             G_STB(G_SB(1, 1), b3 + HSTEP(wK), wK);
;             G_WAIT_V(6); G_BAR; G_MMA(1, 1, At, B1); G_BAR;
;         }
;         E(acc, cur, wr, wc, fr, fq);
;     __device__ __forceinline__ void operator()(const f32x4 (&acc)[2][2][4][2], const UnitD& u, int wr, int wc, int fr, int fq) const {
;     ...
;             for (int ai = 0; ai < 2; ++ai)
; #pragma unroll
;                 for (int m = 0; m < 4; ++m) { const int row = row0 + ai * HALF + m * 16;
;                     const unsigned char* gp = (const unsigned char*)(proj + (size_t)row * NP + C_G) + col0; const size_t po = (size_t)row * 2048 + col0;
;                     u32x2 g0[2], g1[2], g2[2]; u32x4 a[2], b[2];
; #pragma unroll
;                     for (int bj = 0; bj < 2; ++bj) { g0[bj] = *(const u32x2*)(gp + bj * HALF); g1[bj] = *(const u32x2*)(gp + 2048 + bj * HALF); g2[bj] = *(const u32x2*)(gp + 4096 + bj * HALF);
;                         a[bj] = *(const u32x4*)(PA + po + bj * HALF); b[bj] = *(const u32x4*)(PB + po + bj * HALF); }
	s_waitcnt lgkmcnt(0)
	s_setprio 1
	s_waitcnt lgkmcnt(0)
	v_mfma_f32_16x16x32_bf16 v[62:65], v[134:137], v[160:163], v[62:65]
	v_mfma_f32_16x16x32_bf16 v[58:61], v[148:151], v[160:163], v[58:61]
	v_mfma_f32_16x16x32_bf16 v[54:57], v[134:137], v[168:171], v[54:57]
	v_mfma_f32_16x16x32_bf16 v[50:53], v[148:151], v[168:171], v[50:53]
	v_mfma_f32_16x16x32_bf16 v[38:41], v[134:137], v[176:179], v[38:41]
	v_mfma_f32_16x16x32_bf16 v[34:37], v[148:151], v[176:179], v[34:37]
	v_mfma_f32_16x16x32_bf16 v[22:25], v[134:137], v[202:205], v[22:25]
	v_mfma_f32_16x16x32_bf16 v[18:21], v[148:151], v[202:205], v[18:21]
	v_mfma_f32_16x16x32_bf16 v[62:65], v[144:147], v[164:167], v[62:65]
	v_mfma_f32_16x16x32_bf16 v[58:61], v[152:155], v[164:167], v[58:61]
	v_mfma_f32_16x16x32_bf16 v[54:57], v[144:147], v[172:175], v[54:57]
	v_mfma_f32_16x16x32_bf16 v[50:53], v[152:155], v[172:175], v[50:53]
	v_mfma_f32_16x16x32_bf16 v[38:41], v[144:147], v[198:201], v[38:41]
	v_mfma_f32_16x16x32_bf16 v[34:37], v[152:155], v[198:201], v[34:37]
	v_mfma_f32_16x16x32_bf16 v[22:25], v[144:147], v[206:209], v[22:25]
	v_mfma_f32_16x16x32_bf16 v[18:21], v[152:155], v[206:209], v[18:21]
	s_setprio 0
	s_barrier
	s_add_i32 s24, s24, s5
	v_lshl_add_u64 v[134:135], v[156:157], 0, s[78:79]
	s_mov_b32 m0, s24
	s_nop 0
	global_load_lds_dwordx4 v[134:135], off
	v_lshl_add_u64 v[134:135], v[230:231], 0, s[78:79]
	s_add_i32 m0, s24, 0x2000
	s_nop 0
	global_load_lds_dwordx4 v[134:135], off
	s_waitcnt vmcnt(6)
	s_barrier
	s_setprio 1
	v_mfma_f32_16x16x32_bf16 v[46:49], v[210:213], v[160:163], v[46:49]
	v_mfma_f32_16x16x32_bf16 v[42:45], v[218:221], v[160:163], v[42:45]
	v_mfma_f32_16x16x32_bf16 v[30:33], v[210:213], v[168:171], v[30:33]
	v_mfma_f32_16x16x32_bf16 v[26:29], v[218:221], v[168:171], v[26:29]
	v_mfma_f32_16x16x32_bf16 v[14:17], v[210:213], v[176:179], v[14:17]
	v_mfma_f32_16x16x32_bf16 v[10:13], v[218:221], v[176:179], v[10:13]
	v_mfma_f32_16x16x32_bf16 v[6:9], v[210:213], v[202:205], v[6:9]
	v_mfma_f32_16x16x32_bf16 v[2:5], v[218:221], v[202:205], v[2:5]
	v_mfma_f32_16x16x32_bf16 v[46:49], v[214:217], v[164:167], v[46:49]
	v_mfma_f32_16x16x32_bf16 v[42:45], v[222:225], v[164:167], v[42:45]
	v_mfma_f32_16x16x32_bf16 v[30:33], v[214:217], v[172:175], v[30:33]
	v_mfma_f32_16x16x32_bf16 v[26:29], v[222:225], v[172:175], v[26:29]
	v_mfma_f32_16x16x32_bf16 v[14:17], v[214:217], v[198:201], v[14:17]
	v_mfma_f32_16x16x32_bf16 v[10:13], v[222:225], v[198:201], v[10:13]
	v_mfma_f32_16x16x32_bf16 v[6:9], v[214:217], v[206:209], v[6:9]
	v_mfma_f32_16x16x32_bf16 v[2:5], v[222:225], v[206:209], v[2:5]
	s_setprio 0
	s_add_u32 s22, s22, 0x100
	s_addc_u32 s23, s23, 0
	s_add_u32 s21, s21, 0x100
	s_addc_u32 s46, s46, 0
	s_cmp_ge_u32 s47, s9
	s_barrier
	s_cbranch_scc0 .LBB0_44
	s_cmpk_gt_u32 s4, 0xff
	s_cbranch_scc1 .Lus_g3a
	s_barrier
.Lus_g3a:
	v_lshl_add_u32 v144, s43, 8, v193
	v_lshl_or_b32 v150, s42, 8, v195
	s_cmp_lt_i32 s41, 2
	s_cbranch_scc1 .Lg3_k01
	v_readlane_b32 s20, v249, 2
	v_readlane_b32 s21, v249, 3
	v_lshl_add_u32 v145, v144, 11, v150
	v_lshlrev_b32_e32 v145, 1, v145
	v_mul_lo_u32 v146, v144, s3
	v_add_u32_e32 v146, v146, v150
	v_add_u32_e32 v146, 0x5880, v146
	v_mov_b32_e32 v147, v145
	v_mov_b32_e32 v148, v146
	global_load_dwordx2 v[130:131], v148, s[20:21] offset:-2048
	global_load_dwordx2 v[132:133], v148, s[20:21]
	global_load_dwordx2 v[134:135], v148, s[20:21] offset:2048
	global_load_dwordx2 v[136:137], v148, s[20:21] offset:-1920
	global_load_dwordx2 v[160:161], v148, s[20:21] offset:128
	global_load_dwordx2 v[162:163], v148, s[20:21] offset:2176
	global_load_dwordx4 v[164:167], v147, s[58:59]
	global_load_dwordx4 v[168:171], v147, s[60:61]
	global_load_dwordx4 v[172:175], v147, s[58:59] offset:256
	global_load_dwordx4 v[176:179], v147, s[60:61] offset:256
	v_add_u32_e32 v147, 0x10000, v145
	v_add_u32_e32 v148, 0x82000, v146
	global_load_dwordx2 v[198:199], v148, s[20:21] offset:-2048
	global_load_dwordx2 v[200:201], v148, s[20:21]
	global_load_dwordx2 v[202:203], v148, s[20:21] offset:2048
	global_load_dwordx2 v[204:205], v148, s[20:21] offset:-1920
	global_load_dwordx2 v[206:207], v148, s[20:21] offset:128
	global_load_dwordx2 v[208:209], v148, s[20:21] offset:2176
	global_load_dwordx4 v[210:213], v147, s[58:59]
	global_load_dwordx4 v[214:217], v147, s[60:61]
	global_load_dwordx4 v[218:221], v147, s[58:59] offset:256
	global_load_dwordx4 v[222:225], v147, s[60:61] offset:256
	ds_write_b128 v251, v[126:129]
	ds_read_b128 v[126:129], v252
	ds_write_b128 v251, v[122:125]
	ds_read_b128 v[122:125], v252
	ds_write_b128 v251, v[110:113]
	ds_read_b128 v[110:113], v252
	ds_write_b128 v251, v[106:109]
	ds_read_b128 v[106:109], v252
	v_mov_b32_e32 v149, v145
	s_waitcnt vmcnt(10)
	s_waitcnt lgkmcnt(4)
; __device__ __forceinline__ void unpack8(const u32x4 w, float* f) { f[0] = bflo(w.x); f[1] = bfhi(w.x); f[2] = bflo(w.y); f[3] = bfhi(w.y); f[4] = bflo(w.z); f[5] = bfhi(w.z); f[6] = bflo(w.w); f[7] = bfhi(w.w); }
; __device__ __forceinline__ u32x4 pack8(const float* f) { u32x4 w; w.x = cvt_pk(f[0], f[1]); w.y = cvt_pk(f[2], f[3]); w.z = cvt_pk(f[4], f[5]); w.w = cvt_pk(f[6], f[7]); return w; }
;     __device__ __forceinline__ void operator()(const f32x4 (&acc)[2][2][4][2], const UnitD& u, int wr, int wc, int fr, int fq) const {
;     ...
;             for (int ai = 0; ai < 2; ++ai)
; #pragma unroll
;                 for (int m = 0; m < 4; ++m) { const int row = row0 + ai * HALF + m * 16;
;                     const unsigned char* gp = (const unsigned char*)(proj + (size_t)row * NP + C_G) + col0; const size_t po = (size_t)row * 2048 + col0;
;                     u32x2 g0[2], g1[2], g2[2]; u32x4 a[2], b[2];
; #pragma unroll
;                     for (int bj = 0; bj < 2; ++bj) { g0[bj] = *(const u32x2*)(gp + bj * HALF); g1[bj] = *(const u32x2*)(gp + 2048 + bj * HALF); g2[bj] = *(const u32x2*)(gp + 4096 + bj * HALF);
;                         a[bj] = *(const u32x4*)(PA + po + bj * HALF); b[bj] = *(const u32x4*)(PB + po + bj * HALF); }
; #pragma unroll
;                     for (int bj = 0; bj < 2; ++bj) { float f0[8], f1[8], f2[8], fa[8], fb[8], o[8];
;                         unpack_u8(g0[bj], f0); unpack_u8(g1[bj], f1); unpack_u8(g2[bj], f2); unpack8(a[bj], fa); unpack8(b[bj], fb);
;                         const f32x4 v0 = acc[ai][bj][m][0], v1 = acc[ai][bj][m][1];
; #pragma unroll
;                         for (int j = 0; j < 4; ++j) { o[j] = f0[j] * fa[j] + f1[j] * fb[j] + f2[j] * v0[j]; o[4 + j] = f0[4 + j] * fa[4 + j] + f1[4 + j] * fb[4 + j] + f2[4 + j] * v1[j]; }
;                         *(u32x4*)(H + po + bj * HALF) = pack8(o); } }
	v_cvt_f32_ubyte0_e32 v152, v130
	v_cvt_f32_ubyte0_e32 v153, v132
	v_cvt_f32_ubyte0_e32 v154, v134
	v_lshlrev_b32_e32 v155, 16, v164
	v_lshlrev_b32_e32 v156, 16, v168
	v_mul_f32_e32 v152, 0x3b808081, v152
	v_mul_f32_e32 v153, 0x3b808081, v153
	v_mul_f32_e32 v154, 0x3b808081, v154
	v_mul_f32_e32 v157, v152, v155
	v_fmac_f32_e32 v157, v153, v156
	v_fma_f32 v126, v154, v126, v157
	v_cvt_f32_ubyte1_e32 v152, v130
	v_cvt_f32_ubyte1_e32 v153, v132
	v_cvt_f32_ubyte1_e32 v154, v134
	v_and_b32_e32 v155, 0xffff0000, v164
	v_and_b32_e32 v156, 0xffff0000, v168
	v_mul_f32_e32 v152, 0x3b808081, v152
	v_mul_f32_e32 v153, 0x3b808081, v153
	v_mul_f32_e32 v154, 0x3b808081, v154
	v_mul_f32_e32 v157, v152, v155
	v_fmac_f32_e32 v157, v153, v156
	v_fma_f32 v127, v154, v127, v157
	v_cvt_f32_ubyte2_e32 v152, v130
	v_cvt_f32_ubyte2_e32 v153, v132
	v_cvt_f32_ubyte2_e32 v154, v134
	v_lshlrev_b32_e32 v155, 16, v165
	v_lshlrev_b32_e32 v156, 16, v169
	v_mul_f32_e32 v152, 0x3b808081, v152
	v_mul_f32_e32 v153, 0x3b808081, v153
	v_mul_f32_e32 v154, 0x3b808081, v154
	v_mul_f32_e32 v157, v152, v155
	v_fmac_f32_e32 v157, v153, v156
	v_fma_f32 v128, v154, v128, v157
	v_cvt_f32_ubyte3_e32 v152, v130
	v_cvt_f32_ubyte3_e32 v153, v132
	v_cvt_f32_ubyte3_e32 v154, v134
	v_and_b32_e32 v155, 0xffff0000, v165
	v_and_b32_e32 v156, 0xffff0000, v169
	v_mul_f32_e32 v152, 0x3b808081, v152
	v_mul_f32_e32 v153, 0x3b808081, v153
	v_mul_f32_e32 v154, 0x3b808081, v154
	v_mul_f32_e32 v157, v152, v155
	v_fmac_f32_e32 v157, v153, v156
	v_fma_f32 v129, v154, v129, v157
	v_cvt_f32_ubyte0_e32 v152, v131
	v_cvt_f32_ubyte0_e32 v153, v133
	v_cvt_f32_ubyte0_e32 v154, v135
	v_lshlrev_b32_e32 v155, 16, v166
	v_lshlrev_b32_e32 v156, 16, v170
	v_mul_f32_e32 v152, 0x3b808081, v152
	v_mul_f32_e32 v153, 0x3b808081, v153
	v_mul_f32_e32 v154, 0x3b808081, v154
	v_mul_f32_e32 v157, v152, v155
	v_fmac_f32_e32 v157, v153, v156
	v_fma_f32 v122, v154, v122, v157
	v_cvt_f32_ubyte1_e32 v152, v131
	v_cvt_f32_ubyte1_e32 v153, v133
	v_cvt_f32_ubyte1_e32 v154, v135
	v_and_b32_e32 v155, 0xffff0000, v166
	v_and_b32_e32 v156, 0xffff0000, v170
	v_mul_f32_e32 v152, 0x3b808081, v152
	v_mul_f32_e32 v153, 0x3b808081, v153
	v_mul_f32_e32 v154, 0x3b808081, v154
	v_mul_f32_e32 v157, v152, v155
	v_fmac_f32_e32 v157, v153, v156
	v_fma_f32 v123, v154, v123, v157
	v_cvt_f32_ubyte2_e32 v152, v131
	v_cvt_f32_ubyte2_e32 v153, v133
	v_cvt_f32_ubyte2_e32 v154, v135
	v_lshlrev_b32_e32 v155, 16, v167
	v_lshlrev_b32_e32 v156, 16, v171
	v_mul_f32_e32 v152, 0x3b808081, v152
	v_mul_f32_e32 v153, 0x3b808081, v153
	v_mul_f32_e32 v154, 0x3b808081, v154
	v_mul_f32_e32 v157, v152, v155
	v_fmac_f32_e32 v157, v153, v156
	v_fma_f32 v124, v154, v124, v157
	v_cvt_f32_ubyte3_e32 v152, v131
	v_cvt_f32_ubyte3_e32 v153, v133
	v_cvt_f32_ubyte3_e32 v154, v135
	v_and_b32_e32 v155, 0xffff0000, v167
	v_and_b32_e32 v156, 0xffff0000, v171
	v_mul_f32_e32 v152, 0x3b808081, v152
	v_mul_f32_e32 v153, 0x3b808081, v153
	v_mul_f32_e32 v154, 0x3b808081, v154
	v_mul_f32_e32 v157, v152, v155
	v_fmac_f32_e32 v157, v153, v156
	v_fma_f32 v125, v154, v125, v157
	v_cvt_pk_bf16_f32 v126, v126, v127
	v_cvt_pk_bf16_f32 v127, v128, v129
	v_cvt_pk_bf16_f32 v128, v122, v123
	v_cvt_pk_bf16_f32 v129, v124, v125
	global_store_dwordx4 v149, v[126:129], s[62:63]
	s_waitcnt lgkmcnt(0)
	v_cvt_f32_ubyte0_e32 v152, v136
	v_cvt_f32_ubyte0_e32 v153, v160
	v_cvt_f32_ubyte0_e32 v154, v162
	v_lshlrev_b32_e32 v155, 16, v172
	v_lshlrev_b32_e32 v156, 16, v176
	v_mul_f32_e32 v152, 0x3b808081, v152
	v_mul_f32_e32 v153, 0x3b808081, v153
	v_mul_f32_e32 v154, 0x3b808081, v154
	v_mul_f32_e32 v157, v152, v155
	v_fmac_f32_e32 v157, v153, v156
	v_fma_f32 v110, v154, v110, v157
	v_cvt_f32_ubyte1_e32 v152, v136
	v_cvt_f32_ubyte1_e32 v153, v160
	v_cvt_f32_ubyte1_e32 v154, v162
	v_and_b32_e32 v155, 0xffff0000, v172
	v_and_b32_e32 v156, 0xffff0000, v176
	v_mul_f32_e32 v152, 0x3b808081, v152
	v_mul_f32_e32 v153, 0x3b808081, v153
	v_mul_f32_e32 v154, 0x3b808081, v154
	v_mul_f32_e32 v157, v152, v155
	v_fmac_f32_e32 v157, v153, v156
	v_fma_f32 v111, v154, v111, v157
	v_cvt_f32_ubyte2_e32 v152, v136
	v_cvt_f32_ubyte2_e32 v153, v160
	v_cvt_f32_ubyte2_e32 v154, v162
	v_lshlrev_b32_e32 v155, 16, v173
	v_lshlrev_b32_e32 v156, 16, v177
	v_mul_f32_e32 v152, 0x3b808081, v152
	v_mul_f32_e32 v153, 0x3b808081, v153
	v_mul_f32_e32 v154, 0x3b808081, v154
	v_mul_f32_e32 v157, v152, v155
	v_fmac_f32_e32 v157, v153, v156
	v_fma_f32 v112, v154, v112, v157
	v_cvt_f32_ubyte3_e32 v152, v136
	v_cvt_f32_ubyte3_e32 v153, v160
	v_cvt_f32_ubyte3_e32 v154, v162
	v_and_b32_e32 v155, 0xffff0000, v173
	v_and_b32_e32 v156, 0xffff0000, v177
	v_mul_f32_e32 v152, 0x3b808081, v152
	v_mul_f32_e32 v153, 0x3b808081, v153
	v_mul_f32_e32 v154, 0x3b808081, v154
	v_mul_f32_e32 v157, v152, v155
	v_fmac_f32_e32 v157, v153, v156
	v_fma_f32 v113, v154, v113, v157
	v_cvt_f32_ubyte0_e32 v152, v137
	v_cvt_f32_ubyte0_e32 v153, v161
	v_cvt_f32_ubyte0_e32 v154, v163
	v_lshlrev_b32_e32 v155, 16, v174
	v_lshlrev_b32_e32 v156, 16, v178
	v_mul_f32_e32 v152, 0x3b808081, v152
	v_mul_f32_e32 v153, 0x3b808081, v153
	v_mul_f32_e32 v154, 0x3b808081, v154
	v_mul_f32_e32 v157, v152, v155
	v_fmac_f32_e32 v157, v153, v156
	v_fma_f32 v106, v154, v106, v157
	v_cvt_f32_ubyte1_e32 v152, v137
	v_cvt_f32_ubyte1_e32 v153, v161
	v_cvt_f32_ubyte1_e32 v154, v163
	v_and_b32_e32 v155, 0xffff0000, v174
	v_and_b32_e32 v156, 0xffff0000, v178
	v_mul_f32_e32 v152, 0x3b808081, v152
	v_mul_f32_e32 v153, 0x3b808081, v153
	v_mul_f32_e32 v154, 0x3b808081, v154
	v_mul_f32_e32 v157, v152, v155
	v_fmac_f32_e32 v157, v153, v156
	v_fma_f32 v107, v154, v107, v157
	v_cvt_f32_ubyte2_e32 v152, v137
; __device__ __forceinline__ void unpack8(const u32x4 w, float* f) { f[0] = bflo(w.x); f[1] = bfhi(w.x); f[2] = bflo(w.y); f[3] = bfhi(w.y); f[4] = bflo(w.z); f[5] = bfhi(w.z); f[6] = bflo(w.w); f[7] = bfhi(w.w); }
; __device__ __forceinline__ u32x4 pack8(const float* f) { u32x4 w; w.x = cvt_pk(f[0], f[1]); w.y = cvt_pk(f[2], f[3]); w.z = cvt_pk(f[4], f[5]); w.w = cvt_pk(f[6], f[7]); return w; }
;     __device__ __forceinline__ void operator()(const f32x4 (&acc)[2][2][4][2], const UnitD& u, int wr, int wc, int fr, int fq) const {
;     ...
;             for (int ai = 0; ai < 2; ++ai)
; #pragma unroll
;                 for (int m = 0; m < 4; ++m) { const int row = row0 + ai * HALF + m * 16;
;                     const unsigned char* gp = (const unsigned char*)(proj + (size_t)row * NP + C_G) + col0; const size_t po = (size_t)row * 2048 + col0;
;                     u32x2 g0[2], g1[2], g2[2]; u32x4 a[2], b[2];
; #pragma unroll
;                     for (int bj = 0; bj < 2; ++bj) { g0[bj] = *(const u32x2*)(gp + bj * HALF); g1[bj] = *(const u32x2*)(gp + 2048 + bj * HALF); g2[bj] = *(const u32x2*)(gp + 4096 + bj * HALF);
;                         a[bj] = *(const u32x4*)(PA + po + bj * HALF); b[bj] = *(const u32x4*)(PB + po + bj * HALF); }
; #pragma unroll
;                     for (int bj = 0; bj < 2; ++bj) { float f0[8], f1[8], f2[8], fa[8], fb[8], o[8];
;                         unpack_u8(g0[bj], f0); unpack_u8(g1[bj], f1); unpack_u8(g2[bj], f2); unpack8(a[bj], fa); unpack8(b[bj], fb);
;                         const f32x4 v0 = acc[ai][bj][m][0], v1 = acc[ai][bj][m][1];
; #pragma unroll
;                         for (int j = 0; j < 4; ++j) { o[j] = f0[j] * fa[j] + f1[j] * fb[j] + f2[j] * v0[j]; o[4 + j] = f0[4 + j] * fa[4 + j] + f1[4 + j] * fb[4 + j] + f2[4 + j] * v1[j]; }
;                         *(u32x4*)(H + po + bj * HALF) = pack8(o); } }
	v_cvt_f32_ubyte2_e32 v153, v161
	v_cvt_f32_ubyte2_e32 v154, v163
	v_lshlrev_b32_e32 v155, 16, v175
	v_lshlrev_b32_e32 v156, 16, v179
	v_mul_f32_e32 v152, 0x3b808081, v152
	v_mul_f32_e32 v153, 0x3b808081, v153
	v_mul_f32_e32 v154, 0x3b808081, v154
	v_mul_f32_e32 v157, v152, v155
	v_fmac_f32_e32 v157, v153, v156
	v_fma_f32 v108, v154, v108, v157
	v_cvt_f32_ubyte3_e32 v152, v137
	v_cvt_f32_ubyte3_e32 v153, v161
	v_cvt_f32_ubyte3_e32 v154, v163
	v_and_b32_e32 v155, 0xffff0000, v175
	v_and_b32_e32 v156, 0xffff0000, v179
	v_mul_f32_e32 v152, 0x3b808081, v152
	v_mul_f32_e32 v153, 0x3b808081, v153
	v_mul_f32_e32 v154, 0x3b808081, v154
	v_mul_f32_e32 v157, v152, v155
	v_fmac_f32_e32 v157, v153, v156
	v_fma_f32 v109, v154, v109, v157
	v_cvt_pk_bf16_f32 v110, v110, v111
	v_cvt_pk_bf16_f32 v111, v112, v113
	v_cvt_pk_bf16_f32 v112, v106, v107
	v_cvt_pk_bf16_f32 v113, v108, v109
	global_store_dwordx4 v149, v[110:113], s[62:63] offset:256
	v_add_u32_e32 v147, 0x20000, v145
	v_add_u32_e32 v148, 0x104000, v146
	global_load_dwordx2 v[130:131], v148, s[20:21] offset:-2048
	global_load_dwordx2 v[132:133], v148, s[20:21]
	global_load_dwordx2 v[134:135], v148, s[20:21] offset:2048
	global_load_dwordx2 v[136:137], v148, s[20:21] offset:-1920
	global_load_dwordx2 v[160:161], v148, s[20:21] offset:128
	global_load_dwordx2 v[162:163], v148, s[20:21] offset:2176
	global_load_dwordx4 v[164:167], v147, s[58:59]
	global_load_dwordx4 v[168:171], v147, s[60:61]
	global_load_dwordx4 v[172:175], v147, s[58:59] offset:256
	global_load_dwordx4 v[176:179], v147, s[60:61] offset:256
	ds_write_b128 v251, v[118:121]
	ds_read_b128 v[118:121], v252
	ds_write_b128 v251, v[114:117]
	ds_read_b128 v[114:117], v252
	ds_write_b128 v251, v[94:97]
	ds_read_b128 v[94:97], v252
	ds_write_b128 v251, v[90:93]
	ds_read_b128 v[90:93], v252
	v_add_u32_e32 v149, 0x10000, v145
	s_waitcnt vmcnt(12)
	s_waitcnt lgkmcnt(4)
	v_cvt_f32_ubyte0_e32 v152, v198
	v_cvt_f32_ubyte0_e32 v153, v200
	v_cvt_f32_ubyte0_e32 v154, v202
	v_lshlrev_b32_e32 v155, 16, v210
	v_lshlrev_b32_e32 v156, 16, v214
	v_mul_f32_e32 v152, 0x3b808081, v152
	v_mul_f32_e32 v153, 0x3b808081, v153
	v_mul_f32_e32 v154, 0x3b808081, v154
	v_mul_f32_e32 v157, v152, v155
	v_fmac_f32_e32 v157, v153, v156
	v_fma_f32 v118, v154, v118, v157
	v_cvt_f32_ubyte1_e32 v152, v198
	v_cvt_f32_ubyte1_e32 v153, v200
	v_cvt_f32_ubyte1_e32 v154, v202
	v_and_b32_e32 v155, 0xffff0000, v210
	v_and_b32_e32 v156, 0xffff0000, v214
	v_mul_f32_e32 v152, 0x3b808081, v152
	v_mul_f32_e32 v153, 0x3b808081, v153
	v_mul_f32_e32 v154, 0x3b808081, v154
	v_mul_f32_e32 v157, v152, v155
	v_fmac_f32_e32 v157, v153, v156
	v_fma_f32 v119, v154, v119, v157
	v_cvt_f32_ubyte2_e32 v152, v198
	v_cvt_f32_ubyte2_e32 v153, v200
	v_cvt_f32_ubyte2_e32 v154, v202
	v_lshlrev_b32_e32 v155, 16, v211
	v_lshlrev_b32_e32 v156, 16, v215
	v_mul_f32_e32 v152, 0x3b808081, v152
	v_mul_f32_e32 v153, 0x3b808081, v153
	v_mul_f32_e32 v154, 0x3b808081, v154
	v_mul_f32_e32 v157, v152, v155
	v_fmac_f32_e32 v157, v153, v156
	v_fma_f32 v120, v154, v120, v157
	v_cvt_f32_ubyte3_e32 v152, v198
	v_cvt_f32_ubyte3_e32 v153, v200
	v_cvt_f32_ubyte3_e32 v154, v202
	v_and_b32_e32 v155, 0xffff0000, v211
	v_and_b32_e32 v156, 0xffff0000, v215
	v_mul_f32_e32 v152, 0x3b808081, v152
	v_mul_f32_e32 v153, 0x3b808081, v153
	v_mul_f32_e32 v154, 0x3b808081, v154
	v_mul_f32_e32 v157, v152, v155
	v_fmac_f32_e32 v157, v153, v156
	v_fma_f32 v121, v154, v121, v157
	v_cvt_f32_ubyte0_e32 v152, v199
	v_cvt_f32_ubyte0_e32 v153, v201
	v_cvt_f32_ubyte0_e32 v154, v203
	v_lshlrev_b32_e32 v155, 16, v212
	v_lshlrev_b32_e32 v156, 16, v216
	v_mul_f32_e32 v152, 0x3b808081, v152
	v_mul_f32_e32 v153, 0x3b808081, v153
	v_mul_f32_e32 v154, 0x3b808081, v154
	v_mul_f32_e32 v157, v152, v155
	v_fmac_f32_e32 v157, v153, v156
	v_fma_f32 v114, v154, v114, v157
	v_cvt_f32_ubyte1_e32 v152, v199
	v_cvt_f32_ubyte1_e32 v153, v201
	v_cvt_f32_ubyte1_e32 v154, v203
	v_and_b32_e32 v155, 0xffff0000, v212
	v_and_b32_e32 v156, 0xffff0000, v216
	v_mul_f32_e32 v152, 0x3b808081, v152
	v_mul_f32_e32 v153, 0x3b808081, v153
	v_mul_f32_e32 v154, 0x3b808081, v154
	v_mul_f32_e32 v157, v152, v155
	v_fmac_f32_e32 v157, v153, v156
	v_fma_f32 v115, v154, v115, v157
	v_cvt_f32_ubyte2_e32 v152, v199
	v_cvt_f32_ubyte2_e32 v153, v201
	v_cvt_f32_ubyte2_e32 v154, v203
	v_lshlrev_b32_e32 v155, 16, v213
	v_lshlrev_b32_e32 v156, 16, v217
	v_mul_f32_e32 v152, 0x3b808081, v152
	v_mul_f32_e32 v153, 0x3b808081, v153
	v_mul_f32_e32 v154, 0x3b808081, v154
	v_mul_f32_e32 v157, v152, v155
	v_fmac_f32_e32 v157, v153, v156
	v_fma_f32 v116, v154, v116, v157
	v_cvt_f32_ubyte3_e32 v152, v199
	v_cvt_f32_ubyte3_e32 v153, v201
	v_cvt_f32_ubyte3_e32 v154, v203
	v_and_b32_e32 v155, 0xffff0000, v213
	v_and_b32_e32 v156, 0xffff0000, v217
	v_mul_f32_e32 v152, 0x3b808081, v152
	v_mul_f32_e32 v153, 0x3b808081, v153
	v_mul_f32_e32 v154, 0x3b808081, v154
	v_mul_f32_e32 v157, v152, v155
	v_fmac_f32_e32 v157, v153, v156
	v_fma_f32 v117, v154, v117, v157
	v_cvt_pk_bf16_f32 v118, v118, v119
	v_cvt_pk_bf16_f32 v119, v120, v121
	v_cvt_pk_bf16_f32 v120, v114, v115
	v_cvt_pk_bf16_f32 v121, v116, v117
	global_store_dwordx4 v149, v[118:121], s[62:63]
	s_waitcnt lgkmcnt(0)
; __device__ __forceinline__ void unpack8(const u32x4 w, float* f) { f[0] = bflo(w.x); f[1] = bfhi(w.x); f[2] = bflo(w.y); f[3] = bfhi(w.y); f[4] = bflo(w.z); f[5] = bfhi(w.z); f[6] = bflo(w.w); f[7] = bfhi(w.w); }
; __device__ __forceinline__ u32x4 pack8(const float* f) { u32x4 w; w.x = cvt_pk(f[0], f[1]); w.y = cvt_pk(f[2], f[3]); w.z = cvt_pk(f[4], f[5]); w.w = cvt_pk(f[6], f[7]); return w; }
;     __device__ __forceinline__ void operator()(const f32x4 (&acc)[2][2][4][2], const UnitD& u, int wr, int wc, int fr, int fq) const {
;     ...
;             for (int ai = 0; ai < 2; ++ai)
; #pragma unroll
;                 for (int m = 0; m < 4; ++m) { const int row = row0 + ai * HALF + m * 16;
;                     const unsigned char* gp = (const unsigned char*)(proj + (size_t)row * NP + C_G) + col0; const size_t po = (size_t)row * 2048 + col0;
;                     u32x2 g0[2], g1[2], g2[2]; u32x4 a[2], b[2];
; #pragma unroll
;                     for (int bj = 0; bj < 2; ++bj) { g0[bj] = *(const u32x2*)(gp + bj * HALF); g1[bj] = *(const u32x2*)(gp + 2048 + bj * HALF); g2[bj] = *(const u32x2*)(gp + 4096 + bj * HALF);
;                         a[bj] = *(const u32x4*)(PA + po + bj * HALF); b[bj] = *(const u32x4*)(PB + po + bj * HALF); }
; #pragma unroll
;                     for (int bj = 0; bj < 2; ++bj) { float f0[8], f1[8], f2[8], fa[8], fb[8], o[8];
;                         unpack_u8(g0[bj], f0); unpack_u8(g1[bj], f1); unpack_u8(g2[bj], f2); unpack8(a[bj], fa); unpack8(b[bj], fb);
;                         const f32x4 v0 = acc[ai][bj][m][0], v1 = acc[ai][bj][m][1];
; #pragma unroll
;                         for (int j = 0; j < 4; ++j) { o[j] = f0[j] * fa[j] + f1[j] * fb[j] + f2[j] * v0[j]; o[4 + j] = f0[4 + j] * fa[4 + j] + f1[4 + j] * fb[4 + j] + f2[4 + j] * v1[j]; }
;                         *(u32x4*)(H + po + bj * HALF) = pack8(o); } }
	v_cvt_f32_ubyte0_e32 v152, v204
	v_cvt_f32_ubyte0_e32 v153, v206
	v_cvt_f32_ubyte0_e32 v154, v208
	v_lshlrev_b32_e32 v155, 16, v218
	v_lshlrev_b32_e32 v156, 16, v222
	v_mul_f32_e32 v152, 0x3b808081, v152
	v_mul_f32_e32 v153, 0x3b808081, v153
	v_mul_f32_e32 v154, 0x3b808081, v154
	v_mul_f32_e32 v157, v152, v155
	v_fmac_f32_e32 v157, v153, v156
	v_fma_f32 v94, v154, v94, v157
	v_cvt_f32_ubyte1_e32 v152, v204
	v_cvt_f32_ubyte1_e32 v153, v206
	v_cvt_f32_ubyte1_e32 v154, v208
	v_and_b32_e32 v155, 0xffff0000, v218
	v_and_b32_e32 v156, 0xffff0000, v222
	v_mul_f32_e32 v152, 0x3b808081, v152
	v_mul_f32_e32 v153, 0x3b808081, v153
	v_mul_f32_e32 v154, 0x3b808081, v154
	v_mul_f32_e32 v157, v152, v155
	v_fmac_f32_e32 v157, v153, v156
	v_fma_f32 v95, v154, v95, v157
	v_cvt_f32_ubyte2_e32 v152, v204
	v_cvt_f32_ubyte2_e32 v153, v206
	v_cvt_f32_ubyte2_e32 v154, v208
	v_lshlrev_b32_e32 v155, 16, v219
	v_lshlrev_b32_e32 v156, 16, v223
	v_mul_f32_e32 v152, 0x3b808081, v152
	v_mul_f32_e32 v153, 0x3b808081, v153
	v_mul_f32_e32 v154, 0x3b808081, v154
	v_mul_f32_e32 v157, v152, v155
	v_fmac_f32_e32 v157, v153, v156
	v_fma_f32 v96, v154, v96, v157
	v_cvt_f32_ubyte3_e32 v152, v204
	v_cvt_f32_ubyte3_e32 v153, v206
	v_cvt_f32_ubyte3_e32 v154, v208
	v_and_b32_e32 v155, 0xffff0000, v219
	v_and_b32_e32 v156, 0xffff0000, v223
	v_mul_f32_e32 v152, 0x3b808081, v152
	v_mul_f32_e32 v153, 0x3b808081, v153
	v_mul_f32_e32 v154, 0x3b808081, v154
	v_mul_f32_e32 v157, v152, v155
	v_fmac_f32_e32 v157, v153, v156
	v_fma_f32 v97, v154, v97, v157
	v_cvt_f32_ubyte0_e32 v152, v205
	v_cvt_f32_ubyte0_e32 v153, v207
	v_cvt_f32_ubyte0_e32 v154, v209
	v_lshlrev_b32_e32 v155, 16, v220
	v_lshlrev_b32_e32 v156, 16, v224
	v_mul_f32_e32 v152, 0x3b808081, v152
	v_mul_f32_e32 v153, 0x3b808081, v153
	v_mul_f32_e32 v154, 0x3b808081, v154
	v_mul_f32_e32 v157, v152, v155
	v_fmac_f32_e32 v157, v153, v156
	v_fma_f32 v90, v154, v90, v157
	v_cvt_f32_ubyte1_e32 v152, v205
	v_cvt_f32_ubyte1_e32 v153, v207
	v_cvt_f32_ubyte1_e32 v154, v209
	v_and_b32_e32 v155, 0xffff0000, v220
	v_and_b32_e32 v156, 0xffff0000, v224
	v_mul_f32_e32 v152, 0x3b808081, v152
	v_mul_f32_e32 v153, 0x3b808081, v153
	v_mul_f32_e32 v154, 0x3b808081, v154
	v_mul_f32_e32 v157, v152, v155
	v_fmac_f32_e32 v157, v153, v156
	v_fma_f32 v91, v154, v91, v157
	v_cvt_f32_ubyte2_e32 v152, v205
	v_cvt_f32_ubyte2_e32 v153, v207
	v_cvt_f32_ubyte2_e32 v154, v209
	v_lshlrev_b32_e32 v155, 16, v221
	v_lshlrev_b32_e32 v156, 16, v225
	v_mul_f32_e32 v152, 0x3b808081, v152
	v_mul_f32_e32 v153, 0x3b808081, v153
	v_mul_f32_e32 v154, 0x3b808081, v154
	v_mul_f32_e32 v157, v152, v155
	v_fmac_f32_e32 v157, v153, v156
	v_fma_f32 v92, v154, v92, v157
	v_cvt_f32_ubyte3_e32 v152, v205
	v_cvt_f32_ubyte3_e32 v153, v207
	v_cvt_f32_ubyte3_e32 v154, v209
	v_and_b32_e32 v155, 0xffff0000, v221
	v_and_b32_e32 v156, 0xffff0000, v225
	v_mul_f32_e32 v152, 0x3b808081, v152
	v_mul_f32_e32 v153, 0x3b808081, v153
	v_mul_f32_e32 v154, 0x3b808081, v154
	v_mul_f32_e32 v157, v152, v155
	v_fmac_f32_e32 v157, v153, v156
	v_fma_f32 v93, v154, v93, v157
	v_cvt_pk_bf16_f32 v94, v94, v95
	v_cvt_pk_bf16_f32 v95, v96, v97
	v_cvt_pk_bf16_f32 v96, v90, v91
	v_cvt_pk_bf16_f32 v97, v92, v93
	global_store_dwordx4 v149, v[94:97], s[62:63] offset:256
	v_add_u32_e32 v147, 0x30000, v145
	v_add_u32_e32 v148, 0x186000, v146
	global_load_dwordx2 v[198:199], v148, s[20:21] offset:-2048
	global_load_dwordx2 v[200:201], v148, s[20:21]
	global_load_dwordx2 v[202:203], v148, s[20:21] offset:2048
	global_load_dwordx2 v[204:205], v148, s[20:21] offset:-1920
	global_load_dwordx2 v[206:207], v148, s[20:21] offset:128
	global_load_dwordx2 v[208:209], v148, s[20:21] offset:2176
	global_load_dwordx4 v[210:213], v147, s[58:59]
	global_load_dwordx4 v[214:217], v147, s[60:61]
	global_load_dwordx4 v[218:221], v147, s[58:59] offset:256
	global_load_dwordx4 v[222:225], v147, s[60:61] offset:256
	ds_write_b128 v251, v[102:105]
	ds_read_b128 v[102:105], v252
	ds_write_b128 v251, v[98:101]
	ds_read_b128 v[98:101], v252
	ds_write_b128 v251, v[78:81]
	ds_read_b128 v[78:81], v252
	ds_write_b128 v251, v[74:77]
	ds_read_b128 v[74:77], v252
	v_add_u32_e32 v149, 0x20000, v145
	s_waitcnt vmcnt(12)
	s_waitcnt lgkmcnt(4)
	v_cvt_f32_ubyte0_e32 v152, v130
	v_cvt_f32_ubyte0_e32 v153, v132
	v_cvt_f32_ubyte0_e32 v154, v134
	v_lshlrev_b32_e32 v155, 16, v164
	v_lshlrev_b32_e32 v156, 16, v168
	v_mul_f32_e32 v152, 0x3b808081, v152
	v_mul_f32_e32 v153, 0x3b808081, v153
	v_mul_f32_e32 v154, 0x3b808081, v154
	v_mul_f32_e32 v157, v152, v155
	v_fmac_f32_e32 v157, v153, v156
	v_fma_f32 v102, v154, v102, v157
	v_cvt_f32_ubyte1_e32 v152, v130
	v_cvt_f32_ubyte1_e32 v153, v132
	v_cvt_f32_ubyte1_e32 v154, v134
	v_and_b32_e32 v155, 0xffff0000, v164
	v_and_b32_e32 v156, 0xffff0000, v168
	v_mul_f32_e32 v152, 0x3b808081, v152
	v_mul_f32_e32 v153, 0x3b808081, v153
	v_mul_f32_e32 v154, 0x3b808081, v154
	v_mul_f32_e32 v157, v152, v155
	v_fmac_f32_e32 v157, v153, v156
	v_fma_f32 v103, v154, v103, v157
	v_cvt_f32_ubyte2_e32 v152, v130
	v_cvt_f32_ubyte2_e32 v153, v132
	v_cvt_f32_ubyte2_e32 v154, v134
	v_lshlrev_b32_e32 v155, 16, v165
	v_lshlrev_b32_e32 v156, 16, v169
	v_mul_f32_e32 v152, 0x3b808081, v152
	v_mul_f32_e32 v153, 0x3b808081, v153
	v_mul_f32_e32 v154, 0x3b808081, v154
	v_mul_f32_e32 v157, v152, v155
	v_fmac_f32_e32 v157, v153, v156
	v_fma_f32 v104, v154, v104, v157
	v_cvt_f32_ubyte3_e32 v152, v130
	v_cvt_f32_ubyte3_e32 v153, v132
	v_cvt_f32_ubyte3_e32 v154, v134
	v_and_b32_e32 v155, 0xffff0000, v165
	v_and_b32_e32 v156, 0xffff0000, v169
	v_mul_f32_e32 v152, 0x3b808081, v152
	v_mul_f32_e32 v153, 0x3b808081, v153
	v_mul_f32_e32 v154, 0x3b808081, v154
; __device__ __forceinline__ void unpack8(const u32x4 w, float* f) { f[0] = bflo(w.x); f[1] = bfhi(w.x); f[2] = bflo(w.y); f[3] = bfhi(w.y); f[4] = bflo(w.z); f[5] = bfhi(w.z); f[6] = bflo(w.w); f[7] = bfhi(w.w); }
; __device__ __forceinline__ u32x4 pack8(const float* f) { u32x4 w; w.x = cvt_pk(f[0], f[1]); w.y = cvt_pk(f[2], f[3]); w.z = cvt_pk(f[4], f[5]); w.w = cvt_pk(f[6], f[7]); return w; }
;     __device__ __forceinline__ void operator()(const f32x4 (&acc)[2][2][4][2], const UnitD& u, int wr, int wc, int fr, int fq) const {
;     ...
;             for (int ai = 0; ai < 2; ++ai)
; #pragma unroll
;                 for (int m = 0; m < 4; ++m) { const int row = row0 + ai * HALF + m * 16;
;                     const unsigned char* gp = (const unsigned char*)(proj + (size_t)row * NP + C_G) + col0; const size_t po = (size_t)row * 2048 + col0;
;                     u32x2 g0[2], g1[2], g2[2]; u32x4 a[2], b[2];
; #pragma unroll
;                     for (int bj = 0; bj < 2; ++bj) { g0[bj] = *(const u32x2*)(gp + bj * HALF); g1[bj] = *(const u32x2*)(gp + 2048 + bj * HALF); g2[bj] = *(const u32x2*)(gp + 4096 + bj * HALF);
;                         a[bj] = *(const u32x4*)(PA + po + bj * HALF); b[bj] = *(const u32x4*)(PB + po + bj * HALF); }
; #pragma unroll
;                     for (int bj = 0; bj < 2; ++bj) { float f0[8], f1[8], f2[8], fa[8], fb[8], o[8];
;                         unpack_u8(g0[bj], f0); unpack_u8(g1[bj], f1); unpack_u8(g2[bj], f2); unpack8(a[bj], fa); unpack8(b[bj], fb);
;                         const f32x4 v0 = acc[ai][bj][m][0], v1 = acc[ai][bj][m][1];
; #pragma unroll
;                         for (int j = 0; j < 4; ++j) { o[j] = f0[j] * fa[j] + f1[j] * fb[j] + f2[j] * v0[j]; o[4 + j] = f0[4 + j] * fa[4 + j] + f1[4 + j] * fb[4 + j] + f2[4 + j] * v1[j]; }
;                         *(u32x4*)(H + po + bj * HALF) = pack8(o); } }
	v_mul_f32_e32 v157, v152, v155
	v_fmac_f32_e32 v157, v153, v156
	v_fma_f32 v105, v154, v105, v157
	v_cvt_f32_ubyte0_e32 v152, v131
	v_cvt_f32_ubyte0_e32 v153, v133
	v_cvt_f32_ubyte0_e32 v154, v135
	v_lshlrev_b32_e32 v155, 16, v166
	v_lshlrev_b32_e32 v156, 16, v170
	v_mul_f32_e32 v152, 0x3b808081, v152
	v_mul_f32_e32 v153, 0x3b808081, v153
	v_mul_f32_e32 v154, 0x3b808081, v154
	v_mul_f32_e32 v157, v152, v155
	v_fmac_f32_e32 v157, v153, v156
	v_fma_f32 v98, v154, v98, v157
	v_cvt_f32_ubyte1_e32 v152, v131
	v_cvt_f32_ubyte1_e32 v153, v133
	v_cvt_f32_ubyte1_e32 v154, v135
	v_and_b32_e32 v155, 0xffff0000, v166
	v_and_b32_e32 v156, 0xffff0000, v170
	v_mul_f32_e32 v152, 0x3b808081, v152
	v_mul_f32_e32 v153, 0x3b808081, v153
	v_mul_f32_e32 v154, 0x3b808081, v154
	v_mul_f32_e32 v157, v152, v155
	v_fmac_f32_e32 v157, v153, v156
	v_fma_f32 v99, v154, v99, v157
	v_cvt_f32_ubyte2_e32 v152, v131
	v_cvt_f32_ubyte2_e32 v153, v133
	v_cvt_f32_ubyte2_e32 v154, v135
	v_lshlrev_b32_e32 v155, 16, v167
	v_lshlrev_b32_e32 v156, 16, v171
	v_mul_f32_e32 v152, 0x3b808081, v152
	v_mul_f32_e32 v153, 0x3b808081, v153
	v_mul_f32_e32 v154, 0x3b808081, v154
	v_mul_f32_e32 v157, v152, v155
	v_fmac_f32_e32 v157, v153, v156
	v_fma_f32 v100, v154, v100, v157
	v_cvt_f32_ubyte3_e32 v152, v131
	v_cvt_f32_ubyte3_e32 v153, v133
	v_cvt_f32_ubyte3_e32 v154, v135
	v_and_b32_e32 v155, 0xffff0000, v167
	v_and_b32_e32 v156, 0xffff0000, v171
	v_mul_f32_e32 v152, 0x3b808081, v152
	v_mul_f32_e32 v153, 0x3b808081, v153
	v_mul_f32_e32 v154, 0x3b808081, v154
	v_mul_f32_e32 v157, v152, v155
	v_fmac_f32_e32 v157, v153, v156
	v_fma_f32 v101, v154, v101, v157
	v_cvt_pk_bf16_f32 v102, v102, v103
	v_cvt_pk_bf16_f32 v103, v104, v105
	v_cvt_pk_bf16_f32 v104, v98, v99
	v_cvt_pk_bf16_f32 v105, v100, v101
	global_store_dwordx4 v149, v[102:105], s[62:63]
	s_waitcnt lgkmcnt(0)
	v_cvt_f32_ubyte0_e32 v152, v136
	v_cvt_f32_ubyte0_e32 v153, v160
	v_cvt_f32_ubyte0_e32 v154, v162
	v_lshlrev_b32_e32 v155, 16, v172
	v_lshlrev_b32_e32 v156, 16, v176
	v_mul_f32_e32 v152, 0x3b808081, v152
	v_mul_f32_e32 v153, 0x3b808081, v153
	v_mul_f32_e32 v154, 0x3b808081, v154
	v_mul_f32_e32 v157, v152, v155
	v_fmac_f32_e32 v157, v153, v156
	v_fma_f32 v78, v154, v78, v157
	v_cvt_f32_ubyte1_e32 v152, v136
	v_cvt_f32_ubyte1_e32 v153, v160
	v_cvt_f32_ubyte1_e32 v154, v162
	v_and_b32_e32 v155, 0xffff0000, v172
	v_and_b32_e32 v156, 0xffff0000, v176
	v_mul_f32_e32 v152, 0x3b808081, v152
	v_mul_f32_e32 v153, 0x3b808081, v153
	v_mul_f32_e32 v154, 0x3b808081, v154
	v_mul_f32_e32 v157, v152, v155
	v_fmac_f32_e32 v157, v153, v156
	v_fma_f32 v79, v154, v79, v157
	v_cvt_f32_ubyte2_e32 v152, v136
	v_cvt_f32_ubyte2_e32 v153, v160
	v_cvt_f32_ubyte2_e32 v154, v162
	v_lshlrev_b32_e32 v155, 16, v173
	v_lshlrev_b32_e32 v156, 16, v177
	v_mul_f32_e32 v152, 0x3b808081, v152
	v_mul_f32_e32 v153, 0x3b808081, v153
	v_mul_f32_e32 v154, 0x3b808081, v154
	v_mul_f32_e32 v157, v152, v155
	v_fmac_f32_e32 v157, v153, v156
	v_fma_f32 v80, v154, v80, v157
	v_cvt_f32_ubyte3_e32 v152, v136
	v_cvt_f32_ubyte3_e32 v153, v160
	v_cvt_f32_ubyte3_e32 v154, v162
	v_and_b32_e32 v155, 0xffff0000, v173
	v_and_b32_e32 v156, 0xffff0000, v177
	v_mul_f32_e32 v152, 0x3b808081, v152
	v_mul_f32_e32 v153, 0x3b808081, v153
	v_mul_f32_e32 v154, 0x3b808081, v154
	v_mul_f32_e32 v157, v152, v155
	v_fmac_f32_e32 v157, v153, v156
	v_fma_f32 v81, v154, v81, v157
	v_cvt_f32_ubyte0_e32 v152, v137
	v_cvt_f32_ubyte0_e32 v153, v161
	v_cvt_f32_ubyte0_e32 v154, v163
	v_lshlrev_b32_e32 v155, 16, v174
	v_lshlrev_b32_e32 v156, 16, v178
	v_mul_f32_e32 v152, 0x3b808081, v152
	v_mul_f32_e32 v153, 0x3b808081, v153
	v_mul_f32_e32 v154, 0x3b808081, v154
	v_mul_f32_e32 v157, v152, v155
	v_fmac_f32_e32 v157, v153, v156
	v_fma_f32 v74, v154, v74, v157
	v_cvt_f32_ubyte1_e32 v152, v137
	v_cvt_f32_ubyte1_e32 v153, v161
	v_cvt_f32_ubyte1_e32 v154, v163
	v_and_b32_e32 v155, 0xffff0000, v174
	v_and_b32_e32 v156, 0xffff0000, v178
	v_mul_f32_e32 v152, 0x3b808081, v152
	v_mul_f32_e32 v153, 0x3b808081, v153
	v_mul_f32_e32 v154, 0x3b808081, v154
	v_mul_f32_e32 v157, v152, v155
	v_fmac_f32_e32 v157, v153, v156
	v_fma_f32 v75, v154, v75, v157
	v_cvt_f32_ubyte2_e32 v152, v137
	v_cvt_f32_ubyte2_e32 v153, v161
	v_cvt_f32_ubyte2_e32 v154, v163
	v_lshlrev_b32_e32 v155, 16, v175
	v_lshlrev_b32_e32 v156, 16, v179
	v_mul_f32_e32 v152, 0x3b808081, v152
	v_mul_f32_e32 v153, 0x3b808081, v153
	v_mul_f32_e32 v154, 0x3b808081, v154
	v_mul_f32_e32 v157, v152, v155
	v_fmac_f32_e32 v157, v153, v156
	v_fma_f32 v76, v154, v76, v157
	v_cvt_f32_ubyte3_e32 v152, v137
	v_cvt_f32_ubyte3_e32 v153, v161
	v_cvt_f32_ubyte3_e32 v154, v163
	v_and_b32_e32 v155, 0xffff0000, v175
	v_and_b32_e32 v156, 0xffff0000, v179
	v_mul_f32_e32 v152, 0x3b808081, v152
	v_mul_f32_e32 v153, 0x3b808081, v153
	v_mul_f32_e32 v154, 0x3b808081, v154
	v_mul_f32_e32 v157, v152, v155
	v_fmac_f32_e32 v157, v153, v156
	v_fma_f32 v77, v154, v77, v157
	v_cvt_pk_bf16_f32 v78, v78, v79
	v_cvt_pk_bf16_f32 v79, v80, v81
	v_cvt_pk_bf16_f32 v80, v74, v75
	v_cvt_pk_bf16_f32 v81, v76, v77
	global_store_dwordx4 v149, v[78:81], s[62:63] offset:256
	v_add_u32_e32 v147, 0x80000, v145
	v_add_u32_e32 v148, 0x410000, v146
	global_load_dwordx2 v[130:131], v148, s[20:21] offset:-2048
	global_load_dwordx2 v[132:133], v148, s[20:21]
	global_load_dwordx2 v[134:135], v148, s[20:21] offset:2048
	global_load_dwordx2 v[136:137], v148, s[20:21] offset:-1920
	global_load_dwordx2 v[160:161], v148, s[20:21] offset:128
	global_load_dwordx2 v[162:163], v148, s[20:21] offset:2176
	global_load_dwordx4 v[164:167], v147, s[58:59]
	global_load_dwordx4 v[168:171], v147, s[60:61]
	global_load_dwordx4 v[172:175], v147, s[58:59] offset:256
	global_load_dwordx4 v[176:179], v147, s[60:61] offset:256
	ds_write_b128 v251, v[86:89]
	ds_read_b128 v[86:89], v252
	ds_write_b128 v251, v[82:85]
	ds_read_b128 v[82:85], v252
	ds_write_b128 v251, v[70:73]
	ds_read_b128 v[70:73], v252
	ds_write_b128 v251, v[66:69]
	ds_read_b128 v[66:69], v252
	v_add_u32_e32 v149, 0x30000, v145
	s_waitcnt vmcnt(12)
; __device__ __forceinline__ void unpack8(const u32x4 w, float* f) { f[0] = bflo(w.x); f[1] = bfhi(w.x); f[2] = bflo(w.y); f[3] = bfhi(w.y); f[4] = bflo(w.z); f[5] = bfhi(w.z); f[6] = bflo(w.w); f[7] = bfhi(w.w); }
; __device__ __forceinline__ u32x4 pack8(const float* f) { u32x4 w; w.x = cvt_pk(f[0], f[1]); w.y = cvt_pk(f[2], f[3]); w.z = cvt_pk(f[4], f[5]); w.w = cvt_pk(f[6], f[7]); return w; }
;     __device__ __forceinline__ void operator()(const f32x4 (&acc)[2][2][4][2], const UnitD& u, int wr, int wc, int fr, int fq) const {
;     ...
;                 for (int m = 0; m < 4; ++m) { const int row = row0 + ai * HALF + m * 16;
;                     const unsigned char* gp = (const unsigned char*)(proj + (size_t)row * NP + C_G) + col0; const size_t po = (size_t)row * 2048 + col0;
;                     u32x2 g0[2], g1[2], g2[2]; u32x4 a[2], b[2];
; #pragma unroll
;                     for (int bj = 0; bj < 2; ++bj) { g0[bj] = *(const u32x2*)(gp + bj * HALF); g1[bj] = *(const u32x2*)(gp + 2048 + bj * HALF); g2[bj] = *(const u32x2*)(gp + 4096 + bj * HALF);
;                         a[bj] = *(const u32x4*)(PA + po + bj * HALF); b[bj] = *(const u32x4*)(PB + po + bj * HALF); }
; #pragma unroll
;                     for (int bj = 0; bj < 2; ++bj) { float f0[8], f1[8], f2[8], fa[8], fb[8], o[8];
;                         unpack_u8(g0[bj], f0); unpack_u8(g1[bj], f1); unpack_u8(g2[bj], f2); unpack8(a[bj], fa); unpack8(b[bj], fb);
;                         const f32x4 v0 = acc[ai][bj][m][0], v1 = acc[ai][bj][m][1];
; #pragma unroll
;                         for (int j = 0; j < 4; ++j) { o[j] = f0[j] * fa[j] + f1[j] * fb[j] + f2[j] * v0[j]; o[4 + j] = f0[4 + j] * fa[4 + j] + f1[4 + j] * fb[4 + j] + f2[4 + j] * v1[j]; }
;                         *(u32x4*)(H + po + bj * HALF) = pack8(o); } }
	s_waitcnt lgkmcnt(4)
	v_cvt_f32_ubyte0_e32 v152, v198
	v_cvt_f32_ubyte0_e32 v153, v200
	v_cvt_f32_ubyte0_e32 v154, v202
	v_lshlrev_b32_e32 v155, 16, v210
	v_lshlrev_b32_e32 v156, 16, v214
	v_mul_f32_e32 v152, 0x3b808081, v152
	v_mul_f32_e32 v153, 0x3b808081, v153
	v_mul_f32_e32 v154, 0x3b808081, v154
	v_mul_f32_e32 v157, v152, v155
	v_fmac_f32_e32 v157, v153, v156
	v_fma_f32 v86, v154, v86, v157
	v_cvt_f32_ubyte1_e32 v152, v198
	v_cvt_f32_ubyte1_e32 v153, v200
	v_cvt_f32_ubyte1_e32 v154, v202
	v_and_b32_e32 v155, 0xffff0000, v210
	v_and_b32_e32 v156, 0xffff0000, v214
	v_mul_f32_e32 v152, 0x3b808081, v152
	v_mul_f32_e32 v153, 0x3b808081, v153
	v_mul_f32_e32 v154, 0x3b808081, v154
	v_mul_f32_e32 v157, v152, v155
	v_fmac_f32_e32 v157, v153, v156
	v_fma_f32 v87, v154, v87, v157
	v_cvt_f32_ubyte2_e32 v152, v198
	v_cvt_f32_ubyte2_e32 v153, v200
	v_cvt_f32_ubyte2_e32 v154, v202
	v_lshlrev_b32_e32 v155, 16, v211
	v_lshlrev_b32_e32 v156, 16, v215
	v_mul_f32_e32 v152, 0x3b808081, v152
	v_mul_f32_e32 v153, 0x3b808081, v153
	v_mul_f32_e32 v154, 0x3b808081, v154
	v_mul_f32_e32 v157, v152, v155
	v_fmac_f32_e32 v157, v153, v156
	v_fma_f32 v88, v154, v88, v157
	v_cvt_f32_ubyte3_e32 v152, v198
	v_cvt_f32_ubyte3_e32 v153, v200
	v_cvt_f32_ubyte3_e32 v154, v202
	v_and_b32_e32 v155, 0xffff0000, v211
	v_and_b32_e32 v156, 0xffff0000, v215
	v_mul_f32_e32 v152, 0x3b808081, v152
	v_mul_f32_e32 v153, 0x3b808081, v153
	v_mul_f32_e32 v154, 0x3b808081, v154
	v_mul_f32_e32 v157, v152, v155
	v_fmac_f32_e32 v157, v153, v156
	v_fma_f32 v89, v154, v89, v157
	v_cvt_f32_ubyte0_e32 v152, v199
	v_cvt_f32_ubyte0_e32 v153, v201
	v_cvt_f32_ubyte0_e32 v154, v203
	v_lshlrev_b32_e32 v155, 16, v212
	v_lshlrev_b32_e32 v156, 16, v216
	v_mul_f32_e32 v152, 0x3b808081, v152
	v_mul_f32_e32 v153, 0x3b808081, v153
	v_mul_f32_e32 v154, 0x3b808081, v154
	v_mul_f32_e32 v157, v152, v155
	v_fmac_f32_e32 v157, v153, v156
	v_fma_f32 v82, v154, v82, v157
	v_cvt_f32_ubyte1_e32 v152, v199
	v_cvt_f32_ubyte1_e32 v153, v201
	v_cvt_f32_ubyte1_e32 v154, v203
	v_and_b32_e32 v155, 0xffff0000, v212
	v_and_b32_e32 v156, 0xffff0000, v216
	v_mul_f32_e32 v152, 0x3b808081, v152
	v_mul_f32_e32 v153, 0x3b808081, v153
	v_mul_f32_e32 v154, 0x3b808081, v154
	v_mul_f32_e32 v157, v152, v155
	v_fmac_f32_e32 v157, v153, v156
	v_fma_f32 v83, v154, v83, v157
	v_cvt_f32_ubyte2_e32 v152, v199
	v_cvt_f32_ubyte2_e32 v153, v201
	v_cvt_f32_ubyte2_e32 v154, v203
	v_lshlrev_b32_e32 v155, 16, v213
	v_lshlrev_b32_e32 v156, 16, v217
	v_mul_f32_e32 v152, 0x3b808081, v152
	v_mul_f32_e32 v153, 0x3b808081, v153
	v_mul_f32_e32 v154, 0x3b808081, v154
	v_mul_f32_e32 v157, v152, v155
	v_fmac_f32_e32 v157, v153, v156
	v_fma_f32 v84, v154, v84, v157
	v_cvt_f32_ubyte3_e32 v152, v199
	v_cvt_f32_ubyte3_e32 v153, v201
	v_cvt_f32_ubyte3_e32 v154, v203
	v_and_b32_e32 v155, 0xffff0000, v213
	v_and_b32_e32 v156, 0xffff0000, v217
	v_mul_f32_e32 v152, 0x3b808081, v152
	v_mul_f32_e32 v153, 0x3b808081, v153
	v_mul_f32_e32 v154, 0x3b808081, v154
	v_mul_f32_e32 v157, v152, v155
	v_fmac_f32_e32 v157, v153, v156
	v_fma_f32 v85, v154, v85, v157
	v_cvt_pk_bf16_f32 v86, v86, v87
	v_cvt_pk_bf16_f32 v87, v88, v89
	v_cvt_pk_bf16_f32 v88, v82, v83
	v_cvt_pk_bf16_f32 v89, v84, v85
	global_store_dwordx4 v149, v[86:89], s[62:63]
	s_waitcnt lgkmcnt(0)
	v_cvt_f32_ubyte0_e32 v152, v204
	v_cvt_f32_ubyte0_e32 v153, v206
	v_cvt_f32_ubyte0_e32 v154, v208
	v_lshlrev_b32_e32 v155, 16, v218
	v_lshlrev_b32_e32 v156, 16, v222
	v_mul_f32_e32 v152, 0x3b808081, v152
	v_mul_f32_e32 v153, 0x3b808081, v153
	v_mul_f32_e32 v154, 0x3b808081, v154
	v_mul_f32_e32 v157, v152, v155
	v_fmac_f32_e32 v157, v153, v156
	v_fma_f32 v70, v154, v70, v157
	v_cvt_f32_ubyte1_e32 v152, v204
	v_cvt_f32_ubyte1_e32 v153, v206
	v_cvt_f32_ubyte1_e32 v154, v208
	v_and_b32_e32 v155, 0xffff0000, v218
	v_and_b32_e32 v156, 0xffff0000, v222
	v_mul_f32_e32 v152, 0x3b808081, v152
	v_mul_f32_e32 v153, 0x3b808081, v153
	v_mul_f32_e32 v154, 0x3b808081, v154
	v_mul_f32_e32 v157, v152, v155
	v_fmac_f32_e32 v157, v153, v156
	v_fma_f32 v71, v154, v71, v157
	v_cvt_f32_ubyte2_e32 v152, v204
	v_cvt_f32_ubyte2_e32 v153, v206
	v_cvt_f32_ubyte2_e32 v154, v208
	v_lshlrev_b32_e32 v155, 16, v219
	v_lshlrev_b32_e32 v156, 16, v223
	v_mul_f32_e32 v152, 0x3b808081, v152
	v_mul_f32_e32 v153, 0x3b808081, v153
	v_mul_f32_e32 v154, 0x3b808081, v154
	v_mul_f32_e32 v157, v152, v155
	v_fmac_f32_e32 v157, v153, v156
	v_fma_f32 v72, v154, v72, v157
	v_cvt_f32_ubyte3_e32 v152, v204
	v_cvt_f32_ubyte3_e32 v153, v206
	v_cvt_f32_ubyte3_e32 v154, v208
	v_and_b32_e32 v155, 0xffff0000, v219
	v_and_b32_e32 v156, 0xffff0000, v223
	v_mul_f32_e32 v152, 0x3b808081, v152
	v_mul_f32_e32 v153, 0x3b808081, v153
	v_mul_f32_e32 v154, 0x3b808081, v154
	v_mul_f32_e32 v157, v152, v155
	v_fmac_f32_e32 v157, v153, v156
	v_fma_f32 v73, v154, v73, v157
	v_cvt_f32_ubyte0_e32 v152, v205
	v_cvt_f32_ubyte0_e32 v153, v207
	v_cvt_f32_ubyte0_e32 v154, v209
	v_lshlrev_b32_e32 v155, 16, v220
	v_lshlrev_b32_e32 v156, 16, v224
	v_mul_f32_e32 v152, 0x3b808081, v152
	v_mul_f32_e32 v153, 0x3b808081, v153
	v_mul_f32_e32 v154, 0x3b808081, v154
	v_mul_f32_e32 v157, v152, v155
	v_fmac_f32_e32 v157, v153, v156
	v_fma_f32 v66, v154, v66, v157
	v_cvt_f32_ubyte1_e32 v152, v205
	v_cvt_f32_ubyte1_e32 v153, v207
	v_cvt_f32_ubyte1_e32 v154, v209
	v_and_b32_e32 v155, 0xffff0000, v220
	v_and_b32_e32 v156, 0xffff0000, v224
	v_mul_f32_e32 v152, 0x3b808081, v152
	v_mul_f32_e32 v153, 0x3b808081, v153
	v_mul_f32_e32 v154, 0x3b808081, v154
	v_mul_f32_e32 v157, v152, v155
	v_fmac_f32_e32 v157, v153, v156
	v_fma_f32 v67, v154, v67, v157
	v_cvt_f32_ubyte2_e32 v152, v205
	v_cvt_f32_ubyte2_e32 v153, v207
; __device__ __forceinline__ void unpack8(const u32x4 w, float* f) { f[0] = bflo(w.x); f[1] = bfhi(w.x); f[2] = bflo(w.y); f[3] = bfhi(w.y); f[4] = bflo(w.z); f[5] = bfhi(w.z); f[6] = bflo(w.w); f[7] = bfhi(w.w); }
; __device__ __forceinline__ u32x4 pack8(const float* f) { u32x4 w; w.x = cvt_pk(f[0], f[1]); w.y = cvt_pk(f[2], f[3]); w.z = cvt_pk(f[4], f[5]); w.w = cvt_pk(f[6], f[7]); return w; }
;     __device__ __forceinline__ void operator()(const f32x4 (&acc)[2][2][4][2], const UnitD& u, int wr, int wc, int fr, int fq) const {
;     ...
;                 for (int m = 0; m < 4; ++m) { const int row = row0 + ai * HALF + m * 16;
;                     const unsigned char* gp = (const unsigned char*)(proj + (size_t)row * NP + C_G) + col0; const size_t po = (size_t)row * 2048 + col0;
;                     u32x2 g0[2], g1[2], g2[2]; u32x4 a[2], b[2];
; #pragma unroll
;                     for (int bj = 0; bj < 2; ++bj) { g0[bj] = *(const u32x2*)(gp + bj * HALF); g1[bj] = *(const u32x2*)(gp + 2048 + bj * HALF); g2[bj] = *(const u32x2*)(gp + 4096 + bj * HALF);
;                         a[bj] = *(const u32x4*)(PA + po + bj * HALF); b[bj] = *(const u32x4*)(PB + po + bj * HALF); }
; #pragma unroll
;                     for (int bj = 0; bj < 2; ++bj) { float f0[8], f1[8], f2[8], fa[8], fb[8], o[8];
;                         unpack_u8(g0[bj], f0); unpack_u8(g1[bj], f1); unpack_u8(g2[bj], f2); unpack8(a[bj], fa); unpack8(b[bj], fb);
;                         const f32x4 v0 = acc[ai][bj][m][0], v1 = acc[ai][bj][m][1];
; #pragma unroll
;                         for (int j = 0; j < 4; ++j) { o[j] = f0[j] * fa[j] + f1[j] * fb[j] + f2[j] * v0[j]; o[4 + j] = f0[4 + j] * fa[4 + j] + f1[4 + j] * fb[4 + j] + f2[4 + j] * v1[j]; }
;                         *(u32x4*)(H + po + bj * HALF) = pack8(o); } }
	v_cvt_f32_ubyte2_e32 v154, v209
	v_lshlrev_b32_e32 v155, 16, v221
	v_lshlrev_b32_e32 v156, 16, v225
	v_mul_f32_e32 v152, 0x3b808081, v152
	v_mul_f32_e32 v153, 0x3b808081, v153
	v_mul_f32_e32 v154, 0x3b808081, v154
	v_mul_f32_e32 v157, v152, v155
	v_fmac_f32_e32 v157, v153, v156
	v_fma_f32 v68, v154, v68, v157
	v_cvt_f32_ubyte3_e32 v152, v205
	v_cvt_f32_ubyte3_e32 v153, v207
	v_cvt_f32_ubyte3_e32 v154, v209
	v_and_b32_e32 v155, 0xffff0000, v221
	v_and_b32_e32 v156, 0xffff0000, v225
	v_mul_f32_e32 v152, 0x3b808081, v152
	v_mul_f32_e32 v153, 0x3b808081, v153
	v_mul_f32_e32 v154, 0x3b808081, v154
	v_mul_f32_e32 v157, v152, v155
	v_fmac_f32_e32 v157, v153, v156
	v_fma_f32 v69, v154, v69, v157
	v_cvt_pk_bf16_f32 v70, v70, v71
	v_cvt_pk_bf16_f32 v71, v72, v73
	v_cvt_pk_bf16_f32 v72, v66, v67
	v_cvt_pk_bf16_f32 v73, v68, v69
	global_store_dwordx4 v149, v[70:73], s[62:63] offset:256
	v_add_u32_e32 v147, 0x90000, v145
	v_add_u32_e32 v148, 0x492000, v146
	global_load_dwordx2 v[198:199], v148, s[20:21] offset:-2048
	global_load_dwordx2 v[200:201], v148, s[20:21]
	global_load_dwordx2 v[202:203], v148, s[20:21] offset:2048
	global_load_dwordx2 v[204:205], v148, s[20:21] offset:-1920
	global_load_dwordx2 v[206:207], v148, s[20:21] offset:128
	global_load_dwordx2 v[208:209], v148, s[20:21] offset:2176
	global_load_dwordx4 v[210:213], v147, s[58:59]
	global_load_dwordx4 v[214:217], v147, s[60:61]
	global_load_dwordx4 v[218:221], v147, s[58:59] offset:256
	global_load_dwordx4 v[222:225], v147, s[60:61] offset:256
	ds_write_b128 v251, v[62:65]
	ds_read_b128 v[62:65], v252
	ds_write_b128 v251, v[58:61]
	ds_read_b128 v[58:61], v252
	ds_write_b128 v251, v[46:49]
	ds_read_b128 v[46:49], v252
	ds_write_b128 v251, v[42:45]
	ds_read_b128 v[42:45], v252
	v_add_u32_e32 v149, 0x80000, v145
	s_waitcnt vmcnt(12)
	s_waitcnt lgkmcnt(4)
	v_cvt_f32_ubyte0_e32 v152, v130
	v_cvt_f32_ubyte0_e32 v153, v132
	v_cvt_f32_ubyte0_e32 v154, v134
	v_lshlrev_b32_e32 v155, 16, v164
	v_lshlrev_b32_e32 v156, 16, v168
	v_mul_f32_e32 v152, 0x3b808081, v152
	v_mul_f32_e32 v153, 0x3b808081, v153
	v_mul_f32_e32 v154, 0x3b808081, v154
	v_mul_f32_e32 v157, v152, v155
	v_fmac_f32_e32 v157, v153, v156
	v_fma_f32 v62, v154, v62, v157
	v_cvt_f32_ubyte1_e32 v152, v130
	v_cvt_f32_ubyte1_e32 v153, v132
	v_cvt_f32_ubyte1_e32 v154, v134
	v_and_b32_e32 v155, 0xffff0000, v164
	v_and_b32_e32 v156, 0xffff0000, v168
	v_mul_f32_e32 v152, 0x3b808081, v152
	v_mul_f32_e32 v153, 0x3b808081, v153
	v_mul_f32_e32 v154, 0x3b808081, v154
	v_mul_f32_e32 v157, v152, v155
	v_fmac_f32_e32 v157, v153, v156
	v_fma_f32 v63, v154, v63, v157
	v_cvt_f32_ubyte2_e32 v152, v130
	v_cvt_f32_ubyte2_e32 v153, v132
	v_cvt_f32_ubyte2_e32 v154, v134
	v_lshlrev_b32_e32 v155, 16, v165
	v_lshlrev_b32_e32 v156, 16, v169
	v_mul_f32_e32 v152, 0x3b808081, v152
	v_mul_f32_e32 v153, 0x3b808081, v153
	v_mul_f32_e32 v154, 0x3b808081, v154
	v_mul_f32_e32 v157, v152, v155
	v_fmac_f32_e32 v157, v153, v156
	v_fma_f32 v64, v154, v64, v157
	v_cvt_f32_ubyte3_e32 v152, v130
	v_cvt_f32_ubyte3_e32 v153, v132
	v_cvt_f32_ubyte3_e32 v154, v134
	v_and_b32_e32 v155, 0xffff0000, v165
	v_and_b32_e32 v156, 0xffff0000, v169
	v_mul_f32_e32 v152, 0x3b808081, v152
	v_mul_f32_e32 v153, 0x3b808081, v153
	v_mul_f32_e32 v154, 0x3b808081, v154
	v_mul_f32_e32 v157, v152, v155
	v_fmac_f32_e32 v157, v153, v156
	v_fma_f32 v65, v154, v65, v157
	v_cvt_f32_ubyte0_e32 v152, v131
	v_cvt_f32_ubyte0_e32 v153, v133
	v_cvt_f32_ubyte0_e32 v154, v135
	v_lshlrev_b32_e32 v155, 16, v166
	v_lshlrev_b32_e32 v156, 16, v170
	v_mul_f32_e32 v152, 0x3b808081, v152
	v_mul_f32_e32 v153, 0x3b808081, v153
	v_mul_f32_e32 v154, 0x3b808081, v154
	v_mul_f32_e32 v157, v152, v155
	v_fmac_f32_e32 v157, v153, v156
	v_fma_f32 v58, v154, v58, v157
	v_cvt_f32_ubyte1_e32 v152, v131
	v_cvt_f32_ubyte1_e32 v153, v133
	v_cvt_f32_ubyte1_e32 v154, v135
	v_and_b32_e32 v155, 0xffff0000, v166
	v_and_b32_e32 v156, 0xffff0000, v170
	v_mul_f32_e32 v152, 0x3b808081, v152
	v_mul_f32_e32 v153, 0x3b808081, v153
	v_mul_f32_e32 v154, 0x3b808081, v154
	v_mul_f32_e32 v157, v152, v155
	v_fmac_f32_e32 v157, v153, v156
	v_fma_f32 v59, v154, v59, v157
	v_cvt_f32_ubyte2_e32 v152, v131
	v_cvt_f32_ubyte2_e32 v153, v133
	v_cvt_f32_ubyte2_e32 v154, v135
	v_lshlrev_b32_e32 v155, 16, v167
	v_lshlrev_b32_e32 v156, 16, v171
	v_mul_f32_e32 v152, 0x3b808081, v152
	v_mul_f32_e32 v153, 0x3b808081, v153
	v_mul_f32_e32 v154, 0x3b808081, v154
	v_mul_f32_e32 v157, v152, v155
	v_fmac_f32_e32 v157, v153, v156
	v_fma_f32 v60, v154, v60, v157
	v_cvt_f32_ubyte3_e32 v152, v131
	v_cvt_f32_ubyte3_e32 v153, v133
	v_cvt_f32_ubyte3_e32 v154, v135
	v_and_b32_e32 v155, 0xffff0000, v167
	v_and_b32_e32 v156, 0xffff0000, v171
	v_mul_f32_e32 v152, 0x3b808081, v152
	v_mul_f32_e32 v153, 0x3b808081, v153
	v_mul_f32_e32 v154, 0x3b808081, v154
	v_mul_f32_e32 v157, v152, v155
	v_fmac_f32_e32 v157, v153, v156
	v_fma_f32 v61, v154, v61, v157
	v_cvt_pk_bf16_f32 v62, v62, v63
	v_cvt_pk_bf16_f32 v63, v64, v65
	v_cvt_pk_bf16_f32 v64, v58, v59
	v_cvt_pk_bf16_f32 v65, v60, v61
	global_store_dwordx4 v149, v[62:65], s[62:63]
	s_waitcnt lgkmcnt(0)
; __device__ __forceinline__ void unpack8(const u32x4 w, float* f) { f[0] = bflo(w.x); f[1] = bfhi(w.x); f[2] = bflo(w.y); f[3] = bfhi(w.y); f[4] = bflo(w.z); f[5] = bfhi(w.z); f[6] = bflo(w.w); f[7] = bfhi(w.w); }
; __device__ __forceinline__ u32x4 pack8(const float* f) { u32x4 w; w.x = cvt_pk(f[0], f[1]); w.y = cvt_pk(f[2], f[3]); w.z = cvt_pk(f[4], f[5]); w.w = cvt_pk(f[6], f[7]); return w; }
;     __device__ __forceinline__ void operator()(const f32x4 (&acc)[2][2][4][2], const UnitD& u, int wr, int wc, int fr, int fq) const {
;     ...
;                 for (int m = 0; m < 4; ++m) { const int row = row0 + ai * HALF + m * 16;
;                     const unsigned char* gp = (const unsigned char*)(proj + (size_t)row * NP + C_G) + col0; const size_t po = (size_t)row * 2048 + col0;
;                     u32x2 g0[2], g1[2], g2[2]; u32x4 a[2], b[2];
; #pragma unroll
;                     for (int bj = 0; bj < 2; ++bj) { g0[bj] = *(const u32x2*)(gp + bj * HALF); g1[bj] = *(const u32x2*)(gp + 2048 + bj * HALF); g2[bj] = *(const u32x2*)(gp + 4096 + bj * HALF);
;                         a[bj] = *(const u32x4*)(PA + po + bj * HALF); b[bj] = *(const u32x4*)(PB + po + bj * HALF); }
; #pragma unroll
;                     for (int bj = 0; bj < 2; ++bj) { float f0[8], f1[8], f2[8], fa[8], fb[8], o[8];
;                         unpack_u8(g0[bj], f0); unpack_u8(g1[bj], f1); unpack_u8(g2[bj], f2); unpack8(a[bj], fa); unpack8(b[bj], fb);
;                         const f32x4 v0 = acc[ai][bj][m][0], v1 = acc[ai][bj][m][1];
; #pragma unroll
;                         for (int j = 0; j < 4; ++j) { o[j] = f0[j] * fa[j] + f1[j] * fb[j] + f2[j] * v0[j]; o[4 + j] = f0[4 + j] * fa[4 + j] + f1[4 + j] * fb[4 + j] + f2[4 + j] * v1[j]; }
;                         *(u32x4*)(H + po + bj * HALF) = pack8(o); } }
	v_cvt_f32_ubyte0_e32 v152, v136
	v_cvt_f32_ubyte0_e32 v153, v160
	v_cvt_f32_ubyte0_e32 v154, v162
	v_lshlrev_b32_e32 v155, 16, v172
	v_lshlrev_b32_e32 v156, 16, v176
	v_mul_f32_e32 v152, 0x3b808081, v152
	v_mul_f32_e32 v153, 0x3b808081, v153
	v_mul_f32_e32 v154, 0x3b808081, v154
	v_mul_f32_e32 v157, v152, v155
	v_fmac_f32_e32 v157, v153, v156
	v_fma_f32 v46, v154, v46, v157
	v_cvt_f32_ubyte1_e32 v152, v136
	v_cvt_f32_ubyte1_e32 v153, v160
	v_cvt_f32_ubyte1_e32 v154, v162
	v_and_b32_e32 v155, 0xffff0000, v172
	v_and_b32_e32 v156, 0xffff0000, v176
	v_mul_f32_e32 v152, 0x3b808081, v152
	v_mul_f32_e32 v153, 0x3b808081, v153
	v_mul_f32_e32 v154, 0x3b808081, v154
	v_mul_f32_e32 v157, v152, v155
	v_fmac_f32_e32 v157, v153, v156
	v_fma_f32 v47, v154, v47, v157
	v_cvt_f32_ubyte2_e32 v152, v136
	v_cvt_f32_ubyte2_e32 v153, v160
	v_cvt_f32_ubyte2_e32 v154, v162
	v_lshlrev_b32_e32 v155, 16, v173
	v_lshlrev_b32_e32 v156, 16, v177
	v_mul_f32_e32 v152, 0x3b808081, v152
	v_mul_f32_e32 v153, 0x3b808081, v153
	v_mul_f32_e32 v154, 0x3b808081, v154
	v_mul_f32_e32 v157, v152, v155
	v_fmac_f32_e32 v157, v153, v156
	v_fma_f32 v48, v154, v48, v157
	v_cvt_f32_ubyte3_e32 v152, v136
	v_cvt_f32_ubyte3_e32 v153, v160
	v_cvt_f32_ubyte3_e32 v154, v162
	v_and_b32_e32 v155, 0xffff0000, v173
	v_and_b32_e32 v156, 0xffff0000, v177
	v_mul_f32_e32 v152, 0x3b808081, v152
	v_mul_f32_e32 v153, 0x3b808081, v153
	v_mul_f32_e32 v154, 0x3b808081, v154
	v_mul_f32_e32 v157, v152, v155
	v_fmac_f32_e32 v157, v153, v156
	v_fma_f32 v49, v154, v49, v157
	v_cvt_f32_ubyte0_e32 v152, v137
	v_cvt_f32_ubyte0_e32 v153, v161
	v_cvt_f32_ubyte0_e32 v154, v163
	v_lshlrev_b32_e32 v155, 16, v174
	v_lshlrev_b32_e32 v156, 16, v178
	v_mul_f32_e32 v152, 0x3b808081, v152
	v_mul_f32_e32 v153, 0x3b808081, v153
	v_mul_f32_e32 v154, 0x3b808081, v154
	v_mul_f32_e32 v157, v152, v155
	v_fmac_f32_e32 v157, v153, v156
	v_fma_f32 v42, v154, v42, v157
	v_cvt_f32_ubyte1_e32 v152, v137
	v_cvt_f32_ubyte1_e32 v153, v161
	v_cvt_f32_ubyte1_e32 v154, v163
	v_and_b32_e32 v155, 0xffff0000, v174
	v_and_b32_e32 v156, 0xffff0000, v178
	v_mul_f32_e32 v152, 0x3b808081, v152
	v_mul_f32_e32 v153, 0x3b808081, v153
	v_mul_f32_e32 v154, 0x3b808081, v154
	v_mul_f32_e32 v157, v152, v155
	v_fmac_f32_e32 v157, v153, v156
	v_fma_f32 v43, v154, v43, v157
	v_cvt_f32_ubyte2_e32 v152, v137
	v_cvt_f32_ubyte2_e32 v153, v161
	v_cvt_f32_ubyte2_e32 v154, v163
	v_lshlrev_b32_e32 v155, 16, v175
	v_lshlrev_b32_e32 v156, 16, v179
	v_mul_f32_e32 v152, 0x3b808081, v152
	v_mul_f32_e32 v153, 0x3b808081, v153
	v_mul_f32_e32 v154, 0x3b808081, v154
	v_mul_f32_e32 v157, v152, v155
	v_fmac_f32_e32 v157, v153, v156
	v_fma_f32 v44, v154, v44, v157
	v_cvt_f32_ubyte3_e32 v152, v137
	v_cvt_f32_ubyte3_e32 v153, v161
	v_cvt_f32_ubyte3_e32 v154, v163
	v_and_b32_e32 v155, 0xffff0000, v175
	v_and_b32_e32 v156, 0xffff0000, v179
	v_mul_f32_e32 v152, 0x3b808081, v152
	v_mul_f32_e32 v153, 0x3b808081, v153
	v_mul_f32_e32 v154, 0x3b808081, v154
	v_mul_f32_e32 v157, v152, v155
	v_fmac_f32_e32 v157, v153, v156
	v_fma_f32 v45, v154, v45, v157
	v_cvt_pk_bf16_f32 v46, v46, v47
	v_cvt_pk_bf16_f32 v47, v48, v49
	v_cvt_pk_bf16_f32 v48, v42, v43
	v_cvt_pk_bf16_f32 v49, v44, v45
	global_store_dwordx4 v149, v[46:49], s[62:63] offset:256
	v_add_u32_e32 v147, 0xa0000, v145
	v_add_u32_e32 v148, 0x514000, v146
	global_load_dwordx2 v[130:131], v148, s[20:21] offset:-2048
	global_load_dwordx2 v[132:133], v148, s[20:21]
	global_load_dwordx2 v[134:135], v148, s[20:21] offset:2048
	global_load_dwordx2 v[136:137], v148, s[20:21] offset:-1920
	global_load_dwordx2 v[160:161], v148, s[20:21] offset:128
	global_load_dwordx2 v[162:163], v148, s[20:21] offset:2176
	global_load_dwordx4 v[164:167], v147, s[58:59]
	global_load_dwordx4 v[168:171], v147, s[60:61]
	global_load_dwordx4 v[172:175], v147, s[58:59] offset:256
	global_load_dwordx4 v[176:179], v147, s[60:61] offset:256
	ds_write_b128 v251, v[54:57]
	ds_read_b128 v[54:57], v252
	ds_write_b128 v251, v[50:53]
	ds_read_b128 v[50:53], v252
	ds_write_b128 v251, v[30:33]
	ds_read_b128 v[30:33], v252
	ds_write_b128 v251, v[26:29]
	ds_read_b128 v[26:29], v252
	v_add_u32_e32 v149, 0x90000, v145
	s_waitcnt vmcnt(12)
	s_waitcnt lgkmcnt(4)
	v_cvt_f32_ubyte0_e32 v152, v198
	v_cvt_f32_ubyte0_e32 v153, v200
	v_cvt_f32_ubyte0_e32 v154, v202
	v_lshlrev_b32_e32 v155, 16, v210
	v_lshlrev_b32_e32 v156, 16, v214
	v_mul_f32_e32 v152, 0x3b808081, v152
	v_mul_f32_e32 v153, 0x3b808081, v153
	v_mul_f32_e32 v154, 0x3b808081, v154
	v_mul_f32_e32 v157, v152, v155
	v_fmac_f32_e32 v157, v153, v156
	v_fma_f32 v54, v154, v54, v157
	v_cvt_f32_ubyte1_e32 v152, v198
	v_cvt_f32_ubyte1_e32 v153, v200
	v_cvt_f32_ubyte1_e32 v154, v202
	v_and_b32_e32 v155, 0xffff0000, v210
	v_and_b32_e32 v156, 0xffff0000, v214
	v_mul_f32_e32 v152, 0x3b808081, v152
	v_mul_f32_e32 v153, 0x3b808081, v153
	v_mul_f32_e32 v154, 0x3b808081, v154
	v_mul_f32_e32 v157, v152, v155
	v_fmac_f32_e32 v157, v153, v156
	v_fma_f32 v55, v154, v55, v157
	v_cvt_f32_ubyte2_e32 v152, v198
	v_cvt_f32_ubyte2_e32 v153, v200
	v_cvt_f32_ubyte2_e32 v154, v202
	v_lshlrev_b32_e32 v155, 16, v211
	v_lshlrev_b32_e32 v156, 16, v215
	v_mul_f32_e32 v152, 0x3b808081, v152
	v_mul_f32_e32 v153, 0x3b808081, v153
	v_mul_f32_e32 v154, 0x3b808081, v154
	v_mul_f32_e32 v157, v152, v155
	v_fmac_f32_e32 v157, v153, v156
	v_fma_f32 v56, v154, v56, v157
	v_cvt_f32_ubyte3_e32 v152, v198
	v_cvt_f32_ubyte3_e32 v153, v200
	v_cvt_f32_ubyte3_e32 v154, v202
	v_and_b32_e32 v155, 0xffff0000, v211
	v_and_b32_e32 v156, 0xffff0000, v215
	v_mul_f32_e32 v152, 0x3b808081, v152
	v_mul_f32_e32 v153, 0x3b808081, v153
	v_mul_f32_e32 v154, 0x3b808081, v154
; __device__ __forceinline__ void unpack8(const u32x4 w, float* f) { f[0] = bflo(w.x); f[1] = bfhi(w.x); f[2] = bflo(w.y); f[3] = bfhi(w.y); f[4] = bflo(w.z); f[5] = bfhi(w.z); f[6] = bflo(w.w); f[7] = bfhi(w.w); }
; __device__ __forceinline__ u32x4 pack8(const float* f) { u32x4 w; w.x = cvt_pk(f[0], f[1]); w.y = cvt_pk(f[2], f[3]); w.z = cvt_pk(f[4], f[5]); w.w = cvt_pk(f[6], f[7]); return w; }
;     __device__ __forceinline__ void operator()(const f32x4 (&acc)[2][2][4][2], const UnitD& u, int wr, int wc, int fr, int fq) const {
;     ...
;                 for (int m = 0; m < 4; ++m) { const int row = row0 + ai * HALF + m * 16;
;                     const unsigned char* gp = (const unsigned char*)(proj + (size_t)row * NP + C_G) + col0; const size_t po = (size_t)row * 2048 + col0;
;                     u32x2 g0[2], g1[2], g2[2]; u32x4 a[2], b[2];
; #pragma unroll
;                     for (int bj = 0; bj < 2; ++bj) { g0[bj] = *(const u32x2*)(gp + bj * HALF); g1[bj] = *(const u32x2*)(gp + 2048 + bj * HALF); g2[bj] = *(const u32x2*)(gp + 4096 + bj * HALF);
;                         a[bj] = *(const u32x4*)(PA + po + bj * HALF); b[bj] = *(const u32x4*)(PB + po + bj * HALF); }
; #pragma unroll
;                     for (int bj = 0; bj < 2; ++bj) { float f0[8], f1[8], f2[8], fa[8], fb[8], o[8];
;                         unpack_u8(g0[bj], f0); unpack_u8(g1[bj], f1); unpack_u8(g2[bj], f2); unpack8(a[bj], fa); unpack8(b[bj], fb);
;                         const f32x4 v0 = acc[ai][bj][m][0], v1 = acc[ai][bj][m][1];
; #pragma unroll
;                         for (int j = 0; j < 4; ++j) { o[j] = f0[j] * fa[j] + f1[j] * fb[j] + f2[j] * v0[j]; o[4 + j] = f0[4 + j] * fa[4 + j] + f1[4 + j] * fb[4 + j] + f2[4 + j] * v1[j]; }
;                         *(u32x4*)(H + po + bj * HALF) = pack8(o); } }
	v_mul_f32_e32 v157, v152, v155
	v_fmac_f32_e32 v157, v153, v156
	v_fma_f32 v57, v154, v57, v157
	v_cvt_f32_ubyte0_e32 v152, v199
	v_cvt_f32_ubyte0_e32 v153, v201
	v_cvt_f32_ubyte0_e32 v154, v203
	v_lshlrev_b32_e32 v155, 16, v212
	v_lshlrev_b32_e32 v156, 16, v216
	v_mul_f32_e32 v152, 0x3b808081, v152
	v_mul_f32_e32 v153, 0x3b808081, v153
	v_mul_f32_e32 v154, 0x3b808081, v154
	v_mul_f32_e32 v157, v152, v155
	v_fmac_f32_e32 v157, v153, v156
	v_fma_f32 v50, v154, v50, v157
	v_cvt_f32_ubyte1_e32 v152, v199
	v_cvt_f32_ubyte1_e32 v153, v201
	v_cvt_f32_ubyte1_e32 v154, v203
	v_and_b32_e32 v155, 0xffff0000, v212
	v_and_b32_e32 v156, 0xffff0000, v216
	v_mul_f32_e32 v152, 0x3b808081, v152
	v_mul_f32_e32 v153, 0x3b808081, v153
	v_mul_f32_e32 v154, 0x3b808081, v154
	v_mul_f32_e32 v157, v152, v155
	v_fmac_f32_e32 v157, v153, v156
	v_fma_f32 v51, v154, v51, v157
	v_cvt_f32_ubyte2_e32 v152, v199
	v_cvt_f32_ubyte2_e32 v153, v201
	v_cvt_f32_ubyte2_e32 v154, v203
	v_lshlrev_b32_e32 v155, 16, v213
	v_lshlrev_b32_e32 v156, 16, v217
	v_mul_f32_e32 v152, 0x3b808081, v152
	v_mul_f32_e32 v153, 0x3b808081, v153
	v_mul_f32_e32 v154, 0x3b808081, v154
	v_mul_f32_e32 v157, v152, v155
	v_fmac_f32_e32 v157, v153, v156
	v_fma_f32 v52, v154, v52, v157
	v_cvt_f32_ubyte3_e32 v152, v199
	v_cvt_f32_ubyte3_e32 v153, v201
	v_cvt_f32_ubyte3_e32 v154, v203
	v_and_b32_e32 v155, 0xffff0000, v213
	v_and_b32_e32 v156, 0xffff0000, v217
	v_mul_f32_e32 v152, 0x3b808081, v152
	v_mul_f32_e32 v153, 0x3b808081, v153
	v_mul_f32_e32 v154, 0x3b808081, v154
	v_mul_f32_e32 v157, v152, v155
	v_fmac_f32_e32 v157, v153, v156
	v_fma_f32 v53, v154, v53, v157
	v_cvt_pk_bf16_f32 v54, v54, v55
	v_cvt_pk_bf16_f32 v55, v56, v57
	v_cvt_pk_bf16_f32 v56, v50, v51
	v_cvt_pk_bf16_f32 v57, v52, v53
	global_store_dwordx4 v149, v[54:57], s[62:63]
	s_waitcnt lgkmcnt(0)
	v_cvt_f32_ubyte0_e32 v152, v204
	v_cvt_f32_ubyte0_e32 v153, v206
	v_cvt_f32_ubyte0_e32 v154, v208
	v_lshlrev_b32_e32 v155, 16, v218
	v_lshlrev_b32_e32 v156, 16, v222
	v_mul_f32_e32 v152, 0x3b808081, v152
	v_mul_f32_e32 v153, 0x3b808081, v153
	v_mul_f32_e32 v154, 0x3b808081, v154
	v_mul_f32_e32 v157, v152, v155
	v_fmac_f32_e32 v157, v153, v156
	v_fma_f32 v30, v154, v30, v157
	v_cvt_f32_ubyte1_e32 v152, v204
	v_cvt_f32_ubyte1_e32 v153, v206
	v_cvt_f32_ubyte1_e32 v154, v208
	v_and_b32_e32 v155, 0xffff0000, v218
	v_and_b32_e32 v156, 0xffff0000, v222
	v_mul_f32_e32 v152, 0x3b808081, v152
	v_mul_f32_e32 v153, 0x3b808081, v153
	v_mul_f32_e32 v154, 0x3b808081, v154
	v_mul_f32_e32 v157, v152, v155
	v_fmac_f32_e32 v157, v153, v156
	v_fma_f32 v31, v154, v31, v157
	v_cvt_f32_ubyte2_e32 v152, v204
	v_cvt_f32_ubyte2_e32 v153, v206
	v_cvt_f32_ubyte2_e32 v154, v208
	v_lshlrev_b32_e32 v155, 16, v219
	v_lshlrev_b32_e32 v156, 16, v223
	v_mul_f32_e32 v152, 0x3b808081, v152
	v_mul_f32_e32 v153, 0x3b808081, v153
	v_mul_f32_e32 v154, 0x3b808081, v154
	v_mul_f32_e32 v157, v152, v155
	v_fmac_f32_e32 v157, v153, v156
	v_fma_f32 v32, v154, v32, v157
	v_cvt_f32_ubyte3_e32 v152, v204
	v_cvt_f32_ubyte3_e32 v153, v206
	v_cvt_f32_ubyte3_e32 v154, v208
	v_and_b32_e32 v155, 0xffff0000, v219
	v_and_b32_e32 v156, 0xffff0000, v223
	v_mul_f32_e32 v152, 0x3b808081, v152
	v_mul_f32_e32 v153, 0x3b808081, v153
	v_mul_f32_e32 v154, 0x3b808081, v154
	v_mul_f32_e32 v157, v152, v155
	v_fmac_f32_e32 v157, v153, v156
	v_fma_f32 v33, v154, v33, v157
	v_cvt_f32_ubyte0_e32 v152, v205
	v_cvt_f32_ubyte0_e32 v153, v207
	v_cvt_f32_ubyte0_e32 v154, v209
	v_lshlrev_b32_e32 v155, 16, v220
	v_lshlrev_b32_e32 v156, 16, v224
	v_mul_f32_e32 v152, 0x3b808081, v152
	v_mul_f32_e32 v153, 0x3b808081, v153
	v_mul_f32_e32 v154, 0x3b808081, v154
	v_mul_f32_e32 v157, v152, v155
	v_fmac_f32_e32 v157, v153, v156
	v_fma_f32 v26, v154, v26, v157
	v_cvt_f32_ubyte1_e32 v152, v205
	v_cvt_f32_ubyte1_e32 v153, v207
	v_cvt_f32_ubyte1_e32 v154, v209
	v_and_b32_e32 v155, 0xffff0000, v220
	v_and_b32_e32 v156, 0xffff0000, v224
	v_mul_f32_e32 v152, 0x3b808081, v152
	v_mul_f32_e32 v153, 0x3b808081, v153
	v_mul_f32_e32 v154, 0x3b808081, v154
	v_mul_f32_e32 v157, v152, v155
	v_fmac_f32_e32 v157, v153, v156
	v_fma_f32 v27, v154, v27, v157
	v_cvt_f32_ubyte2_e32 v152, v205
	v_cvt_f32_ubyte2_e32 v153, v207
	v_cvt_f32_ubyte2_e32 v154, v209
	v_lshlrev_b32_e32 v155, 16, v221
	v_lshlrev_b32_e32 v156, 16, v225
	v_mul_f32_e32 v152, 0x3b808081, v152
	v_mul_f32_e32 v153, 0x3b808081, v153
	v_mul_f32_e32 v154, 0x3b808081, v154
	v_mul_f32_e32 v157, v152, v155
	v_fmac_f32_e32 v157, v153, v156
	v_fma_f32 v28, v154, v28, v157
	v_cvt_f32_ubyte3_e32 v152, v205
	v_cvt_f32_ubyte3_e32 v153, v207
	v_cvt_f32_ubyte3_e32 v154, v209
	v_and_b32_e32 v155, 0xffff0000, v221
	v_and_b32_e32 v156, 0xffff0000, v225
	v_mul_f32_e32 v152, 0x3b808081, v152
	v_mul_f32_e32 v153, 0x3b808081, v153
	v_mul_f32_e32 v154, 0x3b808081, v154
	v_mul_f32_e32 v157, v152, v155
	v_fmac_f32_e32 v157, v153, v156
	v_fma_f32 v29, v154, v29, v157
	v_cvt_pk_bf16_f32 v30, v30, v31
	v_cvt_pk_bf16_f32 v31, v32, v33
	v_cvt_pk_bf16_f32 v32, v26, v27
	v_cvt_pk_bf16_f32 v33, v28, v29
	global_store_dwordx4 v149, v[30:33], s[62:63] offset:256
	v_add_u32_e32 v147, 0xb0000, v145
	v_add_u32_e32 v148, 0x596000, v146
	global_load_dwordx2 v[198:199], v148, s[20:21] offset:-2048
	global_load_dwordx2 v[200:201], v148, s[20:21]
	global_load_dwordx2 v[202:203], v148, s[20:21] offset:2048
	global_load_dwordx2 v[204:205], v148, s[20:21] offset:-1920
	global_load_dwordx2 v[206:207], v148, s[20:21] offset:128
	global_load_dwordx2 v[208:209], v148, s[20:21] offset:2176
	global_load_dwordx4 v[210:213], v147, s[58:59]
	global_load_dwordx4 v[214:217], v147, s[60:61]
	global_load_dwordx4 v[218:221], v147, s[58:59] offset:256
	global_load_dwordx4 v[222:225], v147, s[60:61] offset:256
	ds_write_b128 v251, v[38:41]
	ds_read_b128 v[38:41], v252
	ds_write_b128 v251, v[34:37]
	ds_read_b128 v[34:37], v252
	ds_write_b128 v251, v[14:17]
	ds_read_b128 v[14:17], v252
	ds_write_b128 v251, v[10:13]
	ds_read_b128 v[10:13], v252
	v_add_u32_e32 v149, 0xa0000, v145
	s_waitcnt vmcnt(12)
; __device__ __forceinline__ void unpack8(const u32x4 w, float* f) { f[0] = bflo(w.x); f[1] = bfhi(w.x); f[2] = bflo(w.y); f[3] = bfhi(w.y); f[4] = bflo(w.z); f[5] = bfhi(w.z); f[6] = bflo(w.w); f[7] = bfhi(w.w); }
; __device__ __forceinline__ u32x4 pack8(const float* f) { u32x4 w; w.x = cvt_pk(f[0], f[1]); w.y = cvt_pk(f[2], f[3]); w.z = cvt_pk(f[4], f[5]); w.w = cvt_pk(f[6], f[7]); return w; }
;     __device__ __forceinline__ void operator()(const f32x4 (&acc)[2][2][4][2], const UnitD& u, int wr, int wc, int fr, int fq) const {
;     ...
;                 for (int m = 0; m < 4; ++m) { const int row = row0 + ai * HALF + m * 16;
;                     const unsigned char* gp = (const unsigned char*)(proj + (size_t)row * NP + C_G) + col0; const size_t po = (size_t)row * 2048 + col0;
;                     u32x2 g0[2], g1[2], g2[2]; u32x4 a[2], b[2];
; #pragma unroll
;                     for (int bj = 0; bj < 2; ++bj) { g0[bj] = *(const u32x2*)(gp + bj * HALF); g1[bj] = *(const u32x2*)(gp + 2048 + bj * HALF); g2[bj] = *(const u32x2*)(gp + 4096 + bj * HALF);
;                         a[bj] = *(const u32x4*)(PA + po + bj * HALF); b[bj] = *(const u32x4*)(PB + po + bj * HALF); }
; #pragma unroll
;                     for (int bj = 0; bj < 2; ++bj) { float f0[8], f1[8], f2[8], fa[8], fb[8], o[8];
;                         unpack_u8(g0[bj], f0); unpack_u8(g1[bj], f1); unpack_u8(g2[bj], f2); unpack8(a[bj], fa); unpack8(b[bj], fb);
;                         const f32x4 v0 = acc[ai][bj][m][0], v1 = acc[ai][bj][m][1];
; #pragma unroll
;                         for (int j = 0; j < 4; ++j) { o[j] = f0[j] * fa[j] + f1[j] * fb[j] + f2[j] * v0[j]; o[4 + j] = f0[4 + j] * fa[4 + j] + f1[4 + j] * fb[4 + j] + f2[4 + j] * v1[j]; }
;                         *(u32x4*)(H + po + bj * HALF) = pack8(o); } }
	s_waitcnt lgkmcnt(4)
	v_cvt_f32_ubyte0_e32 v152, v130
	v_cvt_f32_ubyte0_e32 v153, v132
	v_cvt_f32_ubyte0_e32 v154, v134
	v_lshlrev_b32_e32 v155, 16, v164
	v_lshlrev_b32_e32 v156, 16, v168
	v_mul_f32_e32 v152, 0x3b808081, v152
	v_mul_f32_e32 v153, 0x3b808081, v153
	v_mul_f32_e32 v154, 0x3b808081, v154
	v_mul_f32_e32 v157, v152, v155
	v_fmac_f32_e32 v157, v153, v156
	v_fma_f32 v38, v154, v38, v157
	v_cvt_f32_ubyte1_e32 v152, v130
	v_cvt_f32_ubyte1_e32 v153, v132
	v_cvt_f32_ubyte1_e32 v154, v134
	v_and_b32_e32 v155, 0xffff0000, v164
	v_and_b32_e32 v156, 0xffff0000, v168
	v_mul_f32_e32 v152, 0x3b808081, v152
	v_mul_f32_e32 v153, 0x3b808081, v153
	v_mul_f32_e32 v154, 0x3b808081, v154
	v_mul_f32_e32 v157, v152, v155
	v_fmac_f32_e32 v157, v153, v156
	v_fma_f32 v39, v154, v39, v157
	v_cvt_f32_ubyte2_e32 v152, v130
	v_cvt_f32_ubyte2_e32 v153, v132
	v_cvt_f32_ubyte2_e32 v154, v134
	v_lshlrev_b32_e32 v155, 16, v165
	v_lshlrev_b32_e32 v156, 16, v169
	v_mul_f32_e32 v152, 0x3b808081, v152
	v_mul_f32_e32 v153, 0x3b808081, v153
	v_mul_f32_e32 v154, 0x3b808081, v154
	v_mul_f32_e32 v157, v152, v155
	v_fmac_f32_e32 v157, v153, v156
	v_fma_f32 v40, v154, v40, v157
	v_cvt_f32_ubyte3_e32 v152, v130
	v_cvt_f32_ubyte3_e32 v153, v132
	v_cvt_f32_ubyte3_e32 v154, v134
	v_and_b32_e32 v155, 0xffff0000, v165
	v_and_b32_e32 v156, 0xffff0000, v169
	v_mul_f32_e32 v152, 0x3b808081, v152
	v_mul_f32_e32 v153, 0x3b808081, v153
	v_mul_f32_e32 v154, 0x3b808081, v154
	v_mul_f32_e32 v157, v152, v155
	v_fmac_f32_e32 v157, v153, v156
	v_fma_f32 v41, v154, v41, v157
	v_cvt_f32_ubyte0_e32 v152, v131
	v_cvt_f32_ubyte0_e32 v153, v133
	v_cvt_f32_ubyte0_e32 v154, v135
	v_lshlrev_b32_e32 v155, 16, v166
	v_lshlrev_b32_e32 v156, 16, v170
	v_mul_f32_e32 v152, 0x3b808081, v152
	v_mul_f32_e32 v153, 0x3b808081, v153
	v_mul_f32_e32 v154, 0x3b808081, v154
	v_mul_f32_e32 v157, v152, v155
	v_fmac_f32_e32 v157, v153, v156
	v_fma_f32 v34, v154, v34, v157
	v_cvt_f32_ubyte1_e32 v152, v131
	v_cvt_f32_ubyte1_e32 v153, v133
	v_cvt_f32_ubyte1_e32 v154, v135
	v_and_b32_e32 v155, 0xffff0000, v166
	v_and_b32_e32 v156, 0xffff0000, v170
	v_mul_f32_e32 v152, 0x3b808081, v152
	v_mul_f32_e32 v153, 0x3b808081, v153
	v_mul_f32_e32 v154, 0x3b808081, v154
	v_mul_f32_e32 v157, v152, v155
	v_fmac_f32_e32 v157, v153, v156
	v_fma_f32 v35, v154, v35, v157
	v_cvt_f32_ubyte2_e32 v152, v131
	v_cvt_f32_ubyte2_e32 v153, v133
	v_cvt_f32_ubyte2_e32 v154, v135
	v_lshlrev_b32_e32 v155, 16, v167
	v_lshlrev_b32_e32 v156, 16, v171
	v_mul_f32_e32 v152, 0x3b808081, v152
	v_mul_f32_e32 v153, 0x3b808081, v153
	v_mul_f32_e32 v154, 0x3b808081, v154
	v_mul_f32_e32 v157, v152, v155
	v_fmac_f32_e32 v157, v153, v156
	v_fma_f32 v36, v154, v36, v157
	v_cvt_f32_ubyte3_e32 v152, v131
	v_cvt_f32_ubyte3_e32 v153, v133
	v_cvt_f32_ubyte3_e32 v154, v135
	v_and_b32_e32 v155, 0xffff0000, v167
	v_and_b32_e32 v156, 0xffff0000, v171
	v_mul_f32_e32 v152, 0x3b808081, v152
	v_mul_f32_e32 v153, 0x3b808081, v153
	v_mul_f32_e32 v154, 0x3b808081, v154
	v_mul_f32_e32 v157, v152, v155
	v_fmac_f32_e32 v157, v153, v156
	v_fma_f32 v37, v154, v37, v157
	v_cvt_pk_bf16_f32 v38, v38, v39
	v_cvt_pk_bf16_f32 v39, v40, v41
	v_cvt_pk_bf16_f32 v40, v34, v35
	v_cvt_pk_bf16_f32 v41, v36, v37
	global_store_dwordx4 v149, v[38:41], s[62:63]
	s_waitcnt lgkmcnt(0)
	v_cvt_f32_ubyte0_e32 v152, v136
	v_cvt_f32_ubyte0_e32 v153, v160
	v_cvt_f32_ubyte0_e32 v154, v162
	v_lshlrev_b32_e32 v155, 16, v172
	v_lshlrev_b32_e32 v156, 16, v176
	v_mul_f32_e32 v152, 0x3b808081, v152
	v_mul_f32_e32 v153, 0x3b808081, v153
	v_mul_f32_e32 v154, 0x3b808081, v154
	v_mul_f32_e32 v157, v152, v155
	v_fmac_f32_e32 v157, v153, v156
	v_fma_f32 v14, v154, v14, v157
	v_cvt_f32_ubyte1_e32 v152, v136
	v_cvt_f32_ubyte1_e32 v153, v160
	v_cvt_f32_ubyte1_e32 v154, v162
	v_and_b32_e32 v155, 0xffff0000, v172
	v_and_b32_e32 v156, 0xffff0000, v176
	v_mul_f32_e32 v152, 0x3b808081, v152
	v_mul_f32_e32 v153, 0x3b808081, v153
	v_mul_f32_e32 v154, 0x3b808081, v154
	v_mul_f32_e32 v157, v152, v155
	v_fmac_f32_e32 v157, v153, v156
	v_fma_f32 v15, v154, v15, v157
	v_cvt_f32_ubyte2_e32 v152, v136
	v_cvt_f32_ubyte2_e32 v153, v160
	v_cvt_f32_ubyte2_e32 v154, v162
	v_lshlrev_b32_e32 v155, 16, v173
	v_lshlrev_b32_e32 v156, 16, v177
	v_mul_f32_e32 v152, 0x3b808081, v152
	v_mul_f32_e32 v153, 0x3b808081, v153
	v_mul_f32_e32 v154, 0x3b808081, v154
	v_mul_f32_e32 v157, v152, v155
	v_fmac_f32_e32 v157, v153, v156
	v_fma_f32 v16, v154, v16, v157
	v_cvt_f32_ubyte3_e32 v152, v136
	v_cvt_f32_ubyte3_e32 v153, v160
	v_cvt_f32_ubyte3_e32 v154, v162
	v_and_b32_e32 v155, 0xffff0000, v173
	v_and_b32_e32 v156, 0xffff0000, v177
	v_mul_f32_e32 v152, 0x3b808081, v152
	v_mul_f32_e32 v153, 0x3b808081, v153
	v_mul_f32_e32 v154, 0x3b808081, v154
	v_mul_f32_e32 v157, v152, v155
	v_fmac_f32_e32 v157, v153, v156
	v_fma_f32 v17, v154, v17, v157
	v_cvt_f32_ubyte0_e32 v152, v137
	v_cvt_f32_ubyte0_e32 v153, v161
	v_cvt_f32_ubyte0_e32 v154, v163
	v_lshlrev_b32_e32 v155, 16, v174
	v_lshlrev_b32_e32 v156, 16, v178
	v_mul_f32_e32 v152, 0x3b808081, v152
	v_mul_f32_e32 v153, 0x3b808081, v153
	v_mul_f32_e32 v154, 0x3b808081, v154
	v_mul_f32_e32 v157, v152, v155
	v_fmac_f32_e32 v157, v153, v156
	v_fma_f32 v10, v154, v10, v157
	v_cvt_f32_ubyte1_e32 v152, v137
	v_cvt_f32_ubyte1_e32 v153, v161
	v_cvt_f32_ubyte1_e32 v154, v163
	v_and_b32_e32 v155, 0xffff0000, v174
	v_and_b32_e32 v156, 0xffff0000, v178
	v_mul_f32_e32 v152, 0x3b808081, v152
	v_mul_f32_e32 v153, 0x3b808081, v153
	v_mul_f32_e32 v154, 0x3b808081, v154
	v_mul_f32_e32 v157, v152, v155
	v_fmac_f32_e32 v157, v153, v156
	v_fma_f32 v11, v154, v11, v157
	v_cvt_f32_ubyte2_e32 v152, v137
	v_cvt_f32_ubyte2_e32 v153, v161
	v_cvt_f32_ubyte2_e32 v154, v163
	v_lshlrev_b32_e32 v155, 16, v175
	v_lshlrev_b32_e32 v156, 16, v179
	v_mul_f32_e32 v152, 0x3b808081, v152
	v_mul_f32_e32 v153, 0x3b808081, v153
	v_mul_f32_e32 v154, 0x3b808081, v154
	v_mul_f32_e32 v157, v152, v155
	v_fmac_f32_e32 v157, v153, v156
	v_fma_f32 v12, v154, v12, v157
	v_cvt_f32_ubyte3_e32 v152, v137
	v_cvt_f32_ubyte3_e32 v153, v161
	v_cvt_f32_ubyte3_e32 v154, v163
	v_and_b32_e32 v155, 0xffff0000, v175
	v_and_b32_e32 v156, 0xffff0000, v179
	v_mul_f32_e32 v152, 0x3b808081, v152
	v_mul_f32_e32 v153, 0x3b808081, v153
	v_mul_f32_e32 v154, 0x3b808081, v154
	v_mul_f32_e32 v157, v152, v155
	v_fmac_f32_e32 v157, v153, v156
	v_fma_f32 v13, v154, v13, v157
	v_cvt_pk_bf16_f32 v14, v14, v15
	v_cvt_pk_bf16_f32 v15, v16, v17
	v_cvt_pk_bf16_f32 v16, v10, v11
	v_cvt_pk_bf16_f32 v17, v12, v13
	global_store_dwordx4 v149, v[14:17], s[62:63] offset:256
	ds_write_b128 v251, v[22:25]
	ds_read_b128 v[22:25], v252
	ds_write_b128 v251, v[18:21]
	ds_read_b128 v[18:21], v252
	ds_write_b128 v251, v[6:9]
	ds_read_b128 v[6:9], v252
	ds_write_b128 v251, v[2:5]
	ds_read_b128 v[2:5], v252
	v_add_u32_e32 v149, 0xb0000, v145
	s_waitcnt vmcnt(2)
; __device__ __forceinline__ void unpack8(const u32x4 w, float* f) { f[0] = bflo(w.x); f[1] = bfhi(w.x); f[2] = bflo(w.y); f[3] = bfhi(w.y); f[4] = bflo(w.z); f[5] = bfhi(w.z); f[6] = bflo(w.w); f[7] = bfhi(w.w); }
; __device__ __forceinline__ u32x4 pack8(const float* f) { u32x4 w; w.x = cvt_pk(f[0], f[1]); w.y = cvt_pk(f[2], f[3]); w.z = cvt_pk(f[4], f[5]); w.w = cvt_pk(f[6], f[7]); return w; }
;     __device__ __forceinline__ void operator()(const f32x4 (&acc)[2][2][4][2], const UnitD& u, int wr, int wc, int fr, int fq) const {
;     ...
;                 for (int m = 0; m < 4; ++m) { const int row = row0 + ai * HALF + m * 16;
;                     const unsigned char* gp = (const unsigned char*)(proj + (size_t)row * NP + C_G) + col0; const size_t po = (size_t)row * 2048 + col0;
;                     u32x2 g0[2], g1[2], g2[2]; u32x4 a[2], b[2];
; #pragma unroll
;                     for (int bj = 0; bj < 2; ++bj) { g0[bj] = *(const u32x2*)(gp + bj * HALF); g1[bj] = *(const u32x2*)(gp + 2048 + bj * HALF); g2[bj] = *(const u32x2*)(gp + 4096 + bj * HALF);
;                         a[bj] = *(const u32x4*)(PA + po + bj * HALF); b[bj] = *(const u32x4*)(PB + po + bj * HALF); }
; #pragma unroll
;                     for (int bj = 0; bj < 2; ++bj) { float f0[8], f1[8], f2[8], fa[8], fb[8], o[8];
;                         unpack_u8(g0[bj], f0); unpack_u8(g1[bj], f1); unpack_u8(g2[bj], f2); unpack8(a[bj], fa); unpack8(b[bj], fb);
;                         const f32x4 v0 = acc[ai][bj][m][0], v1 = acc[ai][bj][m][1];
; #pragma unroll
;                         for (int j = 0; j < 4; ++j) { o[j] = f0[j] * fa[j] + f1[j] * fb[j] + f2[j] * v0[j]; o[4 + j] = f0[4 + j] * fa[4 + j] + f1[4 + j] * fb[4 + j] + f2[4 + j] * v1[j]; }
;                         *(u32x4*)(H + po + bj * HALF) = pack8(o); } }
	s_waitcnt lgkmcnt(4)
	v_cvt_f32_ubyte0_e32 v152, v198
	v_cvt_f32_ubyte0_e32 v153, v200
	v_cvt_f32_ubyte0_e32 v154, v202
	v_lshlrev_b32_e32 v155, 16, v210
	v_lshlrev_b32_e32 v156, 16, v214
	v_mul_f32_e32 v152, 0x3b808081, v152
	v_mul_f32_e32 v153, 0x3b808081, v153
	v_mul_f32_e32 v154, 0x3b808081, v154
	v_mul_f32_e32 v157, v152, v155
	v_fmac_f32_e32 v157, v153, v156
	v_fma_f32 v22, v154, v22, v157
	v_cvt_f32_ubyte1_e32 v152, v198
	v_cvt_f32_ubyte1_e32 v153, v200
	v_cvt_f32_ubyte1_e32 v154, v202
	v_and_b32_e32 v155, 0xffff0000, v210
	v_and_b32_e32 v156, 0xffff0000, v214
	v_mul_f32_e32 v152, 0x3b808081, v152
	v_mul_f32_e32 v153, 0x3b808081, v153
	v_mul_f32_e32 v154, 0x3b808081, v154
	v_mul_f32_e32 v157, v152, v155
	v_fmac_f32_e32 v157, v153, v156
	v_fma_f32 v23, v154, v23, v157
	v_cvt_f32_ubyte2_e32 v152, v198
	v_cvt_f32_ubyte2_e32 v153, v200
	v_cvt_f32_ubyte2_e32 v154, v202
	v_lshlrev_b32_e32 v155, 16, v211
	v_lshlrev_b32_e32 v156, 16, v215
	v_mul_f32_e32 v152, 0x3b808081, v152
	v_mul_f32_e32 v153, 0x3b808081, v153
	v_mul_f32_e32 v154, 0x3b808081, v154
	v_mul_f32_e32 v157, v152, v155
	v_fmac_f32_e32 v157, v153, v156
	v_fma_f32 v24, v154, v24, v157
	v_cvt_f32_ubyte3_e32 v152, v198
	v_cvt_f32_ubyte3_e32 v153, v200
	v_cvt_f32_ubyte3_e32 v154, v202
	v_and_b32_e32 v155, 0xffff0000, v211
	v_and_b32_e32 v156, 0xffff0000, v215
	v_mul_f32_e32 v152, 0x3b808081, v152
	v_mul_f32_e32 v153, 0x3b808081, v153
	v_mul_f32_e32 v154, 0x3b808081, v154
	v_mul_f32_e32 v157, v152, v155
	v_fmac_f32_e32 v157, v153, v156
	v_fma_f32 v25, v154, v25, v157
	v_cvt_f32_ubyte0_e32 v152, v199
	v_cvt_f32_ubyte0_e32 v153, v201
	v_cvt_f32_ubyte0_e32 v154, v203
	v_lshlrev_b32_e32 v155, 16, v212
	v_lshlrev_b32_e32 v156, 16, v216
	v_mul_f32_e32 v152, 0x3b808081, v152
	v_mul_f32_e32 v153, 0x3b808081, v153
	v_mul_f32_e32 v154, 0x3b808081, v154
	v_mul_f32_e32 v157, v152, v155
	v_fmac_f32_e32 v157, v153, v156
	v_fma_f32 v18, v154, v18, v157
	v_cvt_f32_ubyte1_e32 v152, v199
	v_cvt_f32_ubyte1_e32 v153, v201
	v_cvt_f32_ubyte1_e32 v154, v203
	v_and_b32_e32 v155, 0xffff0000, v212
	v_and_b32_e32 v156, 0xffff0000, v216
	v_mul_f32_e32 v152, 0x3b808081, v152
	v_mul_f32_e32 v153, 0x3b808081, v153
	v_mul_f32_e32 v154, 0x3b808081, v154
	v_mul_f32_e32 v157, v152, v155
	v_fmac_f32_e32 v157, v153, v156
	v_fma_f32 v19, v154, v19, v157
	v_cvt_f32_ubyte2_e32 v152, v199
	v_cvt_f32_ubyte2_e32 v153, v201
	v_cvt_f32_ubyte2_e32 v154, v203
	v_lshlrev_b32_e32 v155, 16, v213
	v_lshlrev_b32_e32 v156, 16, v217
	v_mul_f32_e32 v152, 0x3b808081, v152
	v_mul_f32_e32 v153, 0x3b808081, v153
	v_mul_f32_e32 v154, 0x3b808081, v154
	v_mul_f32_e32 v157, v152, v155
	v_fmac_f32_e32 v157, v153, v156
	v_fma_f32 v20, v154, v20, v157
	v_cvt_f32_ubyte3_e32 v152, v199
	v_cvt_f32_ubyte3_e32 v153, v201
	v_cvt_f32_ubyte3_e32 v154, v203
	v_and_b32_e32 v155, 0xffff0000, v213
	v_and_b32_e32 v156, 0xffff0000, v217
	v_mul_f32_e32 v152, 0x3b808081, v152
	v_mul_f32_e32 v153, 0x3b808081, v153
	v_mul_f32_e32 v154, 0x3b808081, v154
	v_mul_f32_e32 v157, v152, v155
	v_fmac_f32_e32 v157, v153, v156
	v_fma_f32 v21, v154, v21, v157
	v_cvt_pk_bf16_f32 v22, v22, v23
	v_cvt_pk_bf16_f32 v23, v24, v25
	v_cvt_pk_bf16_f32 v24, v18, v19
	v_cvt_pk_bf16_f32 v25, v20, v21
	global_store_dwordx4 v149, v[22:25], s[62:63]
	s_waitcnt lgkmcnt(0)
	v_cvt_f32_ubyte0_e32 v152, v204
	v_cvt_f32_ubyte0_e32 v153, v206
	v_cvt_f32_ubyte0_e32 v154, v208
	v_lshlrev_b32_e32 v155, 16, v218
	v_lshlrev_b32_e32 v156, 16, v222
	v_mul_f32_e32 v152, 0x3b808081, v152
	v_mul_f32_e32 v153, 0x3b808081, v153
	v_mul_f32_e32 v154, 0x3b808081, v154
	v_mul_f32_e32 v157, v152, v155
	v_fmac_f32_e32 v157, v153, v156
	v_fma_f32 v6, v154, v6, v157
	v_cvt_f32_ubyte1_e32 v152, v204
	v_cvt_f32_ubyte1_e32 v153, v206
	v_cvt_f32_ubyte1_e32 v154, v208
	v_and_b32_e32 v155, 0xffff0000, v218
	v_and_b32_e32 v156, 0xffff0000, v222
	v_mul_f32_e32 v152, 0x3b808081, v152
	v_mul_f32_e32 v153, 0x3b808081, v153
	v_mul_f32_e32 v154, 0x3b808081, v154
	v_mul_f32_e32 v157, v152, v155
	v_fmac_f32_e32 v157, v153, v156
	v_fma_f32 v7, v154, v7, v157
	v_cvt_f32_ubyte2_e32 v152, v204
	v_cvt_f32_ubyte2_e32 v153, v206
	v_cvt_f32_ubyte2_e32 v154, v208
	v_lshlrev_b32_e32 v155, 16, v219
	v_lshlrev_b32_e32 v156, 16, v223
	v_mul_f32_e32 v152, 0x3b808081, v152
	v_mul_f32_e32 v153, 0x3b808081, v153
	v_mul_f32_e32 v154, 0x3b808081, v154
	v_mul_f32_e32 v157, v152, v155
	v_fmac_f32_e32 v157, v153, v156
	v_fma_f32 v8, v154, v8, v157
	v_cvt_f32_ubyte3_e32 v152, v204
	v_cvt_f32_ubyte3_e32 v153, v206
	v_cvt_f32_ubyte3_e32 v154, v208
	v_and_b32_e32 v155, 0xffff0000, v219
	v_and_b32_e32 v156, 0xffff0000, v223
	v_mul_f32_e32 v152, 0x3b808081, v152
	v_mul_f32_e32 v153, 0x3b808081, v153
	v_mul_f32_e32 v154, 0x3b808081, v154
	v_mul_f32_e32 v157, v152, v155
	v_fmac_f32_e32 v157, v153, v156
	v_fma_f32 v9, v154, v9, v157
	v_cvt_f32_ubyte0_e32 v152, v205
	v_cvt_f32_ubyte0_e32 v153, v207
	v_cvt_f32_ubyte0_e32 v154, v209
	v_lshlrev_b32_e32 v155, 16, v220
	v_lshlrev_b32_e32 v156, 16, v224
	v_mul_f32_e32 v152, 0x3b808081, v152
	v_mul_f32_e32 v153, 0x3b808081, v153
	v_mul_f32_e32 v154, 0x3b808081, v154
	v_mul_f32_e32 v157, v152, v155
	v_fmac_f32_e32 v157, v153, v156
	v_fma_f32 v2, v154, v2, v157
	v_cvt_f32_ubyte1_e32 v152, v205
	v_cvt_f32_ubyte1_e32 v153, v207
	v_cvt_f32_ubyte1_e32 v154, v209
	v_and_b32_e32 v155, 0xffff0000, v220
	v_and_b32_e32 v156, 0xffff0000, v224
	v_mul_f32_e32 v152, 0x3b808081, v152
	v_mul_f32_e32 v153, 0x3b808081, v153
	v_mul_f32_e32 v154, 0x3b808081, v154
	v_mul_f32_e32 v157, v152, v155
	v_fmac_f32_e32 v157, v153, v156
	v_fma_f32 v3, v154, v3, v157
	v_cvt_f32_ubyte2_e32 v152, v205
	v_cvt_f32_ubyte2_e32 v153, v207
	v_cvt_f32_ubyte2_e32 v154, v209
	v_lshlrev_b32_e32 v155, 16, v221
	v_lshlrev_b32_e32 v156, 16, v225
	v_mul_f32_e32 v152, 0x3b808081, v152
	v_mul_f32_e32 v153, 0x3b808081, v153
	v_mul_f32_e32 v154, 0x3b808081, v154
	v_mul_f32_e32 v157, v152, v155
	v_fmac_f32_e32 v157, v153, v156
	v_fma_f32 v4, v154, v4, v157
	v_cvt_f32_ubyte3_e32 v152, v205
	v_cvt_f32_ubyte3_e32 v153, v207
	v_cvt_f32_ubyte3_e32 v154, v209
	v_and_b32_e32 v155, 0xffff0000, v221
	v_and_b32_e32 v156, 0xffff0000, v225
	v_mul_f32_e32 v152, 0x3b808081, v152
	v_mul_f32_e32 v153, 0x3b808081, v153
	v_mul_f32_e32 v154, 0x3b808081, v154
	v_mul_f32_e32 v157, v152, v155
	v_fmac_f32_e32 v157, v153, v156
	v_fma_f32 v5, v154, v5, v157
	v_cvt_pk_bf16_f32 v6, v6, v7
	v_cvt_pk_bf16_f32 v7, v8, v9
	v_cvt_pk_bf16_f32 v8, v2, v3
	v_cvt_pk_bf16_f32 v9, v4, v5
	global_store_dwordx4 v149, v[6:9], s[62:63] offset:256
	s_branch .Lg3_done

; template <bool PERM, class SchedT, class Epi>
; __device__ __forceinline__ void gemm_phase(LAS unsigned char* lds, const SchedT& S, const Epi& E) {
;     ...
;         E(acc, cur, wr, wc, fr, fq);
;         if (!has_next) break;
.Lg3_done:
	s_cmpk_gt_u32 s4, 0xff
	s_cbranch_scc0 .Lus_g3b
	s_barrier

; #define G_STA(bufoff, gbase, ld) G_STAGE(bufoff, gbase, RA0, RA1, ld)
; #define G_STB(bufoff, gbase, ld) G_STAGE(bufoff, gbase, RB0, RB1, ld)
; #define G_LDA(dst, b, h) do { _Pragma("unroll") for (int m = 0; m < 4; ++m) _Pragma("unroll") for (int k = 0; k < 2; ++k) dst[m][k] = *(const LAS bf16x8*)(lds + G_SA(b, h) + aoff + m * 2048 + k * 1024); } while (0)
; #define G_LDB(dst, b, h) do { _Pragma("unroll") for (int n = 0; n < 2; ++n) _Pragma("unroll") for (int k = 0; k < 2; ++k) dst[n][k] = *(const LAS bf16x8*)(lds + G_SB(b, h) + boff + n * 2048 + k * 1024); } while (0)
; #define G_WAIT_V(n) asm volatile("s_waitcnt vmcnt(" #n ")" ::: "memory")
; #define G_BAR __builtin_amdgcn_s_barrier()
; template <bool PERM, class SchedT, class Epi>
; __device__ __forceinline__ void gemm_phase(LAS unsigned char* lds, const SchedT& S, const Epi& E) {
;     ...
;         for (int t = 0; t < nt; t += 2) {
;             const bool last = (t == nt - 2);
;             const char* a1 = cA + (size_t)(t + 1) * kstep;
;             const char* a2 = last ? nA : cA + (size_t)(t + 2) * kstep; const char* b2 = last ? nB : cB + (size_t)(t + 2) * kstep;
;             const char* a3 = a2 + kstep; const char* b3 = b2 + kstep;
;             const int wlda = last ? nlda : lda, wK = last ? nK : K;
;             G_LDB(B0, 0, 0); G_SCHED; G_LDA(At, 0, 0); G_STA(G_SA(1, 1), a1 + HSTEP(lda), lda);
;             G_WAIT_L(8); G_BAR; G_WAIT_L(0); G_MMA(0, 0, At, B0); G_BAR; G_SCHED;
;             G_LDB(B1, 0, 1); G_STB(G_SB(0, 0), b2, wK);
;             G_BAR; G_WAIT_L(0); G_MMA(0, 1, At, B1); G_BAR;
;             G_LDA(At, 0, 1); G_STA(G_SA(0, 0), a2, wlda);
;             G_BAR; G_WAIT_L(0); G_MMA(1, 0, At, B0); G_BAR; G_SCHED;
;             G_STB(G_SB(0, 1), b2 + HSTEP(wK), wK);
;             G_WAIT_V(6); G_BAR; G_MMA(1, 1, At, B1); G_BAR;
;             G_LDB(B0, 1, 0); G_SCHED; G_LDA(At, 1, 0); G_STA(G_SA(0, 1), a2 + HSTEP(wlda), wlda);
;             G_WAIT_L(8); G_BAR; G_WAIT_L(0); G_MMA(0, 0, At, B0); G_BAR; G_SCHED;
;             G_LDB(B1, 1, 1); G_STB(G_SB(1, 0), b3, wK);
;             G_BAR; G_WAIT_L(0); G_MMA(0, 1, At, B1); G_BAR;
;             G_LDA(At, 1, 1); G_STA(G_SA(1, 0), a3, wlda);
;             G_BAR; G_WAIT_L(0); G_MMA(1, 0, At, B0); G_BAR; G_SCHED;
;             G_STB(G_SB(1, 1), b3 + HSTEP(wK), wK);
;             G_WAIT_V(6); G_BAR; G_MMA(1, 1, At, B1); G_BAR;
;         }
.LBB0_165:
	s_add_u32 s26, s12, s22
	s_addc_u32 s27, s13, s23
	s_add_u32 s28, s26, 0x100
	s_addc_u32 s29, s27, 0
	s_add_u32 s51, s7, s22
	s_addc_u32 s52, s49, s23
	s_cmpk_eq_i32 s22, 0x300
	s_cselect_b64 s[30:31], -1, 0
	s_and_b64 s[26:27], s[30:31], exec
	s_cselect_b32 s29, s45, s29
	s_cselect_b32 s28, s46, s28
	s_cselect_b32 s27, s47, s52
	s_cselect_b32 s26, s48, s51
	s_and_b64 s[30:31], s[24:25], s[30:31]
	s_and_b64 s[30:31], s[30:31], exec
	s_cselect_b32 s30, s44, s6
	s_add_i32 s31, 0, 0x10000
	v_add_u32_e32 v160, s31, v139
	ds_read_b128 v[146:149], v160
	ds_read_b128 v[150:153], v160 offset:1024
	ds_read_b128 v[154:157], v160 offset:2048
	ds_read_b128 v[160:163], v160 offset:3072
	v_lshl_add_u64 v[208:209], v[140:141], 0, s[22:23]
	s_add_i32 m0, s35, 0xc000
	ds_read_b128 v[164:167], v145
	ds_read_b128 v[168:171], v145 offset:1024
	ds_read_b128 v[172:175], v145 offset:2048
	ds_read_b128 v[176:179], v145 offset:3072
	ds_read_b128 v[192:195], v145 offset:4096
	ds_read_b128 v[196:199], v145 offset:5120
	ds_read_b128 v[200:203], v145 offset:6144
	ds_read_b128 v[204:207], v145 offset:7168
	global_load_lds_dwordx4 v[208:209], off
	v_lshl_add_u64 v[208:209], v[142:143], 0, s[22:23]
	s_add_i32 m0, s35, 0xe000
	s_nop 0
	global_load_lds_dwordx4 v[208:209], off
	s_waitcnt lgkmcnt(8)
	s_barrier
	s_waitcnt lgkmcnt(0)
	s_setprio 1
	s_waitcnt lgkmcnt(0)
	v_mfma_f32_16x16x32_bf16 v[126:129], v[146:149], v[164:167], v[126:129]
	v_mfma_f32_16x16x32_bf16 v[122:125], v[154:157], v[164:167], v[122:125]
	v_mfma_f32_16x16x32_bf16 v[118:121], v[146:149], v[172:175], v[118:121]
	v_mfma_f32_16x16x32_bf16 v[110:113], v[154:157], v[172:175], v[110:113]
	v_mfma_f32_16x16x32_bf16 v[102:105], v[146:149], v[192:195], v[102:105]
	v_mfma_f32_16x16x32_bf16 v[94:97], v[154:157], v[192:195], v[94:97]
	v_mfma_f32_16x16x32_bf16 v[86:89], v[146:149], v[200:203], v[86:89]
	v_mfma_f32_16x16x32_bf16 v[78:81], v[154:157], v[200:203], v[78:81]
	v_mfma_f32_16x16x32_bf16 v[126:129], v[150:153], v[168:171], v[126:129]
	v_mfma_f32_16x16x32_bf16 v[122:125], v[160:163], v[168:171], v[122:125]
	v_mfma_f32_16x16x32_bf16 v[118:121], v[150:153], v[176:179], v[118:121]
	v_mfma_f32_16x16x32_bf16 v[110:113], v[160:163], v[176:179], v[110:113]
	v_mfma_f32_16x16x32_bf16 v[102:105], v[150:153], v[196:199], v[102:105]
	v_mfma_f32_16x16x32_bf16 v[94:97], v[160:163], v[196:199], v[94:97]
	v_mfma_f32_16x16x32_bf16 v[86:89], v[150:153], v[204:207], v[86:89]
	v_mfma_f32_16x16x32_bf16 v[78:81], v[160:163], v[204:207], v[78:81]
	s_setprio 0
	s_barrier
	s_add_i32 s51, 0, 0x14000
	s_add_i32 s31, s31, s34
	v_add_u32_e32 v220, s51, v139
	v_lshl_add_u64 v[224:225], s[26:27], 0, v[0:1]
	s_mov_b32 m0, s31
	ds_read_b128 v[208:211], v220
	ds_read_b128 v[212:215], v220 offset:1024
	ds_read_b128 v[216:219], v220 offset:2048
	ds_read_b128 v[220:223], v220 offset:3072
	global_load_lds_dwordx4 v[224:225], off
	v_lshl_add_u64 v[230:231], s[26:27], 0, v[134:135]
	s_add_i32 m0, s31, 0x2000
	s_nop 0
	global_load_lds_dwordx4 v[230:231], off
	s_barrier
	s_waitcnt lgkmcnt(0)
	s_setprio 1
	s_waitcnt lgkmcnt(0)
	v_mfma_f32_16x16x32_bf16 v[114:117], v[208:211], v[164:167], v[114:117]
	v_mfma_f32_16x16x32_bf16 v[106:109], v[216:219], v[164:167], v[106:109]
	v_mfma_f32_16x16x32_bf16 v[98:101], v[208:211], v[172:175], v[98:101]
	v_mfma_f32_16x16x32_bf16 v[90:93], v[216:219], v[172:175], v[90:93]
	v_mfma_f32_16x16x32_bf16 v[82:85], v[208:211], v[192:195], v[82:85]
	v_mfma_f32_16x16x32_bf16 v[74:77], v[216:219], v[192:195], v[74:77]
	v_mfma_f32_16x16x32_bf16 v[70:73], v[208:211], v[200:203], v[70:73]
	v_mfma_f32_16x16x32_bf16 v[66:69], v[216:219], v[200:203], v[66:69]
	v_mfma_f32_16x16x32_bf16 v[114:117], v[212:215], v[168:171], v[114:117]
	v_mfma_f32_16x16x32_bf16 v[106:109], v[220:223], v[168:171], v[106:109]
	v_mfma_f32_16x16x32_bf16 v[98:101], v[212:215], v[176:179], v[98:101]
	v_mfma_f32_16x16x32_bf16 v[90:93], v[220:223], v[176:179], v[90:93]
	v_mfma_f32_16x16x32_bf16 v[82:85], v[212:215], v[196:199], v[82:85]
	v_mfma_f32_16x16x32_bf16 v[74:77], v[220:223], v[196:199], v[74:77]
	v_mfma_f32_16x16x32_bf16 v[70:73], v[212:215], v[204:207], v[70:73]
	v_mfma_f32_16x16x32_bf16 v[66:69], v[220:223], v[204:207], v[66:69]
	s_setprio 0
	s_mov_b32 m0, s35
	v_mad_u64_u32 v[232:233], s[52:53], s30, v131, v[130:131]
	s_barrier
	ds_read_b128 v[164:167], v145 offset:16384
	ds_read_b128 v[168:171], v145 offset:17408
	ds_read_b128 v[172:175], v145 offset:18432
	ds_read_b128 v[176:179], v145 offset:19456
	ds_read_b128 v[192:195], v145 offset:20480
	ds_read_b128 v[196:199], v145 offset:21504
	ds_read_b128 v[200:203], v145 offset:22528
	ds_read_b128 v[204:207], v145 offset:23552
	global_load_lds_dwordx4 v232, s[28:29]
	v_mad_u64_u32 v[234:235], s[52:53], s30, v133, v[132:133]
	s_mov_b32 m0, s36
	v_mov_b32_e32 v233, v1
	global_load_lds_dwordx4 v234, s[28:29]
	s_barrier
	s_waitcnt lgkmcnt(0)
	v_mov_b32_e32 v235, v1
	v_lshl_add_u64 v[236:237], s[28:29], 0, v[232:233]
	v_lshl_add_u64 v[238:239], s[28:29], 0, v[234:235]
	s_setprio 1
	s_waitcnt lgkmcnt(0)
	v_mfma_f32_16x16x32_bf16 v[62:65], v[146:149], v[164:167], v[62:65]
	v_mfma_f32_16x16x32_bf16 v[58:61], v[154:157], v[164:167], v[58:61]
	v_mfma_f32_16x16x32_bf16 v[54:57], v[146:149], v[172:175], v[54:57]
	v_mfma_f32_16x16x32_bf16 v[46:49], v[154:157], v[172:175], v[46:49]
	v_mfma_f32_16x16x32_bf16 v[38:41], v[146:149], v[192:195], v[38:41]
	v_mfma_f32_16x16x32_bf16 v[30:33], v[154:157], v[192:195], v[30:33]
	v_mfma_f32_16x16x32_bf16 v[22:25], v[146:149], v[200:203], v[22:25]
	v_mfma_f32_16x16x32_bf16 v[14:17], v[154:157], v[200:203], v[14:17]
	v_mfma_f32_16x16x32_bf16 v[62:65], v[150:153], v[168:171], v[62:65]
	v_mfma_f32_16x16x32_bf16 v[58:61], v[160:163], v[168:171], v[58:61]
	v_mfma_f32_16x16x32_bf16 v[54:57], v[150:153], v[176:179], v[54:57]
	v_mfma_f32_16x16x32_bf16 v[46:49], v[160:163], v[176:179], v[46:49]
	v_mfma_f32_16x16x32_bf16 v[38:41], v[150:153], v[196:199], v[38:41]
	v_mfma_f32_16x16x32_bf16 v[30:33], v[160:163], v[196:199], v[30:33]
	v_mfma_f32_16x16x32_bf16 v[22:25], v[150:153], v[204:207], v[22:25]
	v_mfma_f32_16x16x32_bf16 v[14:17], v[160:163], v[204:207], v[14:17]
	s_setprio 0
	s_barrier
; #define G_STA(bufoff, gbase, ld) G_STAGE(bufoff, gbase, RA0, RA1, ld)
; #define G_STB(bufoff, gbase, ld) G_STAGE(bufoff, gbase, RB0, RB1, ld)
; #define G_LDA(dst, b, h) do { _Pragma("unroll") for (int m = 0; m < 4; ++m) _Pragma("unroll") for (int k = 0; k < 2; ++k) dst[m][k] = *(const LAS bf16x8*)(lds + G_SA(b, h) + aoff + m * 2048 + k * 1024); } while (0)
; #define G_LDB(dst, b, h) do { _Pragma("unroll") for (int n = 0; n < 2; ++n) _Pragma("unroll") for (int k = 0; k < 2; ++k) dst[n][k] = *(const LAS bf16x8*)(lds + G_SB(b, h) + boff + n * 2048 + k * 1024); } while (0)
; #define G_MMA(ai, bj, At, Bt) do { __builtin_amdgcn_s_setprio(1); _Pragma("unroll") for (int m = 0; m < 4; ++m) _Pragma("unroll") for (int n = 0; n < 2; ++n) _Pragma("unroll") for (int k = 0; k < 2; ++k) \
;         acc[ai][bj][m][n] = __builtin_amdgcn_mfma_f32_16x16x32_bf16(Bt[n][k], At[m][k], acc[ai][bj][m][n], 0, 0, 0); __builtin_amdgcn_s_setprio(0); } while (0)
; #define G_WAIT_V(n) asm volatile("s_waitcnt vmcnt(" #n ")" ::: "memory")
; #define G_WAIT_L(n) asm volatile("s_waitcnt lgkmcnt(" #n ")" ::: "memory")
; template <bool PERM, class SchedT, class Epi>
; __device__ __forceinline__ void gemm_phase(LAS unsigned char* lds, const SchedT& S, const Epi& E) {
;     ...
;             G_LDB(B0, 0, 0); G_SCHED; G_LDA(At, 0, 0); G_STA(G_SA(1, 1), a1 + HSTEP(lda), lda);
;             G_WAIT_L(8); G_BAR; G_WAIT_L(0); G_MMA(0, 0, At, B0); G_BAR; G_SCHED;
;             G_LDB(B1, 0, 1); G_STB(G_SB(0, 0), b2, wK);
;             G_BAR; G_WAIT_L(0); G_MMA(0, 1, At, B1); G_BAR;
;             G_LDA(At, 0, 1); G_STA(G_SA(0, 0), a2, wlda);
;             G_BAR; G_WAIT_L(0); G_MMA(1, 0, At, B0); G_BAR; G_SCHED;
;             G_STB(G_SB(0, 1), b2 + HSTEP(wK), wK);
;             G_WAIT_V(6); G_BAR; G_MMA(1, 1, At, B1); G_BAR;
;             G_LDB(B0, 1, 0); G_SCHED; G_LDA(At, 1, 0); G_STA(G_SA(0, 1), a2 + HSTEP(wlda), wlda);
;             G_WAIT_L(8); G_BAR; G_WAIT_L(0); G_MMA(0, 0, At, B0); G_BAR; G_SCHED;
;             G_LDB(B1, 1, 1); G_STB(G_SB(1, 0), b3, wK);
;             G_BAR; G_WAIT_L(0); G_MMA(0, 1, At, B1); G_BAR;
;             G_LDA(At, 1, 1); G_STA(G_SA(1, 0), a3, wlda);
;             G_BAR; G_WAIT_L(0); G_MMA(1, 0, At, B0); G_BAR; G_SCHED;
;             G_STB(G_SB(1, 1), b3 + HSTEP(wK), wK);
;             G_WAIT_V(6); G_BAR; G_MMA(1, 1, At, B1); G_BAR;
;         }
	s_add_u32 s52, s26, 0x20000
	s_addc_u32 s53, s27, 0
	s_add_i32 s31, s51, s34
	v_lshl_add_u64 v[146:147], s[52:53], 0, v[0:1]
	s_mov_b32 m0, s31
	s_nop 0
	global_load_lds_dwordx4 v[146:147], off
	v_lshl_add_u64 v[146:147], s[52:53], 0, v[134:135]
	s_add_i32 m0, s31, 0x2000
	s_nop 0
	global_load_lds_dwordx4 v[146:147], off
	s_waitcnt vmcnt(6)
	s_barrier
	s_setprio 1
	v_mfma_f32_16x16x32_bf16 v[50:53], v[208:211], v[164:167], v[50:53]
	v_mfma_f32_16x16x32_bf16 v[42:45], v[216:219], v[164:167], v[42:45]
	v_mfma_f32_16x16x32_bf16 v[34:37], v[208:211], v[172:175], v[34:37]
	v_mfma_f32_16x16x32_bf16 v[26:29], v[216:219], v[172:175], v[26:29]
	v_mfma_f32_16x16x32_bf16 v[18:21], v[208:211], v[192:195], v[18:21]
	v_mfma_f32_16x16x32_bf16 v[10:13], v[216:219], v[192:195], v[10:13]
	v_mfma_f32_16x16x32_bf16 v[6:9], v[208:211], v[200:203], v[6:9]
	v_mfma_f32_16x16x32_bf16 v[2:5], v[216:219], v[200:203], v[2:5]
	v_mfma_f32_16x16x32_bf16 v[50:53], v[212:215], v[168:171], v[50:53]
	v_mfma_f32_16x16x32_bf16 v[42:45], v[220:223], v[168:171], v[42:45]
	v_mfma_f32_16x16x32_bf16 v[34:37], v[212:215], v[176:179], v[34:37]
	v_mfma_f32_16x16x32_bf16 v[26:29], v[220:223], v[176:179], v[26:29]
	v_mfma_f32_16x16x32_bf16 v[18:21], v[212:215], v[196:199], v[18:21]
	v_mfma_f32_16x16x32_bf16 v[10:13], v[220:223], v[196:199], v[10:13]
	v_mfma_f32_16x16x32_bf16 v[6:9], v[212:215], v[204:207], v[6:9]
	v_mfma_f32_16x16x32_bf16 v[2:5], v[220:223], v[204:207], v[2:5]
	s_setprio 0
	s_add_i32 s51, 0, 0x18000
	v_add_u32_e32 v160, s51, v139
	s_barrier
	ds_read_b128 v[146:149], v160
	ds_read_b128 v[150:153], v160 offset:1024
	ds_read_b128 v[154:157], v160 offset:2048
	ds_read_b128 v[160:163], v160 offset:3072
	s_ashr_i32 s31, s30, 31
	s_lshl_b64 s[30:31], s[30:31], 8
	s_add_u32 s28, s28, s30
	s_addc_u32 s29, s29, s31
	s_mov_b32 m0, s37
	ds_read_b128 v[164:167], v145 offset:32768
	ds_read_b128 v[168:171], v145 offset:33792
	ds_read_b128 v[172:175], v145 offset:34816
	ds_read_b128 v[176:179], v145 offset:35840
	ds_read_b128 v[192:195], v145 offset:36864
	ds_read_b128 v[196:199], v145 offset:37888
	ds_read_b128 v[200:203], v145 offset:38912
	ds_read_b128 v[204:207], v145 offset:39936
	global_load_lds_dwordx4 v232, s[28:29]
	s_mov_b32 m0, s38
	s_nop 0
	global_load_lds_dwordx4 v234, s[28:29]
	s_waitcnt lgkmcnt(8)
	s_barrier
	s_waitcnt lgkmcnt(0)
	s_setprio 1
	s_waitcnt lgkmcnt(0)
	v_mfma_f32_16x16x32_bf16 v[126:129], v[146:149], v[164:167], v[126:129]
	v_mfma_f32_16x16x32_bf16 v[122:125], v[154:157], v[164:167], v[122:125]
	v_mfma_f32_16x16x32_bf16 v[118:121], v[146:149], v[172:175], v[118:121]
	v_mfma_f32_16x16x32_bf16 v[110:113], v[154:157], v[172:175], v[110:113]
	v_mfma_f32_16x16x32_bf16 v[102:105], v[146:149], v[192:195], v[102:105]
	v_mfma_f32_16x16x32_bf16 v[94:97], v[154:157], v[192:195], v[94:97]
	v_mfma_f32_16x16x32_bf16 v[86:89], v[146:149], v[200:203], v[86:89]
	v_mfma_f32_16x16x32_bf16 v[78:81], v[154:157], v[200:203], v[78:81]
	v_mfma_f32_16x16x32_bf16 v[126:129], v[150:153], v[168:171], v[126:129]
	v_mfma_f32_16x16x32_bf16 v[122:125], v[160:163], v[168:171], v[122:125]
	v_mfma_f32_16x16x32_bf16 v[118:121], v[150:153], v[176:179], v[118:121]
	v_mfma_f32_16x16x32_bf16 v[110:113], v[160:163], v[176:179], v[110:113]
	v_mfma_f32_16x16x32_bf16 v[102:105], v[150:153], v[196:199], v[102:105]
	v_mfma_f32_16x16x32_bf16 v[94:97], v[160:163], v[196:199], v[94:97]
	v_mfma_f32_16x16x32_bf16 v[86:89], v[150:153], v[204:207], v[86:89]
	v_mfma_f32_16x16x32_bf16 v[78:81], v[160:163], v[204:207], v[78:81]
	s_setprio 0
	s_barrier
	s_add_i32 s28, 0, 0x1c000
	s_add_i32 s29, s51, s34
	v_add_u32_e32 v220, s28, v139
	v_lshl_add_u64 v[224:225], v[224:225], 0, s[78:79]
	s_mov_b32 m0, s29
	ds_read_b128 v[208:211], v220
	ds_read_b128 v[212:215], v220 offset:1024
	ds_read_b128 v[216:219], v220 offset:2048
	ds_read_b128 v[220:223], v220 offset:3072
	global_load_lds_dwordx4 v[224:225], off
	v_lshl_add_u64 v[224:225], v[230:231], 0, s[78:79]
	s_add_i32 m0, s29, 0x2000
	s_nop 0
	global_load_lds_dwordx4 v[224:225], off
	s_barrier
	s_waitcnt lgkmcnt(0)
	s_setprio 1
	s_waitcnt lgkmcnt(0)
	v_mfma_f32_16x16x32_bf16 v[114:117], v[208:211], v[164:167], v[114:117]
	v_mfma_f32_16x16x32_bf16 v[106:109], v[216:219], v[164:167], v[106:109]
	v_mfma_f32_16x16x32_bf16 v[98:101], v[208:211], v[172:175], v[98:101]
	v_mfma_f32_16x16x32_bf16 v[90:93], v[216:219], v[172:175], v[90:93]
	v_mfma_f32_16x16x32_bf16 v[82:85], v[208:211], v[192:195], v[82:85]
	v_mfma_f32_16x16x32_bf16 v[74:77], v[216:219], v[192:195], v[74:77]
	v_mfma_f32_16x16x32_bf16 v[70:73], v[208:211], v[200:203], v[70:73]
	v_mfma_f32_16x16x32_bf16 v[66:69], v[216:219], v[200:203], v[66:69]
	v_mfma_f32_16x16x32_bf16 v[114:117], v[212:215], v[168:171], v[114:117]
	v_mfma_f32_16x16x32_bf16 v[106:109], v[220:223], v[168:171], v[106:109]
	v_mfma_f32_16x16x32_bf16 v[98:101], v[212:215], v[176:179], v[98:101]
	v_mfma_f32_16x16x32_bf16 v[90:93], v[220:223], v[176:179], v[90:93]
	v_mfma_f32_16x16x32_bf16 v[82:85], v[212:215], v[196:199], v[82:85]
	v_mfma_f32_16x16x32_bf16 v[74:77], v[220:223], v[196:199], v[74:77]
	v_mfma_f32_16x16x32_bf16 v[70:73], v[212:215], v[204:207], v[70:73]
	v_mfma_f32_16x16x32_bf16 v[66:69], v[220:223], v[204:207], v[66:69]
	s_setprio 0
	s_mov_b32 m0, s39
	v_lshl_add_u64 v[224:225], v[236:237], 0, s[78:79]
	s_barrier
	ds_read_b128 v[164:167], v145 offset:49152
	ds_read_b128 v[168:171], v145 offset:50176
	ds_read_b128 v[172:175], v145 offset:51200
	ds_read_b128 v[176:179], v145 offset:52224
	ds_read_b128 v[192:195], v145 offset:53248
	ds_read_b128 v[196:199], v145 offset:54272
	ds_read_b128 v[200:203], v145 offset:55296
	ds_read_b128 v[204:207], v145 offset:56320
	global_load_lds_dwordx4 v[224:225], off
	v_lshl_add_u64 v[224:225], v[238:239], 0, s[78:79]
	s_mov_b32 m0, s40
	s_nop 0
	global_load_lds_dwordx4 v[224:225], off
	s_barrier
; #define G_STA(bufoff, gbase, ld) G_STAGE(bufoff, gbase, RA0, RA1, ld)
; #define G_STB(bufoff, gbase, ld) G_STAGE(bufoff, gbase, RB0, RB1, ld)
; #define G_LDA(dst, b, h) do { _Pragma("unroll") for (int m = 0; m < 4; ++m) _Pragma("unroll") for (int k = 0; k < 2; ++k) dst[m][k] = *(const LAS bf16x8*)(lds + G_SA(b, h) + aoff + m * 2048 + k * 1024); } while (0)
; #define G_LDB(dst, b, h) do { _Pragma("unroll") for (int n = 0; n < 2; ++n) _Pragma("unroll") for (int k = 0; k < 2; ++k) dst[n][k] = *(const LAS bf16x8*)(lds + G_SB(b, h) + boff + n * 2048 + k * 1024); } while (0)
; #define G_MMA(ai, bj, At, Bt) do { __builtin_amdgcn_s_setprio(1); _Pragma("unroll") for (int m = 0; m < 4; ++m) _Pragma("unroll") for (int n = 0; n < 2; ++n) _Pragma("unroll") for (int k = 0; k < 2; ++k) \
;         acc[ai][bj][m][n] = __builtin_amdgcn_mfma_f32_16x16x32_bf16(Bt[n][k], At[m][k], acc[ai][bj][m][n], 0, 0, 0); __builtin_amdgcn_s_setprio(0); } while (0)
; #define G_WAIT_V(n) asm volatile("s_waitcnt vmcnt(" #n ")" ::: "memory")
; #define G_WAIT_L(n) asm volatile("s_waitcnt lgkmcnt(" #n ")" ::: "memory")
; #define G_BAR __builtin_amdgcn_s_barrier()
; #define G_SCHED __builtin_amdgcn_sched_barrier(0)
; template <bool PERM, class SchedT, class Epi>
; __device__ __forceinline__ void gemm_phase(LAS unsigned char* lds, const SchedT& S, const Epi& E) {
;     ...
;             G_WAIT_V(6); G_BAR; G_MMA(1, 1, At, B1); G_BAR;
;             G_LDB(B0, 1, 0); G_SCHED; G_LDA(At, 1, 0); G_STA(G_SA(0, 1), a2 + HSTEP(wlda), wlda);
;             G_WAIT_L(8); G_BAR; G_WAIT_L(0); G_MMA(0, 0, At, B0); G_BAR; G_SCHED;
;             G_LDB(B1, 1, 1); G_STB(G_SB(1, 0), b3, wK);
;             G_BAR; G_WAIT_L(0); G_MMA(0, 1, At, B1); G_BAR;
;             G_LDA(At, 1, 1); G_STA(G_SA(1, 0), a3, wlda);
;             G_BAR; G_WAIT_L(0); G_MMA(1, 0, At, B0); G_BAR; G_SCHED;
;             G_STB(G_SB(1, 1), b3 + HSTEP(wK), wK);
;             G_WAIT_V(6); G_BAR; G_MMA(1, 1, At, B1); G_BAR;
;         }
	s_waitcnt lgkmcnt(0)
	s_setprio 1
	s_waitcnt lgkmcnt(0)
	v_mfma_f32_16x16x32_bf16 v[62:65], v[146:149], v[164:167], v[62:65]
	v_mfma_f32_16x16x32_bf16 v[58:61], v[154:157], v[164:167], v[58:61]
	v_mfma_f32_16x16x32_bf16 v[54:57], v[146:149], v[172:175], v[54:57]
	v_mfma_f32_16x16x32_bf16 v[46:49], v[154:157], v[172:175], v[46:49]
	v_mfma_f32_16x16x32_bf16 v[38:41], v[146:149], v[192:195], v[38:41]
	v_mfma_f32_16x16x32_bf16 v[30:33], v[154:157], v[192:195], v[30:33]
	v_mfma_f32_16x16x32_bf16 v[22:25], v[146:149], v[200:203], v[22:25]
	v_mfma_f32_16x16x32_bf16 v[14:17], v[154:157], v[200:203], v[14:17]
	v_mfma_f32_16x16x32_bf16 v[62:65], v[150:153], v[168:171], v[62:65]
	v_mfma_f32_16x16x32_bf16 v[58:61], v[160:163], v[168:171], v[58:61]
	v_mfma_f32_16x16x32_bf16 v[54:57], v[150:153], v[176:179], v[54:57]
	v_mfma_f32_16x16x32_bf16 v[46:49], v[160:163], v[176:179], v[46:49]
	v_mfma_f32_16x16x32_bf16 v[38:41], v[150:153], v[196:199], v[38:41]
	v_mfma_f32_16x16x32_bf16 v[30:33], v[160:163], v[196:199], v[30:33]
	v_mfma_f32_16x16x32_bf16 v[22:25], v[150:153], v[204:207], v[22:25]
	v_mfma_f32_16x16x32_bf16 v[14:17], v[160:163], v[204:207], v[14:17]
	s_setprio 0
	s_barrier
	s_add_u32 s26, s26, 0x20080
	s_addc_u32 s27, s27, 0
	s_add_i32 s28, s28, s34
	v_lshl_add_u64 v[146:147], s[26:27], 0, v[0:1]
	s_mov_b32 m0, s28
	s_nop 0
	global_load_lds_dwordx4 v[146:147], off
	v_lshl_add_u64 v[146:147], s[26:27], 0, v[134:135]
	s_add_i32 m0, s28, 0x2000
	s_nop 0
	global_load_lds_dwordx4 v[146:147], off
	s_waitcnt vmcnt(6)
	s_barrier
	s_setprio 1
	v_mfma_f32_16x16x32_bf16 v[50:53], v[208:211], v[164:167], v[50:53]
	v_mfma_f32_16x16x32_bf16 v[42:45], v[216:219], v[164:167], v[42:45]
	v_mfma_f32_16x16x32_bf16 v[34:37], v[208:211], v[172:175], v[34:37]
	v_mfma_f32_16x16x32_bf16 v[26:29], v[216:219], v[172:175], v[26:29]
	v_mfma_f32_16x16x32_bf16 v[18:21], v[208:211], v[192:195], v[18:21]
	v_mfma_f32_16x16x32_bf16 v[10:13], v[216:219], v[192:195], v[10:13]
	v_mfma_f32_16x16x32_bf16 v[6:9], v[208:211], v[200:203], v[6:9]
	v_mfma_f32_16x16x32_bf16 v[2:5], v[216:219], v[200:203], v[2:5]
	v_mfma_f32_16x16x32_bf16 v[50:53], v[212:215], v[168:171], v[50:53]
	v_mfma_f32_16x16x32_bf16 v[42:45], v[220:223], v[168:171], v[42:45]
	v_mfma_f32_16x16x32_bf16 v[34:37], v[212:215], v[176:179], v[34:37]
	v_mfma_f32_16x16x32_bf16 v[26:29], v[220:223], v[176:179], v[26:29]
	v_mfma_f32_16x16x32_bf16 v[18:21], v[212:215], v[196:199], v[18:21]
	v_mfma_f32_16x16x32_bf16 v[10:13], v[220:223], v[196:199], v[10:13]
	v_mfma_f32_16x16x32_bf16 v[6:9], v[212:215], v[204:207], v[6:9]
	v_mfma_f32_16x16x32_bf16 v[2:5], v[220:223], v[204:207], v[2:5]
	s_setprio 0
	s_add_i32 s50, s50, 2
	s_add_u32 s22, s22, 0x100
	s_addc_u32 s23, s23, 0
	s_cmp_gt_u32 s50, 5
	s_barrier
	s_cbranch_scc0 .LBB0_165
	s_cmpk_gt_u32 s4, 0xff
	s_cbranch_scc1 .Lus_g2a
	s_barrier
; __device__ __forceinline__ unsigned cvt_pk(float lo, float hi) { unsigned r; asm volatile("v_cvt_pk_bf16_f32 %0, %1, %2" : "=v"(r) : "v"(lo), "v"(hi)); return r; }
; #define GAS __attribute__((address_space(1)))
; template <bool PERM, class SchedT, class Epi>
; __device__ __forceinline__ void gemm_phase(LAS unsigned char* lds, const SchedT& S, const Epi& E) {
;     ...
;         if (!has_next) break;
; #pragma unroll
;         for (int a = 0; a < 2; ++a)
; #pragma unroll
;             for (int b = 0; b < 2; ++b)
; #pragma unroll
;                 for (int m = 0; m < 4; ++m)
; #pragma unroll
;                     for (int n = 0; n < 2; ++n) acc[a][b][m][n] = (f32x4){0.f, 0.f, 0.f, 0.f};
;         cur = nxt; cA = nA; cB = nB; lda = nlda; K = nK; ++ui;
;     __device__ __forceinline__ void operator()(const f32x4 (&acc)[2][2][4][2], const UnitD& u, int wr, int wc, int fr, int fq) const {
;         const int row0 = u.pm * BM + wr * 64 + fr, col0 = u.pn * BM + wc * 32 + 8 * fq;
;         GAS bf16_t* C = (GAS bf16_t*)(unsigned long long)u.C;
; #pragma unroll
;         for (int ai = 0; ai < 2; ++ai)
; #pragma unroll
;             for (int m = 0; m < 4; ++m) { GAS bf16_t* rowp = C + (size_t)(row0 + ai * HALF + m * 16) * u.ldc + col0;
; #pragma unroll
;                 for (int bj = 0; bj < 2; ++bj) { const f32x4 v0 = acc[ai][bj][m][0], v1 = acc[ai][bj][m][1];
;                     u32x4 w; w.x = cvt_pk(v0[0], v0[1]); w.y = cvt_pk(v0[2], v0[3]); w.z = cvt_pk(v1[0], v1[1]); w.w = cvt_pk(v1[2], v1[3]);
;                     *(GAS u32x4*)(rowp + bj * HALF) = w; } }
.Lus_g2a:
	v_lshl_or_b32 v140, s43, 8, v144
	v_lshl_add_u32 v146, s42, 8, v137
	v_ashrrev_i32_e32 v141, 31, v140
	v_lshl_add_u64 v[140:141], v[140:141], 1, s[8:9]
	v_cvt_pk_bf16_f32 v126, v126, v127
	v_cvt_pk_bf16_f32 v127, v128, v129
	v_cvt_pk_bf16_f32 v128, v122, v123
	v_cvt_pk_bf16_f32 v129, v124, v125
	ds_write_b128 v251, v[126:129]
	ds_read_b128 v[126:129], v252
	v_cvt_pk_bf16_f32 v114, v114, v115
	v_cvt_pk_bf16_f32 v115, v116, v117
	v_cvt_pk_bf16_f32 v116, v106, v107
	v_cvt_pk_bf16_f32 v117, v108, v109
	ds_write_b128 v251, v[114:117]
	ds_read_b128 v[114:117], v252
	v_cvt_pk_bf16_f32 v118, v118, v119
	v_cvt_pk_bf16_f32 v119, v120, v121
	v_cvt_pk_bf16_f32 v120, v110, v111
	v_cvt_pk_bf16_f32 v121, v112, v113
	ds_write_b128 v251, v[118:121]
	ds_read_b128 v[118:121], v252
	v_mad_i64_i32 v[254:255], vcc, v146, s5, 0
	v_lshl_add_u64 v[254:255], v[254:255], 1, v[140:141]
	s_waitcnt lgkmcnt(4)
	global_store_dwordx4 v[254:255], v[126:129], off
	v_cvt_pk_bf16_f32 v98, v98, v99
	v_cvt_pk_bf16_f32 v99, v100, v101
	v_cvt_pk_bf16_f32 v100, v90, v91
	v_cvt_pk_bf16_f32 v101, v92, v93
	ds_write_b128 v251, v[98:101]
	ds_read_b128 v[98:101], v252
	s_waitcnt lgkmcnt(4)
	global_store_dwordx4 v[254:255], v[114:117], off offset:256
	v_cvt_pk_bf16_f32 v102, v102, v103
	v_cvt_pk_bf16_f32 v103, v104, v105
	v_cvt_pk_bf16_f32 v104, v94, v95
	v_cvt_pk_bf16_f32 v105, v96, v97
	ds_write_b128 v251, v[102:105]
	ds_read_b128 v[102:105], v252
	v_add_u32_e32 v253, 16, v146
	v_mad_i64_i32 v[254:255], vcc, v253, s5, 0
	v_lshl_add_u64 v[254:255], v[254:255], 1, v[140:141]
	s_waitcnt lgkmcnt(4)
	global_store_dwordx4 v[254:255], v[118:121], off
	v_cvt_pk_bf16_f32 v82, v82, v83
	v_cvt_pk_bf16_f32 v83, v84, v85
	v_cvt_pk_bf16_f32 v84, v74, v75
	v_cvt_pk_bf16_f32 v85, v76, v77
	ds_write_b128 v251, v[82:85]
	ds_read_b128 v[82:85], v252
	s_waitcnt lgkmcnt(4)
	global_store_dwordx4 v[254:255], v[98:101], off offset:256
	v_cvt_pk_bf16_f32 v86, v86, v87
	v_cvt_pk_bf16_f32 v87, v88, v89
	v_cvt_pk_bf16_f32 v88, v78, v79
	v_cvt_pk_bf16_f32 v89, v80, v81
	ds_write_b128 v251, v[86:89]
	ds_read_b128 v[86:89], v252
	v_add_u32_e32 v253, 32, v146
	v_mad_i64_i32 v[254:255], vcc, v253, s5, 0
	v_lshl_add_u64 v[254:255], v[254:255], 1, v[140:141]
	s_waitcnt lgkmcnt(4)
	global_store_dwordx4 v[254:255], v[102:105], off
	v_cvt_pk_bf16_f32 v70, v70, v71
	v_cvt_pk_bf16_f32 v71, v72, v73
	v_cvt_pk_bf16_f32 v72, v66, v67
	v_cvt_pk_bf16_f32 v73, v68, v69
	ds_write_b128 v251, v[70:73]
	ds_read_b128 v[70:73], v252
	s_waitcnt lgkmcnt(4)
	global_store_dwordx4 v[254:255], v[82:85], off offset:256
	v_cvt_pk_bf16_f32 v62, v62, v63
	v_cvt_pk_bf16_f32 v63, v64, v65
	v_cvt_pk_bf16_f32 v64, v58, v59
	v_cvt_pk_bf16_f32 v65, v60, v61
	ds_write_b128 v251, v[62:65]
	ds_read_b128 v[62:65], v252
	v_add_u32_e32 v253, 48, v146
	v_mad_i64_i32 v[254:255], vcc, v253, s5, 0
	v_lshl_add_u64 v[254:255], v[254:255], 1, v[140:141]
	s_waitcnt lgkmcnt(4)
	global_store_dwordx4 v[254:255], v[86:89], off
	v_cvt_pk_bf16_f32 v50, v50, v51
	v_cvt_pk_bf16_f32 v51, v52, v53
	v_cvt_pk_bf16_f32 v52, v42, v43
	v_cvt_pk_bf16_f32 v53, v44, v45
	ds_write_b128 v251, v[50:53]
	ds_read_b128 v[50:53], v252
	s_waitcnt lgkmcnt(4)
	global_store_dwordx4 v[254:255], v[70:73], off offset:256
	v_cvt_pk_bf16_f32 v54, v54, v55
	v_cvt_pk_bf16_f32 v55, v56, v57
	v_cvt_pk_bf16_f32 v56, v46, v47
	v_cvt_pk_bf16_f32 v57, v48, v49
	ds_write_b128 v251, v[54:57]
	ds_read_b128 v[54:57], v252
	v_add_u32_e32 v253, 128, v146
	v_mad_i64_i32 v[254:255], vcc, v253, s5, 0
	v_lshl_add_u64 v[254:255], v[254:255], 1, v[140:141]
	s_waitcnt lgkmcnt(4)
	global_store_dwordx4 v[254:255], v[62:65], off
	v_cvt_pk_bf16_f32 v34, v34, v35
	v_cvt_pk_bf16_f32 v35, v36, v37
	v_cvt_pk_bf16_f32 v36, v26, v27
	v_cvt_pk_bf16_f32 v37, v28, v29
	ds_write_b128 v251, v[34:37]
	ds_read_b128 v[34:37], v252
	s_waitcnt lgkmcnt(4)
	global_store_dwordx4 v[254:255], v[50:53], off offset:256
	v_cvt_pk_bf16_f32 v38, v38, v39
	v_cvt_pk_bf16_f32 v39, v40, v41
	v_cvt_pk_bf16_f32 v40, v30, v31
	v_cvt_pk_bf16_f32 v41, v32, v33
	ds_write_b128 v251, v[38:41]
	ds_read_b128 v[38:41], v252
	v_add_u32_e32 v253, 144, v146
	v_mad_i64_i32 v[254:255], vcc, v253, s5, 0
	v_lshl_add_u64 v[254:255], v[254:255], 1, v[140:141]
	s_waitcnt lgkmcnt(4)
	global_store_dwordx4 v[254:255], v[54:57], off
	v_cvt_pk_bf16_f32 v18, v18, v19
	v_cvt_pk_bf16_f32 v19, v20, v21
	v_cvt_pk_bf16_f32 v20, v10, v11
	v_cvt_pk_bf16_f32 v21, v12, v13
	ds_write_b128 v251, v[18:21]
	ds_read_b128 v[18:21], v252
	s_waitcnt lgkmcnt(4)
	global_store_dwordx4 v[254:255], v[34:37], off offset:256
	v_cvt_pk_bf16_f32 v22, v22, v23
	v_cvt_pk_bf16_f32 v23, v24, v25
	v_cvt_pk_bf16_f32 v24, v14, v15
	v_cvt_pk_bf16_f32 v25, v16, v17
	ds_write_b128 v251, v[22:25]
	ds_read_b128 v[22:25], v252
	v_add_u32_e32 v253, 160, v146
	v_mad_i64_i32 v[254:255], vcc, v253, s5, 0
	v_lshl_add_u64 v[254:255], v[254:255], 1, v[140:141]
	s_waitcnt lgkmcnt(4)
	global_store_dwordx4 v[254:255], v[38:41], off
	v_cvt_pk_bf16_f32 v6, v6, v7
	v_cvt_pk_bf16_f32 v7, v8, v9
	v_cvt_pk_bf16_f32 v8, v2, v3
	v_cvt_pk_bf16_f32 v9, v4, v5
	ds_write_b128 v251, v[6:9]
	ds_read_b128 v[6:9], v252
	s_waitcnt lgkmcnt(4)
	global_store_dwordx4 v[254:255], v[18:21], off offset:256
	v_add_u32_e32 v253, 176, v146
	v_mad_i64_i32 v[254:255], vcc, v253, s5, 0
	v_lshl_add_u64 v[254:255], v[254:255], 1, v[140:141]
	s_waitcnt lgkmcnt(2)
	global_store_dwordx4 v[254:255], v[22:25], off
	s_waitcnt lgkmcnt(0)
	global_store_dwordx4 v[254:255], v[6:9], off offset:256
	s_cmpk_gt_u32 s4, 0xff
	s_cbranch_scc0 .Lus_g2b
	s_barrier
.Lus_g2b:
	s_and_b64 vcc, exec, s[20:21]
	s_mov_b32 s43, s72
	s_mov_b32 s42, s14
	s_mov_b64 s[8:9], s[18:19]
	s_mov_b64 s[26:27], s[10:11]
	s_mov_b64 s[12:13], s[16:17]
	s_mov_b32 s48, 0xffcf4000
	s_movk_i32 s49, 0x3fff
	s_mov_b32 s5, s15
	s_mov_b32 s6, s44
	s_cbranch_vccz .LBB0_148
	s_waitcnt vmcnt(0)
	s_mov_b64 s[46:47], s[80:81]
	s_mov_b32 s45, s97
	s_cmpk_gt_u32 s4, 0xff
	s_cbranch_scc1 .LBB0_169
	s_barrier

; #define G_STA(bufoff, gbase, ld) G_STAGE(bufoff, gbase, RA0, RA1, ld)
; #define G_STB(bufoff, gbase, ld) G_STAGE(bufoff, gbase, RB0, RB1, ld)
; #define G_LDA(dst, b, h) do { _Pragma("unroll") for (int m = 0; m < 4; ++m) _Pragma("unroll") for (int k = 0; k < 2; ++k) dst[m][k] = *(const LAS bf16x8*)(lds + G_SA(b, h) + aoff + m * 2048 + k * 1024); } while (0)
; #define G_LDB(dst, b, h) do { _Pragma("unroll") for (int n = 0; n < 2; ++n) _Pragma("unroll") for (int k = 0; k < 2; ++k) dst[n][k] = *(const LAS bf16x8*)(lds + G_SB(b, h) + boff + n * 2048 + k * 1024); } while (0)
; #define G_WAIT_V(n) asm volatile("s_waitcnt vmcnt(" #n ")" ::: "memory")
; #define G_BAR __builtin_amdgcn_s_barrier()
; template <bool PERM, class SchedT, class Epi>
; __device__ __forceinline__ void gemm_phase(LAS unsigned char* lds, const SchedT& S, const Epi& E) {
;     ...
;         for (int t = 0; t < nt; t += 2) {
;             const bool last = (t == nt - 2);
;             const char* a1 = cA + (size_t)(t + 1) * kstep;
;             const char* a2 = last ? nA : cA + (size_t)(t + 2) * kstep; const char* b2 = last ? nB : cB + (size_t)(t + 2) * kstep;
;             const char* a3 = a2 + kstep; const char* b3 = b2 + kstep;
;             const int wlda = last ? nlda : lda, wK = last ? nK : K;
;             G_LDB(B0, 0, 0); G_SCHED; G_LDA(At, 0, 0); G_STA(G_SA(1, 1), a1 + HSTEP(lda), lda);
;             G_WAIT_L(8); G_BAR; G_WAIT_L(0); G_MMA(0, 0, At, B0); G_BAR; G_SCHED;
;             G_LDB(B1, 0, 1); G_STB(G_SB(0, 0), b2, wK);
;             G_BAR; G_WAIT_L(0); G_MMA(0, 1, At, B1); G_BAR;
;             G_LDA(At, 0, 1); G_STA(G_SA(0, 0), a2, wlda);
;             G_BAR; G_WAIT_L(0); G_MMA(1, 0, At, B0); G_BAR; G_SCHED;
;             G_STB(G_SB(0, 1), b2 + HSTEP(wK), wK);
;             G_WAIT_V(6); G_BAR; G_MMA(1, 1, At, B1); G_BAR;
;             G_LDB(B0, 1, 0); G_SCHED; G_LDA(At, 1, 0); G_STA(G_SA(0, 1), a2 + HSTEP(wlda), wlda);
;             G_WAIT_L(8); G_BAR; G_WAIT_L(0); G_MMA(0, 0, At, B0); G_BAR; G_SCHED;
;             G_LDB(B1, 1, 1); G_STB(G_SB(1, 0), b3, wK);
;             G_BAR; G_WAIT_L(0); G_MMA(0, 1, At, B1); G_BAR;
;             G_LDA(At, 1, 1); G_STA(G_SA(1, 0), a3, wlda);
;             G_BAR; G_WAIT_L(0); G_MMA(1, 0, At, B0); G_BAR; G_SCHED;
;             G_STB(G_SB(1, 1), b3 + HSTEP(wK), wK);
;             G_WAIT_V(6); G_BAR; G_MMA(1, 1, At, B1); G_BAR;
;         }
.LBB0_249:
	s_add_u32 s18, s8, 0xfff80080
	s_addc_u32 s19, s9, -1
	s_add_i32 s35, 0, 0x10000
	v_add_u32_e32 v144, s35, v147
	ds_read_b128 v[140:143], v144
	ds_read_b128 v[150:153], v144 offset:1024
	ds_read_b128 v[154:157], v144 offset:2048
	ds_read_b128 v[160:163], v144 offset:3072
	s_cmp_eq_u32 s34, 28
	s_cselect_b32 s21, s15, s19
	s_cselect_b32 s20, s14, s18
	s_cselect_b32 s19, s17, s13
	s_cselect_b32 s18, s16, s11
	v_lshl_add_u64 v[144:145], s[8:9], 0, v[136:137]
	s_add_i32 m0, s22, 0xc000
	ds_read_b128 v[164:167], v149
	ds_read_b128 v[168:171], v149 offset:1024
	ds_read_b128 v[172:175], v149 offset:2048
	ds_read_b128 v[176:179], v149 offset:3072
	ds_read_b128 v[192:195], v149 offset:4096
	ds_read_b128 v[196:199], v149 offset:5120
	ds_read_b128 v[200:203], v149 offset:6144
	ds_read_b128 v[204:207], v149 offset:7168
	global_load_lds_dwordx4 v[144:145], off
	v_lshl_add_u64 v[144:145], s[8:9], 0, v[138:139]
	s_add_i32 m0, s22, 0xe000
	s_nop 0
	global_load_lds_dwordx4 v[144:145], off
	s_waitcnt lgkmcnt(8)
	s_barrier
	s_waitcnt lgkmcnt(0)
	s_setprio 1
	s_waitcnt lgkmcnt(0)
	v_mfma_f32_16x16x32_bf16 v[126:129], v[140:143], v[164:167], v[126:129]
	v_mfma_f32_16x16x32_bf16 v[122:125], v[154:157], v[164:167], v[122:125]
	v_mfma_f32_16x16x32_bf16 v[118:121], v[140:143], v[172:175], v[118:121]
	v_mfma_f32_16x16x32_bf16 v[114:117], v[154:157], v[172:175], v[114:117]
	v_mfma_f32_16x16x32_bf16 v[110:113], v[140:143], v[192:195], v[110:113]
	v_mfma_f32_16x16x32_bf16 v[106:109], v[154:157], v[192:195], v[106:109]
	v_mfma_f32_16x16x32_bf16 v[102:105], v[140:143], v[200:203], v[102:105]
	v_mfma_f32_16x16x32_bf16 v[98:101], v[154:157], v[200:203], v[98:101]
	v_mfma_f32_16x16x32_bf16 v[126:129], v[150:153], v[168:171], v[126:129]
	v_mfma_f32_16x16x32_bf16 v[122:125], v[160:163], v[168:171], v[122:125]
	v_mfma_f32_16x16x32_bf16 v[118:121], v[150:153], v[176:179], v[118:121]
	v_mfma_f32_16x16x32_bf16 v[114:117], v[160:163], v[176:179], v[114:117]
	v_mfma_f32_16x16x32_bf16 v[110:113], v[150:153], v[196:199], v[110:113]
	v_mfma_f32_16x16x32_bf16 v[106:109], v[160:163], v[196:199], v[106:109]
	v_mfma_f32_16x16x32_bf16 v[102:105], v[150:153], v[204:207], v[102:105]
	v_mfma_f32_16x16x32_bf16 v[98:101], v[160:163], v[204:207], v[98:101]
	s_setprio 0
	s_barrier
	s_add_i32 s38, 0, 0x14000
	v_add_u32_e32 v144, s38, v147
	s_add_i32 s35, s35, s5
	ds_read_b128 v[208:211], v144
	ds_read_b128 v[212:215], v144 offset:1024
	ds_read_b128 v[216:219], v144 offset:2048
	ds_read_b128 v[220:223], v144 offset:3072
	v_lshl_add_u64 v[144:145], s[18:19], 0, v[0:1]
	s_mov_b32 m0, s35
	v_lshl_add_u64 v[224:225], s[18:19], 0, v[130:131]
	global_load_lds_dwordx4 v[144:145], off
	s_add_i32 m0, s35, 0x2000
	s_nop 0
	global_load_lds_dwordx4 v[224:225], off
	s_barrier
	s_waitcnt lgkmcnt(0)
	s_setprio 1
	s_waitcnt lgkmcnt(0)
	v_mfma_f32_16x16x32_bf16 v[62:65], v[208:211], v[164:167], v[62:65]
	v_mfma_f32_16x16x32_bf16 v[58:61], v[216:219], v[164:167], v[58:61]
	v_mfma_f32_16x16x32_bf16 v[54:57], v[208:211], v[172:175], v[54:57]
	v_mfma_f32_16x16x32_bf16 v[50:53], v[216:219], v[172:175], v[50:53]
	v_mfma_f32_16x16x32_bf16 v[46:49], v[208:211], v[192:195], v[46:49]
	v_mfma_f32_16x16x32_bf16 v[42:45], v[216:219], v[192:195], v[42:45]
	v_mfma_f32_16x16x32_bf16 v[38:41], v[208:211], v[200:203], v[38:41]
	v_mfma_f32_16x16x32_bf16 v[34:37], v[216:219], v[200:203], v[34:37]
	v_mfma_f32_16x16x32_bf16 v[62:65], v[212:215], v[168:171], v[62:65]
	v_mfma_f32_16x16x32_bf16 v[58:61], v[220:223], v[168:171], v[58:61]
	v_mfma_f32_16x16x32_bf16 v[54:57], v[212:215], v[176:179], v[54:57]
	v_mfma_f32_16x16x32_bf16 v[50:53], v[220:223], v[176:179], v[50:53]
	v_mfma_f32_16x16x32_bf16 v[46:49], v[212:215], v[196:199], v[46:49]
	v_mfma_f32_16x16x32_bf16 v[42:45], v[220:223], v[196:199], v[42:45]
	v_mfma_f32_16x16x32_bf16 v[38:41], v[212:215], v[204:207], v[38:41]
	v_mfma_f32_16x16x32_bf16 v[34:37], v[220:223], v[204:207], v[34:37]
	s_setprio 0
	s_mov_b32 m0, s22
	v_lshl_add_u64 v[230:231], s[20:21], 0, v[132:133]
	s_barrier
	ds_read_b128 v[164:167], v149 offset:16384
	ds_read_b128 v[168:171], v149 offset:17408
	ds_read_b128 v[172:175], v149 offset:18432
	ds_read_b128 v[176:179], v149 offset:19456
	ds_read_b128 v[192:195], v149 offset:20480
	ds_read_b128 v[196:199], v149 offset:21504
	ds_read_b128 v[200:203], v149 offset:22528
	ds_read_b128 v[204:207], v149 offset:23552
	global_load_lds_dwordx4 v[230:231], off
	v_lshl_add_u64 v[232:233], s[20:21], 0, v[134:135]
	s_mov_b32 m0, s23
	s_nop 0
	global_load_lds_dwordx4 v[232:233], off
	s_barrier
	s_waitcnt lgkmcnt(0)
	s_setprio 1
	s_waitcnt lgkmcnt(0)
	v_mfma_f32_16x16x32_bf16 v[94:97], v[140:143], v[164:167], v[94:97]
	v_mfma_f32_16x16x32_bf16 v[90:93], v[154:157], v[164:167], v[90:93]
	v_mfma_f32_16x16x32_bf16 v[86:89], v[140:143], v[172:175], v[86:89]
	v_mfma_f32_16x16x32_bf16 v[82:85], v[154:157], v[172:175], v[82:85]
	v_mfma_f32_16x16x32_bf16 v[78:81], v[140:143], v[192:195], v[78:81]
	v_mfma_f32_16x16x32_bf16 v[74:77], v[154:157], v[192:195], v[74:77]
	v_mfma_f32_16x16x32_bf16 v[70:73], v[140:143], v[200:203], v[70:73]
	v_mfma_f32_16x16x32_bf16 v[66:69], v[154:157], v[200:203], v[66:69]
	v_mfma_f32_16x16x32_bf16 v[94:97], v[150:153], v[168:171], v[94:97]
	v_mfma_f32_16x16x32_bf16 v[90:93], v[160:163], v[168:171], v[90:93]
	v_mfma_f32_16x16x32_bf16 v[86:89], v[150:153], v[176:179], v[86:89]
	v_mfma_f32_16x16x32_bf16 v[82:85], v[160:163], v[176:179], v[82:85]
	v_mfma_f32_16x16x32_bf16 v[78:81], v[150:153], v[196:199], v[78:81]
	v_mfma_f32_16x16x32_bf16 v[74:77], v[160:163], v[196:199], v[74:77]
	v_mfma_f32_16x16x32_bf16 v[70:73], v[150:153], v[204:207], v[70:73]
	v_mfma_f32_16x16x32_bf16 v[66:69], v[160:163], v[204:207], v[66:69]
	s_setprio 0
	s_barrier
; #define G_STA(bufoff, gbase, ld) G_STAGE(bufoff, gbase, RA0, RA1, ld)
; #define G_STB(bufoff, gbase, ld) G_STAGE(bufoff, gbase, RB0, RB1, ld)
; #define G_LDA(dst, b, h) do { _Pragma("unroll") for (int m = 0; m < 4; ++m) _Pragma("unroll") for (int k = 0; k < 2; ++k) dst[m][k] = *(const LAS bf16x8*)(lds + G_SA(b, h) + aoff + m * 2048 + k * 1024); } while (0)
; #define G_LDB(dst, b, h) do { _Pragma("unroll") for (int n = 0; n < 2; ++n) _Pragma("unroll") for (int k = 0; k < 2; ++k) dst[n][k] = *(const LAS bf16x8*)(lds + G_SB(b, h) + boff + n * 2048 + k * 1024); } while (0)
; #define G_MMA(ai, bj, At, Bt) do { __builtin_amdgcn_s_setprio(1); _Pragma("unroll") for (int m = 0; m < 4; ++m) _Pragma("unroll") for (int n = 0; n < 2; ++n) _Pragma("unroll") for (int k = 0; k < 2; ++k) \
;         acc[ai][bj][m][n] = __builtin_amdgcn_mfma_f32_16x16x32_bf16(Bt[n][k], At[m][k], acc[ai][bj][m][n], 0, 0, 0); __builtin_amdgcn_s_setprio(0); } while (0)
; #define G_WAIT_V(n) asm volatile("s_waitcnt vmcnt(" #n ")" ::: "memory")
; #define G_WAIT_L(n) asm volatile("s_waitcnt lgkmcnt(" #n ")" ::: "memory")
; template <bool PERM, class SchedT, class Epi>
; __device__ __forceinline__ void gemm_phase(LAS unsigned char* lds, const SchedT& S, const Epi& E) {
;     ...
;             G_LDB(B0, 0, 0); G_SCHED; G_LDA(At, 0, 0); G_STA(G_SA(1, 1), a1 + HSTEP(lda), lda);
;             G_WAIT_L(8); G_BAR; G_WAIT_L(0); G_MMA(0, 0, At, B0); G_BAR; G_SCHED;
;             G_LDB(B1, 0, 1); G_STB(G_SB(0, 0), b2, wK);
;             G_BAR; G_WAIT_L(0); G_MMA(0, 1, At, B1); G_BAR;
;             G_LDA(At, 0, 1); G_STA(G_SA(0, 0), a2, wlda);
;             G_BAR; G_WAIT_L(0); G_MMA(1, 0, At, B0); G_BAR; G_SCHED;
;             G_STB(G_SB(0, 1), b2 + HSTEP(wK), wK);
;             G_WAIT_V(6); G_BAR; G_MMA(1, 1, At, B1); G_BAR;
;             G_LDB(B0, 1, 0); G_SCHED; G_LDA(At, 1, 0); G_STA(G_SA(0, 1), a2 + HSTEP(wlda), wlda);
;             G_WAIT_L(8); G_BAR; G_WAIT_L(0); G_MMA(0, 0, At, B0); G_BAR; G_SCHED;
;             G_LDB(B1, 1, 1); G_STB(G_SB(1, 0), b3, wK);
;             G_BAR; G_WAIT_L(0); G_MMA(0, 1, At, B1); G_BAR;
;             G_LDA(At, 1, 1); G_STA(G_SA(1, 0), a3, wlda);
;             G_BAR; G_WAIT_L(0); G_MMA(1, 0, At, B0); G_BAR; G_SCHED;
;             G_STB(G_SB(1, 1), b3 + HSTEP(wK), wK);
;             G_WAIT_V(6); G_BAR; G_MMA(1, 1, At, B1); G_BAR;
;         }
	s_add_u32 s36, s18, 0x80000
	s_addc_u32 s37, s19, 0
	s_add_i32 s35, s38, s5
	v_lshl_add_u64 v[140:141], s[36:37], 0, v[0:1]
	s_mov_b32 m0, s35
	s_nop 0
	global_load_lds_dwordx4 v[140:141], off
	v_lshl_add_u64 v[140:141], s[36:37], 0, v[130:131]
	s_add_i32 m0, s35, 0x2000
	s_nop 0
	global_load_lds_dwordx4 v[140:141], off
	s_waitcnt vmcnt(6)
	s_barrier
	s_setprio 1
	v_mfma_f32_16x16x32_bf16 v[30:33], v[208:211], v[164:167], v[30:33]
	v_mfma_f32_16x16x32_bf16 v[26:29], v[216:219], v[164:167], v[26:29]
	v_mfma_f32_16x16x32_bf16 v[22:25], v[208:211], v[172:175], v[22:25]
	v_mfma_f32_16x16x32_bf16 v[18:21], v[216:219], v[172:175], v[18:21]
	v_mfma_f32_16x16x32_bf16 v[14:17], v[208:211], v[192:195], v[14:17]
	v_mfma_f32_16x16x32_bf16 v[10:13], v[216:219], v[192:195], v[10:13]
	v_mfma_f32_16x16x32_bf16 v[6:9], v[208:211], v[200:203], v[6:9]
	v_mfma_f32_16x16x32_bf16 v[2:5], v[216:219], v[200:203], v[2:5]
	v_mfma_f32_16x16x32_bf16 v[30:33], v[212:215], v[168:171], v[30:33]
	v_mfma_f32_16x16x32_bf16 v[26:29], v[220:223], v[168:171], v[26:29]
	v_mfma_f32_16x16x32_bf16 v[22:25], v[212:215], v[176:179], v[22:25]
	v_mfma_f32_16x16x32_bf16 v[18:21], v[220:223], v[176:179], v[18:21]
	v_mfma_f32_16x16x32_bf16 v[14:17], v[212:215], v[196:199], v[14:17]
	v_mfma_f32_16x16x32_bf16 v[10:13], v[220:223], v[196:199], v[10:13]
	v_mfma_f32_16x16x32_bf16 v[6:9], v[212:215], v[204:207], v[6:9]
	v_mfma_f32_16x16x32_bf16 v[2:5], v[220:223], v[204:207], v[2:5]
	s_setprio 0
	s_add_i32 s35, 0, 0x18000
	v_add_u32_e32 v160, s35, v147
	s_barrier
	ds_read_b128 v[140:143], v160
	ds_read_b128 v[150:153], v160 offset:1024
	ds_read_b128 v[154:157], v160 offset:2048
	ds_read_b128 v[160:163], v160 offset:3072
	s_add_u32 s20, s20, 0x80000
	s_addc_u32 s21, s21, 0
	s_mov_b32 m0, s24
	v_lshl_add_u64 v[208:209], s[20:21], 0, v[132:133]
	ds_read_b128 v[164:167], v149 offset:32768
	ds_read_b128 v[168:171], v149 offset:33792
	ds_read_b128 v[172:175], v149 offset:34816
	ds_read_b128 v[176:179], v149 offset:35840
	ds_read_b128 v[192:195], v149 offset:36864
	ds_read_b128 v[196:199], v149 offset:37888
	ds_read_b128 v[200:203], v149 offset:38912
	ds_read_b128 v[204:207], v149 offset:39936
	global_load_lds_dwordx4 v[208:209], off
	v_lshl_add_u64 v[208:209], s[20:21], 0, v[134:135]
	s_mov_b32 m0, s25
	s_nop 0
	global_load_lds_dwordx4 v[208:209], off
	s_waitcnt lgkmcnt(8)
	s_barrier
	s_waitcnt lgkmcnt(0)
	s_setprio 1
	s_waitcnt lgkmcnt(0)
	v_mfma_f32_16x16x32_bf16 v[126:129], v[140:143], v[164:167], v[126:129]
	v_mfma_f32_16x16x32_bf16 v[122:125], v[154:157], v[164:167], v[122:125]
	v_mfma_f32_16x16x32_bf16 v[118:121], v[140:143], v[172:175], v[118:121]
	v_mfma_f32_16x16x32_bf16 v[114:117], v[154:157], v[172:175], v[114:117]
	v_mfma_f32_16x16x32_bf16 v[110:113], v[140:143], v[192:195], v[110:113]
	v_mfma_f32_16x16x32_bf16 v[106:109], v[154:157], v[192:195], v[106:109]
	v_mfma_f32_16x16x32_bf16 v[102:105], v[140:143], v[200:203], v[102:105]
	v_mfma_f32_16x16x32_bf16 v[98:101], v[154:157], v[200:203], v[98:101]
	v_mfma_f32_16x16x32_bf16 v[126:129], v[150:153], v[168:171], v[126:129]
	v_mfma_f32_16x16x32_bf16 v[122:125], v[160:163], v[168:171], v[122:125]
	v_mfma_f32_16x16x32_bf16 v[118:121], v[150:153], v[176:179], v[118:121]
	v_mfma_f32_16x16x32_bf16 v[114:117], v[160:163], v[176:179], v[114:117]
	v_mfma_f32_16x16x32_bf16 v[110:113], v[150:153], v[196:199], v[110:113]
	v_mfma_f32_16x16x32_bf16 v[106:109], v[160:163], v[196:199], v[106:109]
	v_mfma_f32_16x16x32_bf16 v[102:105], v[150:153], v[204:207], v[102:105]
	v_mfma_f32_16x16x32_bf16 v[98:101], v[160:163], v[204:207], v[98:101]
	s_setprio 0
	s_barrier
	s_add_i32 s20, 0, 0x1c000
	s_add_i32 s21, s35, s5
	v_add_u32_e32 v220, s20, v147
	v_lshl_add_u64 v[144:145], v[144:145], 0, s[78:79]
	s_mov_b32 m0, s21
	ds_read_b128 v[208:211], v220
	ds_read_b128 v[212:215], v220 offset:1024
	ds_read_b128 v[216:219], v220 offset:2048
	ds_read_b128 v[220:223], v220 offset:3072
	global_load_lds_dwordx4 v[144:145], off
	v_lshl_add_u64 v[144:145], v[224:225], 0, s[78:79]
	s_add_i32 m0, s21, 0x2000
	s_nop 0
	global_load_lds_dwordx4 v[144:145], off
	s_barrier
	s_waitcnt lgkmcnt(0)
	s_setprio 1
	s_waitcnt lgkmcnt(0)
	v_mfma_f32_16x16x32_bf16 v[62:65], v[208:211], v[164:167], v[62:65]
	v_mfma_f32_16x16x32_bf16 v[58:61], v[216:219], v[164:167], v[58:61]
	v_mfma_f32_16x16x32_bf16 v[54:57], v[208:211], v[172:175], v[54:57]
	v_mfma_f32_16x16x32_bf16 v[50:53], v[216:219], v[172:175], v[50:53]
	v_mfma_f32_16x16x32_bf16 v[46:49], v[208:211], v[192:195], v[46:49]
	v_mfma_f32_16x16x32_bf16 v[42:45], v[216:219], v[192:195], v[42:45]
	v_mfma_f32_16x16x32_bf16 v[38:41], v[208:211], v[200:203], v[38:41]
	v_mfma_f32_16x16x32_bf16 v[34:37], v[216:219], v[200:203], v[34:37]
	v_mfma_f32_16x16x32_bf16 v[62:65], v[212:215], v[168:171], v[62:65]
	v_mfma_f32_16x16x32_bf16 v[58:61], v[220:223], v[168:171], v[58:61]
	v_mfma_f32_16x16x32_bf16 v[54:57], v[212:215], v[176:179], v[54:57]
	v_mfma_f32_16x16x32_bf16 v[50:53], v[220:223], v[176:179], v[50:53]
	v_mfma_f32_16x16x32_bf16 v[46:49], v[212:215], v[196:199], v[46:49]
	v_mfma_f32_16x16x32_bf16 v[42:45], v[220:223], v[196:199], v[42:45]
	v_mfma_f32_16x16x32_bf16 v[38:41], v[212:215], v[204:207], v[38:41]
	v_mfma_f32_16x16x32_bf16 v[34:37], v[220:223], v[204:207], v[34:37]
	s_setprio 0
	s_mov_b32 m0, s26
	v_lshl_add_u64 v[144:145], v[230:231], 0, s[78:79]
	s_barrier
	ds_read_b128 v[164:167], v149 offset:49152
	ds_read_b128 v[168:171], v149 offset:50176
	ds_read_b128 v[172:175], v149 offset:51200
	ds_read_b128 v[176:179], v149 offset:52224
	ds_read_b128 v[192:195], v149 offset:53248
	ds_read_b128 v[196:199], v149 offset:54272
	ds_read_b128 v[200:203], v149 offset:55296
	ds_read_b128 v[204:207], v149 offset:56320
	global_load_lds_dwordx4 v[144:145], off
	v_lshl_add_u64 v[144:145], v[232:233], 0, s[78:79]
	s_mov_b32 m0, s27
	s_nop 0
	global_load_lds_dwordx4 v[144:145], off
	s_barrier
; #define G_STA(bufoff, gbase, ld) G_STAGE(bufoff, gbase, RA0, RA1, ld)
; #define G_STB(bufoff, gbase, ld) G_STAGE(bufoff, gbase, RB0, RB1, ld)
; #define G_LDA(dst, b, h) do { _Pragma("unroll") for (int m = 0; m < 4; ++m) _Pragma("unroll") for (int k = 0; k < 2; ++k) dst[m][k] = *(const LAS bf16x8*)(lds + G_SA(b, h) + aoff + m * 2048 + k * 1024); } while (0)
; #define G_LDB(dst, b, h) do { _Pragma("unroll") for (int n = 0; n < 2; ++n) _Pragma("unroll") for (int k = 0; k < 2; ++k) dst[n][k] = *(const LAS bf16x8*)(lds + G_SB(b, h) + boff + n * 2048 + k * 1024); } while (0)
; #define G_MMA(ai, bj, At, Bt) do { __builtin_amdgcn_s_setprio(1); _Pragma("unroll") for (int m = 0; m < 4; ++m) _Pragma("unroll") for (int n = 0; n < 2; ++n) _Pragma("unroll") for (int k = 0; k < 2; ++k) \
;         acc[ai][bj][m][n] = __builtin_amdgcn_mfma_f32_16x16x32_bf16(Bt[n][k], At[m][k], acc[ai][bj][m][n], 0, 0, 0); __builtin_amdgcn_s_setprio(0); } while (0)
; #define G_WAIT_V(n) asm volatile("s_waitcnt vmcnt(" #n ")" ::: "memory")
; #define G_WAIT_L(n) asm volatile("s_waitcnt lgkmcnt(" #n ")" ::: "memory")
; #define G_BAR __builtin_amdgcn_s_barrier()
; #define G_SCHED __builtin_amdgcn_sched_barrier(0)
; template <bool PERM, class SchedT, class Epi>
; __device__ __forceinline__ void gemm_phase(LAS unsigned char* lds, const SchedT& S, const Epi& E) {
;     ...
;             G_WAIT_V(6); G_BAR; G_MMA(1, 1, At, B1); G_BAR;
;             G_LDB(B0, 1, 0); G_SCHED; G_LDA(At, 1, 0); G_STA(G_SA(0, 1), a2 + HSTEP(wlda), wlda);
;             G_WAIT_L(8); G_BAR; G_WAIT_L(0); G_MMA(0, 0, At, B0); G_BAR; G_SCHED;
;             G_LDB(B1, 1, 1); G_STB(G_SB(1, 0), b3, wK);
;             G_BAR; G_WAIT_L(0); G_MMA(0, 1, At, B1); G_BAR;
;             G_LDA(At, 1, 1); G_STA(G_SA(1, 0), a3, wlda);
;             G_BAR; G_WAIT_L(0); G_MMA(1, 0, At, B0); G_BAR; G_SCHED;
;             G_STB(G_SB(1, 1), b3 + HSTEP(wK), wK);
;             G_WAIT_V(6); G_BAR; G_MMA(1, 1, At, B1); G_BAR;
;         }
	s_waitcnt lgkmcnt(0)
	s_setprio 1
	s_waitcnt lgkmcnt(0)
	v_mfma_f32_16x16x32_bf16 v[94:97], v[140:143], v[164:167], v[94:97]
	v_mfma_f32_16x16x32_bf16 v[90:93], v[154:157], v[164:167], v[90:93]
	v_mfma_f32_16x16x32_bf16 v[86:89], v[140:143], v[172:175], v[86:89]
	v_mfma_f32_16x16x32_bf16 v[82:85], v[154:157], v[172:175], v[82:85]
	v_mfma_f32_16x16x32_bf16 v[78:81], v[140:143], v[192:195], v[78:81]
	v_mfma_f32_16x16x32_bf16 v[74:77], v[154:157], v[192:195], v[74:77]
	v_mfma_f32_16x16x32_bf16 v[70:73], v[140:143], v[200:203], v[70:73]
	v_mfma_f32_16x16x32_bf16 v[66:69], v[154:157], v[200:203], v[66:69]
	v_mfma_f32_16x16x32_bf16 v[94:97], v[150:153], v[168:171], v[94:97]
	v_mfma_f32_16x16x32_bf16 v[90:93], v[160:163], v[168:171], v[90:93]
	v_mfma_f32_16x16x32_bf16 v[86:89], v[150:153], v[176:179], v[86:89]
	v_mfma_f32_16x16x32_bf16 v[82:85], v[160:163], v[176:179], v[82:85]
	v_mfma_f32_16x16x32_bf16 v[78:81], v[150:153], v[196:199], v[78:81]
	v_mfma_f32_16x16x32_bf16 v[74:77], v[160:163], v[196:199], v[74:77]
	v_mfma_f32_16x16x32_bf16 v[70:73], v[150:153], v[204:207], v[70:73]
	v_mfma_f32_16x16x32_bf16 v[66:69], v[160:163], v[204:207], v[66:69]
	s_setprio 0
	s_barrier
	s_add_u32 s18, s18, 0x80080
	s_addc_u32 s19, s19, 0
	s_add_i32 s20, s20, s5
	v_lshl_add_u64 v[140:141], s[18:19], 0, v[0:1]
	s_mov_b32 m0, s20
	s_nop 0
	global_load_lds_dwordx4 v[140:141], off
	v_lshl_add_u64 v[140:141], s[18:19], 0, v[130:131]
	s_add_i32 m0, s20, 0x2000
	s_nop 0
	global_load_lds_dwordx4 v[140:141], off
	s_waitcnt vmcnt(6)
	s_barrier
	s_setprio 1
	v_mfma_f32_16x16x32_bf16 v[30:33], v[208:211], v[164:167], v[30:33]
	v_mfma_f32_16x16x32_bf16 v[26:29], v[216:219], v[164:167], v[26:29]
	v_mfma_f32_16x16x32_bf16 v[22:25], v[208:211], v[172:175], v[22:25]
	v_mfma_f32_16x16x32_bf16 v[18:21], v[216:219], v[172:175], v[18:21]
	v_mfma_f32_16x16x32_bf16 v[14:17], v[208:211], v[192:195], v[14:17]
	v_mfma_f32_16x16x32_bf16 v[10:13], v[216:219], v[192:195], v[10:13]
	v_mfma_f32_16x16x32_bf16 v[6:9], v[208:211], v[200:203], v[6:9]
	v_mfma_f32_16x16x32_bf16 v[2:5], v[216:219], v[200:203], v[2:5]
	v_mfma_f32_16x16x32_bf16 v[30:33], v[212:215], v[168:171], v[30:33]
	v_mfma_f32_16x16x32_bf16 v[26:29], v[220:223], v[168:171], v[26:29]
	v_mfma_f32_16x16x32_bf16 v[22:25], v[212:215], v[176:179], v[22:25]
	v_mfma_f32_16x16x32_bf16 v[18:21], v[220:223], v[176:179], v[18:21]
	v_mfma_f32_16x16x32_bf16 v[14:17], v[212:215], v[196:199], v[14:17]
	v_mfma_f32_16x16x32_bf16 v[10:13], v[220:223], v[196:199], v[10:13]
	v_mfma_f32_16x16x32_bf16 v[6:9], v[212:215], v[204:207], v[6:9]
	v_mfma_f32_16x16x32_bf16 v[2:5], v[220:223], v[204:207], v[2:5]
	s_setprio 0
	s_add_i32 s34, s34, 2
	s_add_u32 s8, s8, 0x100
	s_addc_u32 s9, s9, 0
	s_add_u32 s11, s11, 0x100
	s_addc_u32 s13, s13, 0
	s_cmp_gt_u32 s34, 29
	s_barrier
	s_cbranch_scc0 .LBB0_249
	s_cmpk_gt_u32 s4, 0xff
	s_cbranch_scc1 .Lus_g1a
	s_barrier
; __device__ __forceinline__ unsigned cvt_pk(float lo, float hi) { unsigned r; asm volatile("v_cvt_pk_bf16_f32 %0, %1, %2" : "=v"(r) : "v"(lo), "v"(hi)); return r; }
; #define GAS __attribute__((address_space(1)))
;     __device__ __forceinline__ void operator()(const f32x4 (&acc)[2][2][4][2], const UnitD& u, int wr, int wc, int fr, int fq) const {
;         const int row0 = u.pm * BM + wr * 64 + fr, col0 = u.pn * BM + wc * 32 + 8 * fq;
;         GAS bf16_t* C = (GAS bf16_t*)(unsigned long long)u.C;
; #pragma unroll
;         for (int bj = 0; bj < 2; ++bj) {
;             const bool gate = (u.pn * BM + bj * HALF + wc * 32) >= C_G;
; #pragma unroll
;             for (int ai = 0; ai < 2; ++ai)
; #pragma unroll
;                 for (int m = 0; m < 4; ++m) { GAS bf16_t* rowp = C + (size_t)(row0 + ai * HALF + m * 16) * NP;
;                     const f32x4 v0 = acc[ai][bj][m][0], v1 = acc[ai][bj][m][1];
;                     if (!gate) { u32x4 w; w.x = cvt_pk(v0[0], v0[1]); w.y = cvt_pk(v0[2], v0[3]); w.z = cvt_pk(v1[0], v1[1]); w.w = cvt_pk(v1[2], v1[3]);
;                         *(GAS u32x4*)(rowp + col0 + bj * HALF) = w; }
.Lus_g1a:
	s_cmpk_lt_u32 s31, 0x28
	s_cbranch_scc0 .Lg1_slow
	v_readlane_b32 s8, v249, 2
	v_readlane_b32 s9, v249, 3
	s_lshl_b32 s11, s31, 8
	v_lshrrev_b32_e32 v253, 16, v250
	v_and_b32_e32 v254, 0xff, v250
	v_lshl_add_u32 v150, s30, 8, v253
	v_or_b32_e32 v144, s11, v254
	v_ashrrev_i32_e32 v145, 31, v144
	v_lshl_add_u64 v[140:141], v[144:145], 1, s[8:9]
	v_cvt_pk_bf16_f32 v126, v126, v127
	v_cvt_pk_bf16_f32 v127, v128, v129
	v_cvt_pk_bf16_f32 v128, v122, v123
	v_cvt_pk_bf16_f32 v129, v124, v125
	ds_write_b128 v251, v[126:129]
	ds_read_b128 v[126:129], v252
	v_cvt_pk_bf16_f32 v62, v62, v63
	v_cvt_pk_bf16_f32 v63, v64, v65
	v_cvt_pk_bf16_f32 v64, v58, v59
	v_cvt_pk_bf16_f32 v65, v60, v61
	ds_write_b128 v251, v[62:65]
	ds_read_b128 v[62:65], v252
	v_cvt_pk_bf16_f32 v118, v118, v119
	v_cvt_pk_bf16_f32 v119, v120, v121
	v_cvt_pk_bf16_f32 v120, v114, v115
	v_cvt_pk_bf16_f32 v121, v116, v117
	ds_write_b128 v251, v[118:121]
	ds_read_b128 v[118:121], v252
	v_mad_i64_i32 v[254:255], vcc, v150, s3, 0
	v_lshl_add_u64 v[254:255], v[254:255], 0, v[140:141]
	s_waitcnt lgkmcnt(4)
	global_store_dwordx4 v[254:255], v[126:129], off
	v_cvt_pk_bf16_f32 v54, v54, v55
	v_cvt_pk_bf16_f32 v55, v56, v57
	v_cvt_pk_bf16_f32 v56, v50, v51
	v_cvt_pk_bf16_f32 v57, v52, v53
	ds_write_b128 v251, v[54:57]
	ds_read_b128 v[54:57], v252
	s_waitcnt lgkmcnt(4)
	global_store_dwordx4 v[254:255], v[62:65], off offset:256
	v_cvt_pk_bf16_f32 v110, v110, v111
	v_cvt_pk_bf16_f32 v111, v112, v113
	v_cvt_pk_bf16_f32 v112, v106, v107
	v_cvt_pk_bf16_f32 v113, v108, v109
	ds_write_b128 v251, v[110:113]
	ds_read_b128 v[110:113], v252
	v_add_u32_e32 v253, 16, v150
	v_mad_i64_i32 v[254:255], vcc, v253, s3, 0
	v_lshl_add_u64 v[254:255], v[254:255], 0, v[140:141]
	s_waitcnt lgkmcnt(4)
	global_store_dwordx4 v[254:255], v[118:121], off
	v_cvt_pk_bf16_f32 v46, v46, v47
	v_cvt_pk_bf16_f32 v47, v48, v49
	v_cvt_pk_bf16_f32 v48, v42, v43
	v_cvt_pk_bf16_f32 v49, v44, v45
	ds_write_b128 v251, v[46:49]
	ds_read_b128 v[46:49], v252
	s_waitcnt lgkmcnt(4)
	global_store_dwordx4 v[254:255], v[54:57], off offset:256
	v_cvt_pk_bf16_f32 v102, v102, v103
	v_cvt_pk_bf16_f32 v103, v104, v105
	v_cvt_pk_bf16_f32 v104, v98, v99
	v_cvt_pk_bf16_f32 v105, v100, v101
	ds_write_b128 v251, v[102:105]
	ds_read_b128 v[102:105], v252
	v_add_u32_e32 v253, 32, v150
	v_mad_i64_i32 v[254:255], vcc, v253, s3, 0
	v_lshl_add_u64 v[254:255], v[254:255], 0, v[140:141]
	s_waitcnt lgkmcnt(4)
	global_store_dwordx4 v[254:255], v[110:113], off
	v_cvt_pk_bf16_f32 v38, v38, v39
	v_cvt_pk_bf16_f32 v39, v40, v41
	v_cvt_pk_bf16_f32 v40, v34, v35
	v_cvt_pk_bf16_f32 v41, v36, v37
	ds_write_b128 v251, v[38:41]
	ds_read_b128 v[38:41], v252
	s_waitcnt lgkmcnt(4)
	global_store_dwordx4 v[254:255], v[46:49], off offset:256
	v_cvt_pk_bf16_f32 v94, v94, v95
	v_cvt_pk_bf16_f32 v95, v96, v97
	v_cvt_pk_bf16_f32 v96, v90, v91
	v_cvt_pk_bf16_f32 v97, v92, v93
	ds_write_b128 v251, v[94:97]
	ds_read_b128 v[94:97], v252
	v_add_u32_e32 v253, 48, v150
	v_mad_i64_i32 v[254:255], vcc, v253, s3, 0
	v_lshl_add_u64 v[254:255], v[254:255], 0, v[140:141]
	s_waitcnt lgkmcnt(4)
	global_store_dwordx4 v[254:255], v[102:105], off
	v_cvt_pk_bf16_f32 v30, v30, v31
	v_cvt_pk_bf16_f32 v31, v32, v33
	v_cvt_pk_bf16_f32 v32, v26, v27
	v_cvt_pk_bf16_f32 v33, v28, v29
	ds_write_b128 v251, v[30:33]
	ds_read_b128 v[30:33], v252
	s_waitcnt lgkmcnt(4)
	global_store_dwordx4 v[254:255], v[38:41], off offset:256
	v_cvt_pk_bf16_f32 v86, v86, v87
	v_cvt_pk_bf16_f32 v87, v88, v89
	v_cvt_pk_bf16_f32 v88, v82, v83
	v_cvt_pk_bf16_f32 v89, v84, v85
	ds_write_b128 v251, v[86:89]
	ds_read_b128 v[86:89], v252
	v_add_u32_e32 v253, 128, v150
	v_mad_i64_i32 v[254:255], vcc, v253, s3, 0
	v_lshl_add_u64 v[254:255], v[254:255], 0, v[140:141]
	s_waitcnt lgkmcnt(4)
	global_store_dwordx4 v[254:255], v[94:97], off
	v_cvt_pk_bf16_f32 v22, v22, v23
	v_cvt_pk_bf16_f32 v23, v24, v25
	v_cvt_pk_bf16_f32 v24, v18, v19
	v_cvt_pk_bf16_f32 v25, v20, v21
	ds_write_b128 v251, v[22:25]
	ds_read_b128 v[22:25], v252
	s_waitcnt lgkmcnt(4)
	global_store_dwordx4 v[254:255], v[30:33], off offset:256
	v_cvt_pk_bf16_f32 v78, v78, v79
	v_cvt_pk_bf16_f32 v79, v80, v81
	v_cvt_pk_bf16_f32 v80, v74, v75
	v_cvt_pk_bf16_f32 v81, v76, v77
	ds_write_b128 v251, v[78:81]
	ds_read_b128 v[78:81], v252
	v_add_u32_e32 v253, 144, v150
	v_mad_i64_i32 v[254:255], vcc, v253, s3, 0
	v_lshl_add_u64 v[254:255], v[254:255], 0, v[140:141]
	s_waitcnt lgkmcnt(4)
	global_store_dwordx4 v[254:255], v[86:89], off
	v_cvt_pk_bf16_f32 v14, v14, v15
	v_cvt_pk_bf16_f32 v15, v16, v17
	v_cvt_pk_bf16_f32 v16, v10, v11
	v_cvt_pk_bf16_f32 v17, v12, v13
	ds_write_b128 v251, v[14:17]
	ds_read_b128 v[14:17], v252
	s_waitcnt lgkmcnt(4)
	global_store_dwordx4 v[254:255], v[22:25], off offset:256
	v_cvt_pk_bf16_f32 v70, v70, v71
	v_cvt_pk_bf16_f32 v71, v72, v73
	v_cvt_pk_bf16_f32 v72, v66, v67
	v_cvt_pk_bf16_f32 v73, v68, v69
	ds_write_b128 v251, v[70:73]
	ds_read_b128 v[70:73], v252
	v_add_u32_e32 v253, 160, v150
	v_mad_i64_i32 v[254:255], vcc, v253, s3, 0
	v_lshl_add_u64 v[254:255], v[254:255], 0, v[140:141]
	s_waitcnt lgkmcnt(4)
	global_store_dwordx4 v[254:255], v[78:81], off
	v_cvt_pk_bf16_f32 v6, v6, v7
	v_cvt_pk_bf16_f32 v7, v8, v9
	v_cvt_pk_bf16_f32 v8, v2, v3
	v_cvt_pk_bf16_f32 v9, v4, v5
	ds_write_b128 v251, v[6:9]
	ds_read_b128 v[6:9], v252
	s_waitcnt lgkmcnt(4)
	global_store_dwordx4 v[254:255], v[14:17], off offset:256
	v_add_u32_e32 v253, 176, v150
	v_mad_i64_i32 v[254:255], vcc, v253, s3, 0
	v_lshl_add_u64 v[254:255], v[254:255], 0, v[140:141]
	s_waitcnt lgkmcnt(2)
	global_store_dwordx4 v[254:255], v[70:73], off
	s_waitcnt lgkmcnt(0)
	global_store_dwordx4 v[254:255], v[6:9], off offset:256
	s_branch .LBB0_241

; #define G_STA(bufoff, gbase, ld) G_STAGE(bufoff, gbase, RA0, RA1, ld)
; #define G_STB(bufoff, gbase, ld) G_STAGE(bufoff, gbase, RB0, RB1, ld)
; #define G_LDA(dst, b, h) do { _Pragma("unroll") for (int m = 0; m < 4; ++m) _Pragma("unroll") for (int k = 0; k < 2; ++k) dst[m][k] = *(const LAS bf16x8*)(lds + G_SA(b, h) + aoff + m * 2048 + k * 1024); } while (0)
; #define G_LDB(dst, b, h) do { _Pragma("unroll") for (int n = 0; n < 2; ++n) _Pragma("unroll") for (int k = 0; k < 2; ++k) dst[n][k] = *(const LAS bf16x8*)(lds + G_SB(b, h) + boff + n * 2048 + k * 1024); } while (0)
; #define G_WAIT_V(n) asm volatile("s_waitcnt vmcnt(" #n ")" ::: "memory")
; #define G_BAR __builtin_amdgcn_s_barrier()
; template <bool PERM, class SchedT, class Epi>
; __device__ __forceinline__ void gemm_phase(LAS unsigned char* lds, const SchedT& S, const Epi& E) {
;     ...
;         for (int t = 0; t < nt; t += 2) {
;             const bool last = (t == nt - 2);
;             const char* a1 = cA + (size_t)(t + 1) * kstep;
;             const char* a2 = last ? nA : cA + (size_t)(t + 2) * kstep; const char* b2 = last ? nB : cB + (size_t)(t + 2) * kstep;
;             const char* a3 = a2 + kstep; const char* b3 = b2 + kstep;
;             const int wlda = last ? nlda : lda, wK = last ? nK : K;
;             G_LDB(B0, 0, 0); G_SCHED; G_LDA(At, 0, 0); G_STA(G_SA(1, 1), a1 + HSTEP(lda), lda);
;             G_WAIT_L(8); G_BAR; G_WAIT_L(0); G_MMA(0, 0, At, B0); G_BAR; G_SCHED;
;             G_LDB(B1, 0, 1); G_STB(G_SB(0, 0), b2, wK);
;             G_BAR; G_WAIT_L(0); G_MMA(0, 1, At, B1); G_BAR;
;             G_LDA(At, 0, 1); G_STA(G_SA(0, 0), a2, wlda);
;             G_BAR; G_WAIT_L(0); G_MMA(1, 0, At, B0); G_BAR; G_SCHED;
;             G_STB(G_SB(0, 1), b2 + HSTEP(wK), wK);
;             G_WAIT_V(6); G_BAR; G_MMA(1, 1, At, B1); G_BAR;
;             G_LDB(B0, 1, 0); G_SCHED; G_LDA(At, 1, 0); G_STA(G_SA(0, 1), a2 + HSTEP(wlda), wlda);
;             G_WAIT_L(8); G_BAR; G_WAIT_L(0); G_MMA(0, 0, At, B0); G_BAR; G_SCHED;
;             G_LDB(B1, 1, 1); G_STB(G_SB(1, 0), b3, wK);
;             G_BAR; G_WAIT_L(0); G_MMA(0, 1, At, B1); G_BAR;
;             G_LDA(At, 1, 1); G_STA(G_SA(1, 0), a3, wlda);
;             G_BAR; G_WAIT_L(0); G_MMA(1, 0, At, B0); G_BAR; G_SCHED;
;             G_STB(G_SB(1, 1), b3 + HSTEP(wK), wK);
;             G_WAIT_V(6); G_BAR; G_MMA(1, 1, At, B1); G_BAR;
;         }
.LBB0_366:
	s_add_u32 s26, s24, 0xfff80080
	s_addc_u32 s27, s25, -1
	s_add_i32 s42, 0, 0x10000
	v_add_u32_e32 v148, s42, v155
	ds_read_b128 v[136:139], v148
	ds_read_b128 v[140:143], v148 offset:1024
	ds_read_b128 v[144:147], v148 offset:2048
	ds_read_b128 v[148:151], v148 offset:3072
	s_cmp_eq_u32 s41, 28
	s_cselect_b32 s29, s21, s27
	s_cselect_b32 s28, s20, s26
	s_cselect_b32 s27, s23, s19
	s_cselect_b32 s26, s22, s17
	v_lshl_add_u64 v[152:153], s[24:25], 0, v[132:133]
	s_add_i32 m0, s30, 0xc000
	ds_read_b128 v[160:163], v157
	ds_read_b128 v[164:167], v157 offset:1024
	ds_read_b128 v[168:171], v157 offset:2048
	ds_read_b128 v[172:175], v157 offset:3072
	ds_read_b128 v[176:179], v157 offset:4096
	ds_read_b128 v[192:195], v157 offset:5120
	ds_read_b128 v[196:199], v157 offset:6144
	ds_read_b128 v[200:203], v157 offset:7168
	global_load_lds_dwordx4 v[152:153], off
	v_lshl_add_u64 v[152:153], s[24:25], 0, v[134:135]
	s_add_i32 m0, s30, 0xe000
	s_nop 0
	global_load_lds_dwordx4 v[152:153], off
	s_waitcnt lgkmcnt(8)
	s_barrier
	s_waitcnt lgkmcnt(0)
	s_setprio 1
	s_waitcnt lgkmcnt(0)
	v_mfma_f32_16x16x32_bf16 v[66:69], v[136:139], v[160:163], v[66:69]
	v_mfma_f32_16x16x32_bf16 v[70:73], v[144:147], v[160:163], v[70:73]
	v_mfma_f32_16x16x32_bf16 v[82:85], v[136:139], v[168:171], v[82:85]
	v_mfma_f32_16x16x32_bf16 v[110:113], v[144:147], v[168:171], v[110:113]
	v_mfma_f32_16x16x32_bf16 v[126:129], v[136:139], v[176:179], v[126:129]
	v_mfma_f32_16x16x32_bf16 v[118:121], v[144:147], v[176:179], v[118:121]
	v_mfma_f32_16x16x32_bf16 v[122:125], v[136:139], v[196:199], v[122:125]
	v_mfma_f32_16x16x32_bf16 v[114:117], v[144:147], v[196:199], v[114:117]
	v_mfma_f32_16x16x32_bf16 v[66:69], v[140:143], v[164:167], v[66:69]
	v_mfma_f32_16x16x32_bf16 v[70:73], v[148:151], v[164:167], v[70:73]
	v_mfma_f32_16x16x32_bf16 v[82:85], v[140:143], v[172:175], v[82:85]
	v_mfma_f32_16x16x32_bf16 v[110:113], v[148:151], v[172:175], v[110:113]
	v_mfma_f32_16x16x32_bf16 v[126:129], v[140:143], v[192:195], v[126:129]
	v_mfma_f32_16x16x32_bf16 v[118:121], v[148:151], v[192:195], v[118:121]
	v_mfma_f32_16x16x32_bf16 v[122:125], v[140:143], v[200:203], v[122:125]
	v_mfma_f32_16x16x32_bf16 v[114:117], v[148:151], v[200:203], v[114:117]
	s_setprio 0
	s_barrier
	s_add_i32 s44, 0, 0x14000
	v_add_u32_e32 v152, s44, v155
	s_add_i32 s42, s42, s5
	ds_read_b128 v[204:207], v152
	ds_read_b128 v[208:211], v152 offset:1024
	ds_read_b128 v[212:215], v152 offset:2048
	ds_read_b128 v[216:219], v152 offset:3072
	v_lshl_add_u64 v[152:153], s[26:27], 0, v[0:1]
	s_mov_b32 m0, s42
	v_lshl_add_u64 v[220:221], s[26:27], 0, v[130:131]
	global_load_lds_dwordx4 v[152:153], off
	s_add_i32 m0, s42, 0x2000
	s_nop 0
	global_load_lds_dwordx4 v[220:221], off
	s_barrier
	s_waitcnt lgkmcnt(0)
	s_setprio 1
	s_waitcnt lgkmcnt(0)
	v_mfma_f32_16x16x32_bf16 v[74:77], v[204:207], v[160:163], v[74:77]
	v_mfma_f32_16x16x32_bf16 v[78:81], v[212:215], v[160:163], v[78:81]
	v_mfma_f32_16x16x32_bf16 v[98:101], v[204:207], v[168:171], v[98:101]
	v_mfma_f32_16x16x32_bf16 v[86:89], v[212:215], v[168:171], v[86:89]
	v_mfma_f32_16x16x32_bf16 v[106:109], v[204:207], v[176:179], v[106:109]
	v_mfma_f32_16x16x32_bf16 v[94:97], v[212:215], v[176:179], v[94:97]
	v_mfma_f32_16x16x32_bf16 v[102:105], v[204:207], v[196:199], v[102:105]
	v_mfma_f32_16x16x32_bf16 v[90:93], v[212:215], v[196:199], v[90:93]
	v_mfma_f32_16x16x32_bf16 v[74:77], v[208:211], v[164:167], v[74:77]
	v_mfma_f32_16x16x32_bf16 v[78:81], v[216:219], v[164:167], v[78:81]
	v_mfma_f32_16x16x32_bf16 v[98:101], v[208:211], v[172:175], v[98:101]
	v_mfma_f32_16x16x32_bf16 v[86:89], v[216:219], v[172:175], v[86:89]
	v_mfma_f32_16x16x32_bf16 v[106:109], v[208:211], v[192:195], v[106:109]
	v_mfma_f32_16x16x32_bf16 v[94:97], v[216:219], v[192:195], v[94:97]
	v_mfma_f32_16x16x32_bf16 v[102:105], v[208:211], v[200:203], v[102:105]
	v_mfma_f32_16x16x32_bf16 v[90:93], v[216:219], v[200:203], v[90:93]
	s_setprio 0
	s_mov_b32 m0, s30
	v_lshl_add_u64 v[222:223], s[28:29], 0, v[0:1]
	s_barrier
	ds_read_b128 v[160:163], v157 offset:16384
	ds_read_b128 v[164:167], v157 offset:17408
	ds_read_b128 v[168:171], v157 offset:18432
	ds_read_b128 v[172:175], v157 offset:19456
	ds_read_b128 v[176:179], v157 offset:20480
	ds_read_b128 v[192:195], v157 offset:21504
	ds_read_b128 v[196:199], v157 offset:22528
	ds_read_b128 v[200:203], v157 offset:23552
	global_load_lds_dwordx4 v[222:223], off
	v_lshl_add_u64 v[224:225], s[28:29], 0, v[130:131]
	s_mov_b32 m0, s31
	s_nop 0
	global_load_lds_dwordx4 v[224:225], off
	s_barrier
	s_waitcnt lgkmcnt(0)
	s_setprio 1
	s_waitcnt lgkmcnt(0)
	v_mfma_f32_16x16x32_bf16 v[62:65], v[136:139], v[160:163], v[62:65]
	v_mfma_f32_16x16x32_bf16 v[58:61], v[144:147], v[160:163], v[58:61]
	v_mfma_f32_16x16x32_bf16 v[46:49], v[136:139], v[168:171], v[46:49]
	v_mfma_f32_16x16x32_bf16 v[42:45], v[144:147], v[168:171], v[42:45]
	v_mfma_f32_16x16x32_bf16 v[30:33], v[136:139], v[176:179], v[30:33]
	v_mfma_f32_16x16x32_bf16 v[26:29], v[144:147], v[176:179], v[26:29]
	v_mfma_f32_16x16x32_bf16 v[14:17], v[136:139], v[196:199], v[14:17]
	v_mfma_f32_16x16x32_bf16 v[10:13], v[144:147], v[196:199], v[10:13]
	v_mfma_f32_16x16x32_bf16 v[62:65], v[140:143], v[164:167], v[62:65]
	v_mfma_f32_16x16x32_bf16 v[58:61], v[148:151], v[164:167], v[58:61]
	v_mfma_f32_16x16x32_bf16 v[46:49], v[140:143], v[172:175], v[46:49]
	v_mfma_f32_16x16x32_bf16 v[42:45], v[148:151], v[172:175], v[42:45]
	v_mfma_f32_16x16x32_bf16 v[30:33], v[140:143], v[192:195], v[30:33]
	v_mfma_f32_16x16x32_bf16 v[26:29], v[148:151], v[192:195], v[26:29]
	v_mfma_f32_16x16x32_bf16 v[14:17], v[140:143], v[200:203], v[14:17]
	v_mfma_f32_16x16x32_bf16 v[10:13], v[148:151], v[200:203], v[10:13]
	s_setprio 0
	s_barrier
; #define G_STA(bufoff, gbase, ld) G_STAGE(bufoff, gbase, RA0, RA1, ld)
; #define G_STB(bufoff, gbase, ld) G_STAGE(bufoff, gbase, RB0, RB1, ld)
; #define G_LDA(dst, b, h) do { _Pragma("unroll") for (int m = 0; m < 4; ++m) _Pragma("unroll") for (int k = 0; k < 2; ++k) dst[m][k] = *(const LAS bf16x8*)(lds + G_SA(b, h) + aoff + m * 2048 + k * 1024); } while (0)
; #define G_LDB(dst, b, h) do { _Pragma("unroll") for (int n = 0; n < 2; ++n) _Pragma("unroll") for (int k = 0; k < 2; ++k) dst[n][k] = *(const LAS bf16x8*)(lds + G_SB(b, h) + boff + n * 2048 + k * 1024); } while (0)
; #define G_MMA(ai, bj, At, Bt) do { __builtin_amdgcn_s_setprio(1); _Pragma("unroll") for (int m = 0; m < 4; ++m) _Pragma("unroll") for (int n = 0; n < 2; ++n) _Pragma("unroll") for (int k = 0; k < 2; ++k) \
;         acc[ai][bj][m][n] = __builtin_amdgcn_mfma_f32_16x16x32_bf16(Bt[n][k], At[m][k], acc[ai][bj][m][n], 0, 0, 0); __builtin_amdgcn_s_setprio(0); } while (0)
; #define G_WAIT_V(n) asm volatile("s_waitcnt vmcnt(" #n ")" ::: "memory")
; #define G_WAIT_L(n) asm volatile("s_waitcnt lgkmcnt(" #n ")" ::: "memory")
; template <bool PERM, class SchedT, class Epi>
; __device__ __forceinline__ void gemm_phase(LAS unsigned char* lds, const SchedT& S, const Epi& E) {
;     ...
;             G_LDB(B0, 0, 0); G_SCHED; G_LDA(At, 0, 0); G_STA(G_SA(1, 1), a1 + HSTEP(lda), lda);
;             G_WAIT_L(8); G_BAR; G_WAIT_L(0); G_MMA(0, 0, At, B0); G_BAR; G_SCHED;
;             G_LDB(B1, 0, 1); G_STB(G_SB(0, 0), b2, wK);
;             G_BAR; G_WAIT_L(0); G_MMA(0, 1, At, B1); G_BAR;
;             G_LDA(At, 0, 1); G_STA(G_SA(0, 0), a2, wlda);
;             G_BAR; G_WAIT_L(0); G_MMA(1, 0, At, B0); G_BAR; G_SCHED;
;             G_STB(G_SB(0, 1), b2 + HSTEP(wK), wK);
;             G_WAIT_V(6); G_BAR; G_MMA(1, 1, At, B1); G_BAR;
;             G_LDB(B0, 1, 0); G_SCHED; G_LDA(At, 1, 0); G_STA(G_SA(0, 1), a2 + HSTEP(wlda), wlda);
;             G_WAIT_L(8); G_BAR; G_WAIT_L(0); G_MMA(0, 0, At, B0); G_BAR; G_SCHED;
;             G_LDB(B1, 1, 1); G_STB(G_SB(1, 0), b3, wK);
;             G_BAR; G_WAIT_L(0); G_MMA(0, 1, At, B1); G_BAR;
;             G_LDA(At, 1, 1); G_STA(G_SA(1, 0), a3, wlda);
;             G_BAR; G_WAIT_L(0); G_MMA(1, 0, At, B0); G_BAR; G_SCHED;
;             G_STB(G_SB(1, 1), b3 + HSTEP(wK), wK);
;             G_WAIT_V(6); G_BAR; G_MMA(1, 1, At, B1); G_BAR;
;         }
	s_add_u32 s42, s26, 0x80000
	s_addc_u32 s43, s27, 0
	s_add_i32 s44, s44, s5
	v_lshl_add_u64 v[136:137], s[42:43], 0, v[0:1]
	s_mov_b32 m0, s44
	s_nop 0
	global_load_lds_dwordx4 v[136:137], off
	v_lshl_add_u64 v[136:137], s[42:43], 0, v[130:131]
	s_add_i32 m0, s44, 0x2000
	s_nop 0
	global_load_lds_dwordx4 v[136:137], off
	s_waitcnt vmcnt(6)
	s_barrier
	s_setprio 1
	v_mfma_f32_16x16x32_bf16 v[54:57], v[204:207], v[160:163], v[54:57]
	v_mfma_f32_16x16x32_bf16 v[50:53], v[212:215], v[160:163], v[50:53]
	v_mfma_f32_16x16x32_bf16 v[38:41], v[204:207], v[168:171], v[38:41]
	v_mfma_f32_16x16x32_bf16 v[34:37], v[212:215], v[168:171], v[34:37]
	v_mfma_f32_16x16x32_bf16 v[22:25], v[204:207], v[176:179], v[22:25]
	v_mfma_f32_16x16x32_bf16 v[18:21], v[212:215], v[176:179], v[18:21]
	v_mfma_f32_16x16x32_bf16 v[6:9], v[204:207], v[196:199], v[6:9]
	v_mfma_f32_16x16x32_bf16 v[2:5], v[212:215], v[196:199], v[2:5]
	v_mfma_f32_16x16x32_bf16 v[54:57], v[208:211], v[164:167], v[54:57]
	v_mfma_f32_16x16x32_bf16 v[50:53], v[216:219], v[164:167], v[50:53]
	v_mfma_f32_16x16x32_bf16 v[38:41], v[208:211], v[172:175], v[38:41]
	v_mfma_f32_16x16x32_bf16 v[34:37], v[216:219], v[172:175], v[34:37]
	v_mfma_f32_16x16x32_bf16 v[22:25], v[208:211], v[192:195], v[22:25]
	v_mfma_f32_16x16x32_bf16 v[18:21], v[216:219], v[192:195], v[18:21]
	v_mfma_f32_16x16x32_bf16 v[6:9], v[208:211], v[200:203], v[6:9]
	v_mfma_f32_16x16x32_bf16 v[2:5], v[216:219], v[200:203], v[2:5]
	s_setprio 0
	s_add_i32 s42, 0, 0x18000
	v_add_u32_e32 v148, s42, v155
	s_barrier
	ds_read_b128 v[136:139], v148
	ds_read_b128 v[140:143], v148 offset:1024
	ds_read_b128 v[144:147], v148 offset:2048
	ds_read_b128 v[148:151], v148 offset:3072
	s_add_u32 s28, s28, 0x80000
	s_addc_u32 s29, s29, 0
	s_mov_b32 m0, s34
	v_lshl_add_u64 v[204:205], s[28:29], 0, v[0:1]
	ds_read_b128 v[160:163], v157 offset:32768
	ds_read_b128 v[164:167], v157 offset:33792
	ds_read_b128 v[168:171], v157 offset:34816
	ds_read_b128 v[172:175], v157 offset:35840
	ds_read_b128 v[176:179], v157 offset:36864
	ds_read_b128 v[192:195], v157 offset:37888
	ds_read_b128 v[196:199], v157 offset:38912
	ds_read_b128 v[200:203], v157 offset:39936
	global_load_lds_dwordx4 v[204:205], off
	v_lshl_add_u64 v[204:205], s[28:29], 0, v[130:131]
	s_mov_b32 m0, s35
	s_nop 0
	global_load_lds_dwordx4 v[204:205], off
	s_waitcnt lgkmcnt(8)
	s_barrier
	s_waitcnt lgkmcnt(0)
	s_setprio 1
	s_waitcnt lgkmcnt(0)
	v_mfma_f32_16x16x32_bf16 v[66:69], v[136:139], v[160:163], v[66:69]
	v_mfma_f32_16x16x32_bf16 v[70:73], v[144:147], v[160:163], v[70:73]
	v_mfma_f32_16x16x32_bf16 v[82:85], v[136:139], v[168:171], v[82:85]
	v_mfma_f32_16x16x32_bf16 v[110:113], v[144:147], v[168:171], v[110:113]
	v_mfma_f32_16x16x32_bf16 v[126:129], v[136:139], v[176:179], v[126:129]
	v_mfma_f32_16x16x32_bf16 v[118:121], v[144:147], v[176:179], v[118:121]
	v_mfma_f32_16x16x32_bf16 v[122:125], v[136:139], v[196:199], v[122:125]
	v_mfma_f32_16x16x32_bf16 v[114:117], v[144:147], v[196:199], v[114:117]
	v_mfma_f32_16x16x32_bf16 v[66:69], v[140:143], v[164:167], v[66:69]
	v_mfma_f32_16x16x32_bf16 v[70:73], v[148:151], v[164:167], v[70:73]
	v_mfma_f32_16x16x32_bf16 v[82:85], v[140:143], v[172:175], v[82:85]
	v_mfma_f32_16x16x32_bf16 v[110:113], v[148:151], v[172:175], v[110:113]
	v_mfma_f32_16x16x32_bf16 v[126:129], v[140:143], v[192:195], v[126:129]
	v_mfma_f32_16x16x32_bf16 v[118:121], v[148:151], v[192:195], v[118:121]
	v_mfma_f32_16x16x32_bf16 v[122:125], v[140:143], v[200:203], v[122:125]
	v_mfma_f32_16x16x32_bf16 v[114:117], v[148:151], v[200:203], v[114:117]
	s_setprio 0
	s_barrier
	s_add_i32 s28, 0, 0x1c000
	s_add_i32 s29, s42, s5
	v_add_u32_e32 v216, s28, v155
	v_lshl_add_u64 v[152:153], v[152:153], 0, s[78:79]
	s_mov_b32 m0, s29
	ds_read_b128 v[204:207], v216
	ds_read_b128 v[208:211], v216 offset:1024
	ds_read_b128 v[212:215], v216 offset:2048
	ds_read_b128 v[216:219], v216 offset:3072
	global_load_lds_dwordx4 v[152:153], off
	v_lshl_add_u64 v[152:153], v[220:221], 0, s[78:79]
	s_add_i32 m0, s29, 0x2000
	s_nop 0
	global_load_lds_dwordx4 v[152:153], off
	s_barrier
	s_waitcnt lgkmcnt(0)
	s_setprio 1
	s_waitcnt lgkmcnt(0)
	v_mfma_f32_16x16x32_bf16 v[74:77], v[204:207], v[160:163], v[74:77]
	v_mfma_f32_16x16x32_bf16 v[78:81], v[212:215], v[160:163], v[78:81]
	v_mfma_f32_16x16x32_bf16 v[98:101], v[204:207], v[168:171], v[98:101]
	v_mfma_f32_16x16x32_bf16 v[86:89], v[212:215], v[168:171], v[86:89]
	v_mfma_f32_16x16x32_bf16 v[106:109], v[204:207], v[176:179], v[106:109]
	v_mfma_f32_16x16x32_bf16 v[94:97], v[212:215], v[176:179], v[94:97]
	v_mfma_f32_16x16x32_bf16 v[102:105], v[204:207], v[196:199], v[102:105]
	v_mfma_f32_16x16x32_bf16 v[90:93], v[212:215], v[196:199], v[90:93]
	v_mfma_f32_16x16x32_bf16 v[74:77], v[208:211], v[164:167], v[74:77]
	v_mfma_f32_16x16x32_bf16 v[78:81], v[216:219], v[164:167], v[78:81]
	v_mfma_f32_16x16x32_bf16 v[98:101], v[208:211], v[172:175], v[98:101]
	v_mfma_f32_16x16x32_bf16 v[86:89], v[216:219], v[172:175], v[86:89]
	v_mfma_f32_16x16x32_bf16 v[106:109], v[208:211], v[192:195], v[106:109]
	v_mfma_f32_16x16x32_bf16 v[94:97], v[216:219], v[192:195], v[94:97]
	v_mfma_f32_16x16x32_bf16 v[102:105], v[208:211], v[200:203], v[102:105]
	v_mfma_f32_16x16x32_bf16 v[90:93], v[216:219], v[200:203], v[90:93]
	s_setprio 0
	s_mov_b32 m0, s36
	v_lshl_add_u64 v[152:153], v[222:223], 0, s[78:79]
	s_barrier
	ds_read_b128 v[160:163], v157 offset:49152
	ds_read_b128 v[164:167], v157 offset:50176
	ds_read_b128 v[168:171], v157 offset:51200
	ds_read_b128 v[172:175], v157 offset:52224
	ds_read_b128 v[176:179], v157 offset:53248
	ds_read_b128 v[192:195], v157 offset:54272
	ds_read_b128 v[196:199], v157 offset:55296
	ds_read_b128 v[200:203], v157 offset:56320
	global_load_lds_dwordx4 v[152:153], off
	v_lshl_add_u64 v[152:153], v[224:225], 0, s[78:79]
	s_mov_b32 m0, s37
	s_nop 0
	global_load_lds_dwordx4 v[152:153], off
	s_barrier
; #define G_STA(bufoff, gbase, ld) G_STAGE(bufoff, gbase, RA0, RA1, ld)
; #define G_STB(bufoff, gbase, ld) G_STAGE(bufoff, gbase, RB0, RB1, ld)
; #define G_LDA(dst, b, h) do { _Pragma("unroll") for (int m = 0; m < 4; ++m) _Pragma("unroll") for (int k = 0; k < 2; ++k) dst[m][k] = *(const LAS bf16x8*)(lds + G_SA(b, h) + aoff + m * 2048 + k * 1024); } while (0)
; #define G_LDB(dst, b, h) do { _Pragma("unroll") for (int n = 0; n < 2; ++n) _Pragma("unroll") for (int k = 0; k < 2; ++k) dst[n][k] = *(const LAS bf16x8*)(lds + G_SB(b, h) + boff + n * 2048 + k * 1024); } while (0)
; #define G_WAIT_V(n) asm volatile("s_waitcnt vmcnt(" #n ")" ::: "memory")
; #define G_WAIT_L(n) asm volatile("s_waitcnt lgkmcnt(" #n ")" ::: "memory")
; #define G_BAR __builtin_amdgcn_s_barrier()
; #define G_SCHED __builtin_amdgcn_sched_barrier(0)
; template <bool PERM, class SchedT, class Epi>
; __device__ __forceinline__ void gemm_phase(LAS unsigned char* lds, const SchedT& S, const Epi& E) {
;     ...
;             G_WAIT_V(6); G_BAR; G_MMA(1, 1, At, B1); G_BAR;
;             G_LDB(B0, 1, 0); G_SCHED; G_LDA(At, 1, 0); G_STA(G_SA(0, 1), a2 + HSTEP(wlda), wlda);
;             G_WAIT_L(8); G_BAR; G_WAIT_L(0); G_MMA(0, 0, At, B0); G_BAR; G_SCHED;
;             G_LDB(B1, 1, 1); G_STB(G_SB(1, 0), b3, wK);
;             G_BAR; G_WAIT_L(0); G_MMA(0, 1, At, B1); G_BAR;
;             G_LDA(At, 1, 1); G_STA(G_SA(1, 0), a3, wlda);
;             G_BAR; G_WAIT_L(0); G_MMA(1, 0, At, B0); G_BAR; G_SCHED;
;             G_STB(G_SB(1, 1), b3 + HSTEP(wK), wK);
;             G_WAIT_V(6); G_BAR; G_MMA(1, 1, At, B1); G_BAR;
;         }
;     __device__ __forceinline__ void operator()(f32x4 (&acc)[2][2][4][2], const UnitD& u, int wr, int wc, int fr, int fq) const {
;         const int row0 = u.pm * BM + wr * 64 + fr, col0 = u.pn * BM + wc * 32 + 4 * fq;
; #pragma unroll
;         for (int ai = 0; ai < 2; ++ai)
; #pragma unroll
;             for (int m = 0; m < 4; ++m) { const int row = row0 + ai * HALF + m * 16;
;                 const float* xr = (row < TP ? xp + (size_t)row * 2048 : xs + (size_t)(row - TP) * 2048) + col0;
; #pragma unroll
;                 for (int bj = 0; bj < 2; ++bj)
; #pragma unroll
;                     for (int n = 0; n < 2; ++n) acc[ai][bj][m][n] += *(const f32x4*)(xr + bj * HALF + n * 16);
;                 if (m & 1) asm volatile("" ::: "memory"); }
	s_waitcnt lgkmcnt(0)
	s_setprio 1
	s_waitcnt lgkmcnt(0)
	v_mfma_f32_16x16x32_bf16 v[62:65], v[136:139], v[160:163], v[62:65]
	v_mfma_f32_16x16x32_bf16 v[58:61], v[144:147], v[160:163], v[58:61]
	v_mfma_f32_16x16x32_bf16 v[46:49], v[136:139], v[168:171], v[46:49]
	v_mfma_f32_16x16x32_bf16 v[42:45], v[144:147], v[168:171], v[42:45]
	v_mfma_f32_16x16x32_bf16 v[30:33], v[136:139], v[176:179], v[30:33]
	v_mfma_f32_16x16x32_bf16 v[26:29], v[144:147], v[176:179], v[26:29]
	v_mfma_f32_16x16x32_bf16 v[14:17], v[136:139], v[196:199], v[14:17]
	v_mfma_f32_16x16x32_bf16 v[10:13], v[144:147], v[196:199], v[10:13]
	v_mfma_f32_16x16x32_bf16 v[62:65], v[140:143], v[164:167], v[62:65]
	v_mfma_f32_16x16x32_bf16 v[58:61], v[148:151], v[164:167], v[58:61]
	v_mfma_f32_16x16x32_bf16 v[46:49], v[140:143], v[172:175], v[46:49]
	v_mfma_f32_16x16x32_bf16 v[42:45], v[148:151], v[172:175], v[42:45]
	v_mfma_f32_16x16x32_bf16 v[30:33], v[140:143], v[192:195], v[30:33]
	v_mfma_f32_16x16x32_bf16 v[26:29], v[148:151], v[192:195], v[26:29]
	v_mfma_f32_16x16x32_bf16 v[14:17], v[140:143], v[200:203], v[14:17]
	v_mfma_f32_16x16x32_bf16 v[10:13], v[148:151], v[200:203], v[10:13]
	s_setprio 0
	s_barrier
	s_add_u32 s26, s26, 0x80080
	s_addc_u32 s27, s27, 0
	s_add_i32 s28, s28, s5
	v_lshl_add_u64 v[136:137], s[26:27], 0, v[0:1]
	s_mov_b32 m0, s28
	s_nop 0
	global_load_lds_dwordx4 v[136:137], off
	v_lshl_add_u64 v[136:137], s[26:27], 0, v[130:131]
	s_add_i32 m0, s28, 0x2000
	s_nop 0
	global_load_lds_dwordx4 v[136:137], off
	s_waitcnt vmcnt(6)
	s_barrier
	s_setprio 1
	v_mfma_f32_16x16x32_bf16 v[54:57], v[204:207], v[160:163], v[54:57]
	v_mfma_f32_16x16x32_bf16 v[50:53], v[212:215], v[160:163], v[50:53]
	v_mfma_f32_16x16x32_bf16 v[38:41], v[204:207], v[168:171], v[38:41]
	v_mfma_f32_16x16x32_bf16 v[34:37], v[212:215], v[168:171], v[34:37]
	v_mfma_f32_16x16x32_bf16 v[22:25], v[204:207], v[176:179], v[22:25]
	v_mfma_f32_16x16x32_bf16 v[18:21], v[212:215], v[176:179], v[18:21]
	v_mfma_f32_16x16x32_bf16 v[6:9], v[204:207], v[196:199], v[6:9]
	v_mfma_f32_16x16x32_bf16 v[2:5], v[212:215], v[196:199], v[2:5]
	v_mfma_f32_16x16x32_bf16 v[54:57], v[208:211], v[164:167], v[54:57]
	v_mfma_f32_16x16x32_bf16 v[50:53], v[216:219], v[164:167], v[50:53]
	v_mfma_f32_16x16x32_bf16 v[38:41], v[208:211], v[172:175], v[38:41]
	v_mfma_f32_16x16x32_bf16 v[34:37], v[216:219], v[172:175], v[34:37]
	v_mfma_f32_16x16x32_bf16 v[22:25], v[208:211], v[192:195], v[22:25]
	v_mfma_f32_16x16x32_bf16 v[18:21], v[216:219], v[192:195], v[18:21]
	v_mfma_f32_16x16x32_bf16 v[6:9], v[208:211], v[200:203], v[6:9]
	v_mfma_f32_16x16x32_bf16 v[2:5], v[216:219], v[200:203], v[2:5]
	s_setprio 0
	s_add_i32 s41, s41, 2
	s_add_u32 s24, s24, 0x100
	s_addc_u32 s25, s25, 0
	s_add_u32 s17, s17, 0x100
	s_addc_u32 s19, s19, 0
	s_cmp_gt_u32 s41, 29
	s_barrier
	s_cbranch_scc0 .LBB0_366
	s_cmpk_gt_u32 s4, 0xff
	s_cbranch_scc1 .Lus_g4a
	s_barrier
.Lus_g4a:
	v_lshl_add_u32 v208, s39, 8, v154
	v_lshl_or_b32 v209, s40, 8, v156
	v_lshlrev_b32_e32 v209, 2, v209
	v_lshl_add_u32 v208, v208, 13, v209
	v_mov_b32_e32 v209, 0
	v_lshl_add_u64 v[210:211], s[8:9], 0, v[208:209]
	v_lshl_add_u64 v[212:213], s[12:13], 0, v[208:209]
	v_mov_b32_e32 v214, v210
	v_mov_b32_e32 v215, v211
	global_load_dwordx4 v[136:139], v[214:215], off
	global_load_dwordx4 v[140:143], v[214:215], off offset:64
	global_load_dwordx4 v[144:147], v[214:215], off offset:512
	global_load_dwordx4 v[148:151], v[214:215], off offset:576
	v_add_co_u32_e32 v214, vcc, 0x20000, v210
	s_nop 1
	v_addc_co_u32_e32 v215, vcc, 0, v211, vcc
	global_load_dwordx4 v[160:163], v[214:215], off
	global_load_dwordx4 v[164:167], v[214:215], off offset:64
	global_load_dwordx4 v[168:171], v[214:215], off offset:512
	global_load_dwordx4 v[172:175], v[214:215], off offset:576
	v_add_co_u32_e32 v214, vcc, 0x40000, v210
	s_nop 1
	v_addc_co_u32_e32 v215, vcc, 0, v211, vcc
	global_load_dwordx4 v[192:195], v[214:215], off
	global_load_dwordx4 v[196:199], v[214:215], off offset:64
	global_load_dwordx4 v[200:203], v[214:215], off offset:512
	global_load_dwordx4 v[204:207], v[214:215], off offset:576
	ds_write_b128 v251, v[66:69]
	ds_read_b128 v[66:69], v252
	ds_write_b128 v251, v[70:73]
	ds_read_b128 v[70:73], v252
	ds_write_b128 v251, v[74:77]
	ds_read_b128 v[74:77], v252
	ds_write_b128 v251, v[78:81]
	ds_read_b128 v[78:81], v252
	v_mov_b32_e32 v216, v212
	v_mov_b32_e32 v217, v213
	s_waitcnt vmcnt(8)
	s_waitcnt lgkmcnt(6)
	v_pk_add_f32 v[66:67], v[66:67], v[136:137]
	v_pk_add_f32 v[68:69], v[68:69], v[138:139]
	s_waitcnt lgkmcnt(4)
	v_pk_add_f32 v[70:71], v[70:71], v[140:141]
	v_pk_add_f32 v[72:73], v[72:73], v[142:143]
	s_waitcnt lgkmcnt(2)
	v_pk_add_f32 v[74:75], v[74:75], v[144:145]
	v_pk_add_f32 v[76:77], v[76:77], v[146:147]
	s_waitcnt lgkmcnt(0)
	v_pk_add_f32 v[78:79], v[78:79], v[148:149]
	v_pk_add_f32 v[80:81], v[80:81], v[150:151]
	global_store_dwordx4 v[216:217], v[66:69], off
	global_store_dwordx4 v[216:217], v[70:73], off offset:64
	global_store_dwordx4 v[216:217], v[74:77], off offset:512
	global_store_dwordx4 v[216:217], v[78:81], off offset:576
	v_add_co_u32_e32 v214, vcc, 0x60000, v210
	s_nop 1
	v_addc_co_u32_e32 v215, vcc, 0, v211, vcc
	global_load_dwordx4 v[136:139], v[214:215], off
	global_load_dwordx4 v[140:143], v[214:215], off offset:64
	global_load_dwordx4 v[144:147], v[214:215], off offset:512
	global_load_dwordx4 v[148:151], v[214:215], off offset:576
	ds_write_b128 v251, v[82:85]
	ds_read_b128 v[82:85], v252
	ds_write_b128 v251, v[110:113]
	ds_read_b128 v[110:113], v252
	ds_write_b128 v251, v[98:101]
	ds_read_b128 v[98:101], v252
	ds_write_b128 v251, v[86:89]
	ds_read_b128 v[86:89], v252
	v_add_co_u32_e32 v216, vcc, 0x20000, v212
	s_nop 1
	v_addc_co_u32_e32 v217, vcc, 0, v213, vcc
	s_waitcnt vmcnt(12)
;     __device__ __forceinline__ void operator()(f32x4 (&acc)[2][2][4][2], const UnitD& u, int wr, int wc, int fr, int fq) const {
;     ...
;         for (int ai = 0; ai < 2; ++ai)
; #pragma unroll
;             for (int m = 0; m < 4; ++m) { const int row = row0 + ai * HALF + m * 16;
;                 const float* xr = (row < TP ? xp + (size_t)row * 2048 : xs + (size_t)(row - TP) * 2048) + col0;
; #pragma unroll
;                 for (int bj = 0; bj < 2; ++bj)
; #pragma unroll
;                     for (int n = 0; n < 2; ++n) acc[ai][bj][m][n] += *(const f32x4*)(xr + bj * HALF + n * 16);
;                 if (m & 1) asm volatile("" ::: "memory"); }
; #pragma unroll
;         for (int ai = 0; ai < 2; ++ai)
; #pragma unroll
;             for (int m = 0; m < 4; ++m) { const int row = row0 + ai * HALF + m * 16; float* orow = out + (size_t)row * 2048 + col0;
; #pragma unroll
;                 for (int bj = 0; bj < 2; ++bj)
; #pragma unroll
;                     for (int n = 0; n < 2; ++n) *(f32x4*)(orow + bj * HALF + n * 16) = acc[ai][bj][m][n]; }
	s_waitcnt lgkmcnt(6)
	v_pk_add_f32 v[82:83], v[82:83], v[160:161]
	v_pk_add_f32 v[84:85], v[84:85], v[162:163]
	s_waitcnt lgkmcnt(4)
	v_pk_add_f32 v[110:111], v[110:111], v[164:165]
	v_pk_add_f32 v[112:113], v[112:113], v[166:167]
	s_waitcnt lgkmcnt(2)
	v_pk_add_f32 v[98:99], v[98:99], v[168:169]
	v_pk_add_f32 v[100:101], v[100:101], v[170:171]
	s_waitcnt lgkmcnt(0)
	v_pk_add_f32 v[86:87], v[86:87], v[172:173]
	v_pk_add_f32 v[88:89], v[88:89], v[174:175]
	global_store_dwordx4 v[216:217], v[82:85], off
	global_store_dwordx4 v[216:217], v[110:113], off offset:64
	global_store_dwordx4 v[216:217], v[98:101], off offset:512
	global_store_dwordx4 v[216:217], v[86:89], off offset:576
	v_add_co_u32_e32 v214, vcc, 0x100000, v210
	s_nop 1
	v_addc_co_u32_e32 v215, vcc, 0, v211, vcc
	global_load_dwordx4 v[160:163], v[214:215], off
	global_load_dwordx4 v[164:167], v[214:215], off offset:64
	global_load_dwordx4 v[168:171], v[214:215], off offset:512
	global_load_dwordx4 v[172:175], v[214:215], off offset:576
	ds_write_b128 v251, v[126:129]
	ds_read_b128 v[126:129], v252
	ds_write_b128 v251, v[118:121]
	ds_read_b128 v[118:121], v252
	ds_write_b128 v251, v[106:109]
	ds_read_b128 v[106:109], v252
	ds_write_b128 v251, v[94:97]
	ds_read_b128 v[94:97], v252
	v_add_co_u32_e32 v216, vcc, 0x40000, v212
	s_nop 1
	v_addc_co_u32_e32 v217, vcc, 0, v213, vcc
	s_waitcnt vmcnt(16)
	s_waitcnt lgkmcnt(6)
	v_pk_add_f32 v[126:127], v[126:127], v[192:193]
	v_pk_add_f32 v[128:129], v[128:129], v[194:195]
	s_waitcnt lgkmcnt(4)
	v_pk_add_f32 v[118:119], v[118:119], v[196:197]
	v_pk_add_f32 v[120:121], v[120:121], v[198:199]
	s_waitcnt lgkmcnt(2)
	v_pk_add_f32 v[106:107], v[106:107], v[200:201]
	v_pk_add_f32 v[108:109], v[108:109], v[202:203]
	s_waitcnt lgkmcnt(0)
	v_pk_add_f32 v[94:95], v[94:95], v[204:205]
	v_pk_add_f32 v[96:97], v[96:97], v[206:207]
	global_store_dwordx4 v[216:217], v[126:129], off
	global_store_dwordx4 v[216:217], v[118:121], off offset:64
	global_store_dwordx4 v[216:217], v[106:109], off offset:512
	global_store_dwordx4 v[216:217], v[94:97], off offset:576
	v_add_co_u32_e32 v214, vcc, 0x120000, v210
	s_nop 1
	v_addc_co_u32_e32 v215, vcc, 0, v211, vcc
	global_load_dwordx4 v[192:195], v[214:215], off
	global_load_dwordx4 v[196:199], v[214:215], off offset:64
	global_load_dwordx4 v[200:203], v[214:215], off offset:512
	global_load_dwordx4 v[204:207], v[214:215], off offset:576
	ds_write_b128 v251, v[122:125]
	ds_read_b128 v[122:125], v252
	ds_write_b128 v251, v[114:117]
	ds_read_b128 v[114:117], v252
	ds_write_b128 v251, v[102:105]
	ds_read_b128 v[102:105], v252
	ds_write_b128 v251, v[90:93]
	ds_read_b128 v[90:93], v252
	v_add_co_u32_e32 v216, vcc, 0x60000, v212
	s_nop 1
	v_addc_co_u32_e32 v217, vcc, 0, v213, vcc
	s_waitcnt vmcnt(16)
	s_waitcnt lgkmcnt(6)
	v_pk_add_f32 v[122:123], v[122:123], v[136:137]
	v_pk_add_f32 v[124:125], v[124:125], v[138:139]
	s_waitcnt lgkmcnt(4)
	v_pk_add_f32 v[114:115], v[114:115], v[140:141]
	v_pk_add_f32 v[116:117], v[116:117], v[142:143]
	s_waitcnt lgkmcnt(2)
	v_pk_add_f32 v[102:103], v[102:103], v[144:145]
	v_pk_add_f32 v[104:105], v[104:105], v[146:147]
	s_waitcnt lgkmcnt(0)
	v_pk_add_f32 v[90:91], v[90:91], v[148:149]
	v_pk_add_f32 v[92:93], v[92:93], v[150:151]
	global_store_dwordx4 v[216:217], v[122:125], off
	global_store_dwordx4 v[216:217], v[114:117], off offset:64
	global_store_dwordx4 v[216:217], v[102:105], off offset:512
	global_store_dwordx4 v[216:217], v[90:93], off offset:576
	v_add_co_u32_e32 v214, vcc, 0x140000, v210
	s_nop 1
	v_addc_co_u32_e32 v215, vcc, 0, v211, vcc
	global_load_dwordx4 v[136:139], v[214:215], off
	global_load_dwordx4 v[140:143], v[214:215], off offset:64
	global_load_dwordx4 v[144:147], v[214:215], off offset:512
	global_load_dwordx4 v[148:151], v[214:215], off offset:576
	ds_write_b128 v251, v[62:65]
	ds_read_b128 v[62:65], v252
	ds_write_b128 v251, v[58:61]
	ds_read_b128 v[58:61], v252
	ds_write_b128 v251, v[54:57]
	ds_read_b128 v[54:57], v252
	ds_write_b128 v251, v[50:53]
	ds_read_b128 v[50:53], v252
	v_add_co_u32_e32 v216, vcc, 0x100000, v212
	s_nop 1
	v_addc_co_u32_e32 v217, vcc, 0, v213, vcc
	s_waitcnt vmcnt(16)
	s_waitcnt lgkmcnt(6)
	v_pk_add_f32 v[62:63], v[62:63], v[160:161]
	v_pk_add_f32 v[64:65], v[64:65], v[162:163]
	s_waitcnt lgkmcnt(4)
; template <bool PERM, class SchedT, class Epi>
; __device__ __forceinline__ void gemm_phase(LAS unsigned char* lds, const SchedT& S, const Epi& E) {
;     ...
;         if (!has_next) break;
; #pragma unroll
;         for (int a = 0; a < 2; ++a)
; #pragma unroll
;             for (int b = 0; b < 2; ++b)
; #pragma unroll
;                 for (int m = 0; m < 4; ++m)
; #pragma unroll
;                     for (int n = 0; n < 2; ++n) acc[a][b][m][n] = (f32x4){0.f, 0.f, 0.f, 0.f};
;         cur = nxt; cA = nA; cB = nB; lda = nlda; K = nK; ++ui;
;     __device__ __forceinline__ void operator()(f32x4 (&acc)[2][2][4][2], const UnitD& u, int wr, int wc, int fr, int fq) const {
;     ...
;         for (int ai = 0; ai < 2; ++ai)
; #pragma unroll
;             for (int m = 0; m < 4; ++m) { const int row = row0 + ai * HALF + m * 16;
;                 const float* xr = (row < TP ? xp + (size_t)row * 2048 : xs + (size_t)(row - TP) * 2048) + col0;
; #pragma unroll
;                 for (int bj = 0; bj < 2; ++bj)
; #pragma unroll
;                     for (int n = 0; n < 2; ++n) acc[ai][bj][m][n] += *(const f32x4*)(xr + bj * HALF + n * 16);
;                 if (m & 1) asm volatile("" ::: "memory"); }
; #pragma unroll
;         for (int ai = 0; ai < 2; ++ai)
; #pragma unroll
;             for (int m = 0; m < 4; ++m) { const int row = row0 + ai * HALF + m * 16; float* orow = out + (size_t)row * 2048 + col0;
; #pragma unroll
;                 for (int bj = 0; bj < 2; ++bj)
; #pragma unroll
;                     for (int n = 0; n < 2; ++n) *(f32x4*)(orow + bj * HALF + n * 16) = acc[ai][bj][m][n]; }
	v_pk_add_f32 v[58:59], v[58:59], v[164:165]
	v_pk_add_f32 v[60:61], v[60:61], v[166:167]
	s_waitcnt lgkmcnt(2)
	v_pk_add_f32 v[54:55], v[54:55], v[168:169]
	v_pk_add_f32 v[56:57], v[56:57], v[170:171]
	s_waitcnt lgkmcnt(0)
	v_pk_add_f32 v[50:51], v[50:51], v[172:173]
	v_pk_add_f32 v[52:53], v[52:53], v[174:175]
	global_store_dwordx4 v[216:217], v[62:65], off
	global_store_dwordx4 v[216:217], v[58:61], off offset:64
	global_store_dwordx4 v[216:217], v[54:57], off offset:512
	global_store_dwordx4 v[216:217], v[50:53], off offset:576
	v_add_co_u32_e32 v214, vcc, 0x160000, v210
	s_nop 1
	v_addc_co_u32_e32 v215, vcc, 0, v211, vcc
	global_load_dwordx4 v[160:163], v[214:215], off
	global_load_dwordx4 v[164:167], v[214:215], off offset:64
	global_load_dwordx4 v[168:171], v[214:215], off offset:512
	global_load_dwordx4 v[172:175], v[214:215], off offset:576
	ds_write_b128 v251, v[46:49]
	ds_read_b128 v[46:49], v252
	ds_write_b128 v251, v[42:45]
	ds_read_b128 v[42:45], v252
	ds_write_b128 v251, v[38:41]
	ds_read_b128 v[38:41], v252
	ds_write_b128 v251, v[34:37]
	ds_read_b128 v[34:37], v252
	v_add_co_u32_e32 v216, vcc, 0x120000, v212
	s_nop 1
	v_addc_co_u32_e32 v217, vcc, 0, v213, vcc
	s_waitcnt vmcnt(16)
	s_waitcnt lgkmcnt(6)
	v_pk_add_f32 v[46:47], v[46:47], v[192:193]
	v_pk_add_f32 v[48:49], v[48:49], v[194:195]
	s_waitcnt lgkmcnt(4)
	v_pk_add_f32 v[42:43], v[42:43], v[196:197]
	v_pk_add_f32 v[44:45], v[44:45], v[198:199]
	s_waitcnt lgkmcnt(2)
	v_pk_add_f32 v[38:39], v[38:39], v[200:201]
	v_pk_add_f32 v[40:41], v[40:41], v[202:203]
	s_waitcnt lgkmcnt(0)
	v_pk_add_f32 v[34:35], v[34:35], v[204:205]
	v_pk_add_f32 v[36:37], v[36:37], v[206:207]
	global_store_dwordx4 v[216:217], v[46:49], off
	global_store_dwordx4 v[216:217], v[42:45], off offset:64
	global_store_dwordx4 v[216:217], v[38:41], off offset:512
	global_store_dwordx4 v[216:217], v[34:37], off offset:576
	ds_write_b128 v251, v[30:33]
	ds_read_b128 v[30:33], v252
	ds_write_b128 v251, v[26:29]
	ds_read_b128 v[26:29], v252
	ds_write_b128 v251, v[22:25]
	ds_read_b128 v[22:25], v252
	ds_write_b128 v251, v[18:21]
	ds_read_b128 v[18:21], v252
	v_add_co_u32_e32 v216, vcc, 0x140000, v212
	s_nop 1
	v_addc_co_u32_e32 v217, vcc, 0, v213, vcc
	s_waitcnt vmcnt(12)
	s_waitcnt lgkmcnt(6)
	v_pk_add_f32 v[30:31], v[30:31], v[136:137]
	v_pk_add_f32 v[32:33], v[32:33], v[138:139]
	s_waitcnt lgkmcnt(4)
	v_pk_add_f32 v[26:27], v[26:27], v[140:141]
	v_pk_add_f32 v[28:29], v[28:29], v[142:143]
	s_waitcnt lgkmcnt(2)
	v_pk_add_f32 v[22:23], v[22:23], v[144:145]
	v_pk_add_f32 v[24:25], v[24:25], v[146:147]
	s_waitcnt lgkmcnt(0)
	v_pk_add_f32 v[18:19], v[18:19], v[148:149]
	v_pk_add_f32 v[20:21], v[20:21], v[150:151]
	global_store_dwordx4 v[216:217], v[30:33], off
	global_store_dwordx4 v[216:217], v[26:29], off offset:64
	global_store_dwordx4 v[216:217], v[22:25], off offset:512
	global_store_dwordx4 v[216:217], v[18:21], off offset:576
	ds_write_b128 v251, v[14:17]
	ds_read_b128 v[14:17], v252
	ds_write_b128 v251, v[10:13]
	ds_read_b128 v[10:13], v252
	ds_write_b128 v251, v[6:9]
	ds_read_b128 v[6:9], v252
	ds_write_b128 v251, v[2:5]
	ds_read_b128 v[2:5], v252
	v_add_co_u32_e32 v216, vcc, 0x160000, v212
	s_nop 1
	v_addc_co_u32_e32 v217, vcc, 0, v213, vcc
	s_waitcnt vmcnt(8)
	s_waitcnt lgkmcnt(6)
	v_pk_add_f32 v[14:15], v[14:15], v[160:161]
	v_pk_add_f32 v[16:17], v[16:17], v[162:163]
	s_waitcnt lgkmcnt(4)
	v_pk_add_f32 v[10:11], v[10:11], v[164:165]
	v_pk_add_f32 v[12:13], v[12:13], v[166:167]
	s_waitcnt lgkmcnt(2)
	v_pk_add_f32 v[6:7], v[6:7], v[168:169]
	v_pk_add_f32 v[8:9], v[8:9], v[170:171]
	s_waitcnt lgkmcnt(0)
	v_pk_add_f32 v[2:3], v[2:3], v[172:173]
	v_pk_add_f32 v[4:5], v[4:5], v[174:175]
	global_store_dwordx4 v[216:217], v[14:17], off
	global_store_dwordx4 v[216:217], v[10:13], off offset:64
	global_store_dwordx4 v[216:217], v[6:9], off offset:512
	global_store_dwordx4 v[216:217], v[2:5], off offset:576
	s_movk_i32 s17, 0x3f50
	s_mov_b32 s39, s18
	s_mov_b32 s40, s16
	s_mov_b64 s[26:27], s[22:23]
	s_mov_b64 s[24:25], s[20:21]
	s_cmpk_gt_u32 s4, 0xff
	s_cbranch_scc0 .Lus_g4b
	s_barrier
.Lus_g4b:
	s_and_b64 vcc, exec, s[14:15]
	s_cbranch_vccz .LBB0_359
	s_waitcnt vmcnt(0)
	s_cmpk_gt_u32 s4, 0xff
	s_cbranch_scc1 .LBB0_370
	s_barrier
